# accumulator zeroing of each GEMM tile moved into the first K iteration after the first LDS read issue
# speedup vs baseline: 1.0178x; 1.0000x over previous
; #define PG8_STAGE(bufoff, gbase, voff) do { _Pragma("unroll") for (int _i = 0; _i < 2; ++_i) \
;         __builtin_amdgcn_global_load_lds((const unsigned*)((const char*)(gbase) + (voff)[_i]), (PG8_LAS unsigned*)(lds + (bufoff) + ldsw + _i * 8192), 16, 0, 0); } while (0)
; #define PG8_LDA(dst, b, h) do { _Pragma("unroll") for (int m = 0; m < 4; ++m) _Pragma("unroll") for (int k = 0; k < 2; ++k) dst[m][k] = *(const PG8_LAS bf16x8*)(lds + PG8_SA(b, h) + aoff + m * 2048 + k * 1024); } while (0)
; #define PG8_LDB(dst, b, h) do { _Pragma("unroll") for (int n = 0; n < 2; ++n) _Pragma("unroll") for (int k = 0; k < 2; ++k) dst[n][k] = *(const PG8_LAS bf16x8*)(lds + PG8_SB(b, h) + boff + n * 2048 + k * 1024); } while (0)
; #define PG8_SCHED __builtin_amdgcn_sched_barrier(0)
; template <class Epi, class Sched, bool ALIGN_EPI = false, bool SP2 = false>
; __device__ __forceinline__ void gemm_phase(PG8_LAS unsigned char* lds, const Gemm g, const Sched& S, const Epi& E) {
;     ...
;         const bool has_next = S.next(ui + 1, nxt);
;         const char* nA = has_next ? (const char*)g.A + (size_t)nxt.pm * tstepA : cA; const char* nB = has_next ? (const char*)g.Bt + (size_t)nxt.pn * tstepB : cB;
;         for (int t = 0; t < nt; t += 2) {
;             const bool last = (t == nt - 2);
;             const char* a1 = cA + (size_t)(t + 1) * kstepA;
;             const char* a2 = last ? nA : cA + (size_t)(t + 2) * kstepA; const char* b2 = last ? nB : cB + (size_t)(t + 2) * kstep;
;             const char* a3 = a2 + kstepA; const char* b3 = b2 + kstep;
;             if (last && has_next) S.a_ready(nxt);
;             if constexpr (SP2) {
;             PG8_LDB(B0, 0, 0); PG8_LDB(B1, 0, 1); PG8_SCHED; PG8_LDA(At, 0, 0); PG8_STAGE(PG8_SA(1, 1), a1 + hstepA, voffA);
;     ...
; #pragma unroll
;         for (int a = 0; a < 2; ++a)
; #pragma unroll
;             for (int b = 0; b < 2; ++b)
; #pragma unroll
;                 for (int m = 0; m < 4; ++m)
; #pragma unroll
;                     for (int n = 0; n < 2; ++n) acc[a][b][m][n] = (f32x4){0.f, 0.f, 0.f, 0.f};
.LBB0_140:
	s_ashr_i32 s59, s58, 31
	s_lshl_b64 s[60:61], s[58:59], 19
	s_add_u32 s60, s12, s60
	s_addc_u32 s61, s13, s61
	s_and_b64 s[62:63], s[2:3], exec
	s_cselect_b32 s59, s61, s71
	s_cselect_b32 s92, s60, s70
	s_ashr_i32 s57, s56, 31
	s_lshl_b64 s[62:63], s[56:57], 19
	s_add_u32 s62, s80, s62
	s_addc_u32 s63, s81, s63
	s_and_b64 s[94:95], s[2:3], exec
	s_cselect_b32 s57, s63, s73
	s_cselect_b32 s93, s62, s72
	s_add_u32 s70, s70, 0x10000
	s_addc_u32 s71, s71, 0
	s_add_u32 s72, s72, 0x10000
	s_addc_u32 s73, s73, 0
	s_mov_b32 s94, -2
.LBB0_141:
	ds_read_b128 v[150:153], v143
	ds_read_b128 v[154:157], v143 offset:1024
	ds_read_b128 v[158:161], v143 offset:2048
	ds_read_b128 v[162:165], v143 offset:3072
	ds_read_b128 v[166:169], v144
	ds_read_b128 v[170:173], v144 offset:1024
	ds_read_b128 v[174:177], v144 offset:2048
	ds_read_b128 v[178:181], v144 offset:3072
	s_cmp_eq_u32 s94, 12
	s_cselect_b32 s97, s59, s71
	s_cselect_b32 s96, s92, s70
	s_cselect_b32 vcc_hi, s57, s73
	s_cselect_b32 vcc_lo, s93, s72
	s_movk_i32 s8, 0xc000
	v_lshl_add_u64 v[186:187], s[70:71], 0, v[128:129]
	s_mov_b32 s9, -1
	v_lshl_add_u64 v[220:221], v[186:187], 0, s[8:9]
	s_movk_i32 s8, 0xe000
	s_add_i32 m0, s18, 0xc000
	s_mov_b32 s9, -1
	ds_read_b128 v[182:185], v145
	ds_read_b128 v[190:193], v145 offset:1024
	ds_read_b128 v[194:197], v145 offset:2048
	ds_read_b128 v[198:201], v145 offset:3072
	ds_read_b128 v[202:205], v145 offset:4096
	ds_read_b128 v[206:209], v145 offset:5120
	ds_read_b128 v[210:213], v145 offset:6144
	ds_read_b128 v[214:217], v145 offset:7168
	global_load_lds_dwordx4 v[220:221], off
	v_lshl_add_u64 v[186:187], v[186:187], 0, s[8:9]
	s_add_i32 m0, s18, 0xe000
	s_nop 0
	global_load_lds_dwordx4 v[186:187], off
	s_cmp_lg_u32 s94, -2
	s_cbranch_scc1 .Lzskip_0
	v_mov_b32_e32 v0, 0
	v_mov_b32_e32 v1, 0
	v_mov_b32_e32 v2, 0
	v_mov_b32_e32 v3, 0
	v_mov_b32_e32 v4, 0
	v_mov_b32_e32 v5, 0
	v_mov_b32_e32 v6, 0
	v_mov_b32_e32 v7, 0
	v_mov_b32_e32 v8, 0
	v_mov_b32_e32 v9, 0
	v_mov_b32_e32 v10, 0
	v_mov_b32_e32 v11, 0
	v_mov_b32_e32 v12, 0
	v_mov_b32_e32 v13, 0
	v_mov_b32_e32 v14, 0
	v_mov_b32_e32 v15, 0
	v_mov_b32_e32 v16, 0
	v_mov_b32_e32 v17, 0
	v_mov_b32_e32 v18, 0
	v_mov_b32_e32 v19, 0
	v_mov_b32_e32 v20, 0
	v_mov_b32_e32 v21, 0
	v_mov_b32_e32 v22, 0
	v_mov_b32_e32 v23, 0
	v_mov_b32_e32 v24, 0
	v_mov_b32_e32 v25, 0
	v_mov_b32_e32 v26, 0
	v_mov_b32_e32 v27, 0
	v_mov_b32_e32 v28, 0
	v_mov_b32_e32 v29, 0
	v_mov_b32_e32 v30, 0
	v_mov_b32_e32 v31, 0
	v_mov_b32_e32 v32, 0
	v_mov_b32_e32 v33, 0
	v_mov_b32_e32 v34, 0
	v_mov_b32_e32 v35, 0
	v_mov_b32_e32 v36, 0
	v_mov_b32_e32 v37, 0
	v_mov_b32_e32 v38, 0
	v_mov_b32_e32 v39, 0
	v_mov_b32_e32 v40, 0
	v_mov_b32_e32 v41, 0
	v_mov_b32_e32 v42, 0
	v_mov_b32_e32 v43, 0
	v_mov_b32_e32 v44, 0
	v_mov_b32_e32 v45, 0
	v_mov_b32_e32 v46, 0
	v_mov_b32_e32 v47, 0
	v_mov_b32_e32 v48, 0
	v_mov_b32_e32 v49, 0
	v_mov_b32_e32 v50, 0
	v_mov_b32_e32 v51, 0
	v_mov_b32_e32 v52, 0
	v_mov_b32_e32 v53, 0
	v_mov_b32_e32 v54, 0
	v_mov_b32_e32 v55, 0
	v_mov_b32_e32 v56, 0
	v_mov_b32_e32 v57, 0
	v_mov_b32_e32 v58, 0
	v_mov_b32_e32 v59, 0
	v_mov_b32_e32 v60, 0
	v_mov_b32_e32 v61, 0
	v_mov_b32_e32 v62, 0
	v_mov_b32_e32 v63, 0
	v_mov_b32_e32 v64, 0
	v_mov_b32_e32 v65, 0
	v_mov_b32_e32 v66, 0
	v_mov_b32_e32 v67, 0
	v_mov_b32_e32 v68, 0
	v_mov_b32_e32 v69, 0
	v_mov_b32_e32 v70, 0
	v_mov_b32_e32 v71, 0
	v_mov_b32_e32 v72, 0
	v_mov_b32_e32 v73, 0
	v_mov_b32_e32 v74, 0
	v_mov_b32_e32 v75, 0
	v_mov_b32_e32 v76, 0
	v_mov_b32_e32 v77, 0
	v_mov_b32_e32 v78, 0
	v_mov_b32_e32 v79, 0
	v_mov_b32_e32 v80, 0
	v_mov_b32_e32 v81, 0
	v_mov_b32_e32 v82, 0
	v_mov_b32_e32 v83, 0
	v_mov_b32_e32 v84, 0
	v_mov_b32_e32 v85, 0
	v_mov_b32_e32 v86, 0
	v_mov_b32_e32 v87, 0
	v_mov_b32_e32 v88, 0
	v_mov_b32_e32 v89, 0
	v_mov_b32_e32 v90, 0
	v_mov_b32_e32 v91, 0
	v_mov_b32_e32 v92, 0
	v_mov_b32_e32 v93, 0
	v_mov_b32_e32 v94, 0
	v_mov_b32_e32 v95, 0
	v_mov_b32_e32 v96, 0
	v_mov_b32_e32 v97, 0
	v_mov_b32_e32 v98, 0
	v_mov_b32_e32 v99, 0
	v_mov_b32_e32 v100, 0
	v_mov_b32_e32 v101, 0
	v_mov_b32_e32 v102, 0
	v_mov_b32_e32 v103, 0
	v_mov_b32_e32 v104, 0
	v_mov_b32_e32 v105, 0
	v_mov_b32_e32 v106, 0
	v_mov_b32_e32 v107, 0
	v_mov_b32_e32 v108, 0
	v_mov_b32_e32 v109, 0
	v_mov_b32_e32 v110, 0
	v_mov_b32_e32 v111, 0
	v_mov_b32_e32 v112, 0
	v_mov_b32_e32 v113, 0
	v_mov_b32_e32 v114, 0
	v_mov_b32_e32 v115, 0
	v_mov_b32_e32 v116, 0
	v_mov_b32_e32 v117, 0
	v_mov_b32_e32 v118, 0
	v_mov_b32_e32 v119, 0
	v_mov_b32_e32 v120, 0
	v_mov_b32_e32 v121, 0
	v_mov_b32_e32 v122, 0
	v_mov_b32_e32 v123, 0
	v_mov_b32_e32 v124, 0
	v_mov_b32_e32 v125, 0
	v_mov_b32_e32 v126, 0
	v_mov_b32_e32 v127, 0
; #define PG8_STAGE(bufoff, gbase, voff) do { _Pragma("unroll") for (int _i = 0; _i < 2; ++_i) \
;         __builtin_amdgcn_global_load_lds((const unsigned*)((const char*)(gbase) + (voff)[_i]), (PG8_LAS unsigned*)(lds + (bufoff) + ldsw + _i * 8192), 16, 0, 0); } while (0)
; #define PG8_LDA(dst, b, h) do { _Pragma("unroll") for (int m = 0; m < 4; ++m) _Pragma("unroll") for (int k = 0; k < 2; ++k) dst[m][k] = *(const PG8_LAS bf16x8*)(lds + PG8_SA(b, h) + aoff + m * 2048 + k * 1024); } while (0)
; #define PG8_MMA(ai, bj, At, Bt) do { __builtin_amdgcn_s_setprio(1); _Pragma("unroll") for (int m = 0; m < 4; ++m) _Pragma("unroll") for (int n = 0; n < 2; ++n) _Pragma("unroll") for (int k = 0; k < 2; ++k) \
;         acc[ai][bj][m][n] = __builtin_amdgcn_mfma_f32_16x16x32_bf16(Bt[n][k], At[m][k], acc[ai][bj][m][n], 0, 0, 0); __builtin_amdgcn_s_setprio(0); } while (0)
; #define PG8_WAIT_V(n) asm volatile("s_waitcnt vmcnt(" #n ")" ::: "memory")
; #define PG8_WAIT_L(n) asm volatile("s_waitcnt lgkmcnt(" #n ")" ::: "memory")
; #define PG8_BAR __builtin_amdgcn_s_barrier()
; #define PG8_SCHED __builtin_amdgcn_sched_barrier(0)
; template <class Epi, class Sched, bool ALIGN_EPI = false, bool SP2 = false>
; __device__ __forceinline__ void gemm_phase(PG8_LAS unsigned char* lds, const Gemm g, const Sched& S, const Epi& E) {
;     ...
;             PG8_WAIT_V(8); PG8_WAIT_L(0); PG8_BAR; PG8_MMA(0, 0, At, B0); PG8_MMA(0, 1, At, B1); PG8_BAR; PG8_SCHED;
;             PG8_LDA(At, 0, 1); PG8_STAGE(PG8_SB(0, 0), b2, voffB); PG8_STAGE(PG8_SB(0, 1), b2 + hstepB, voffB); PG8_STAGE(PG8_SA(0, 0), a2, voffA);
;             PG8_WAIT_V(8); PG8_WAIT_L(0); PG8_BAR; PG8_MMA(1, 0, At, B0); PG8_MMA(1, 1, At, B1); PG8_BAR; PG8_SCHED;
.Lzskip_0:
	s_waitcnt vmcnt(8)
	s_waitcnt lgkmcnt(0)
	s_barrier
	s_setprio 1
	s_waitcnt lgkmcnt(0)
	v_mfma_f32_16x16x32_bf16 v[116:119], v[150:153], v[182:185], v[116:119]
	v_mfma_f32_16x16x32_bf16 v[112:115], v[158:161], v[182:185], v[112:115]
	v_mfma_f32_16x16x32_bf16 v[108:111], v[150:153], v[194:197], v[108:111]
	v_mfma_f32_16x16x32_bf16 v[100:103], v[158:161], v[194:197], v[100:103]
	v_mfma_f32_16x16x32_bf16 v[92:95], v[150:153], v[202:205], v[92:95]
	v_mfma_f32_16x16x32_bf16 v[84:87], v[158:161], v[202:205], v[84:87]
	v_mfma_f32_16x16x32_bf16 v[76:79], v[150:153], v[210:213], v[76:79]
	v_mfma_f32_16x16x32_bf16 v[68:71], v[158:161], v[210:213], v[68:71]
	v_mfma_f32_16x16x32_bf16 v[116:119], v[154:157], v[190:193], v[116:119]
	v_mfma_f32_16x16x32_bf16 v[112:115], v[162:165], v[190:193], v[112:115]
	v_mfma_f32_16x16x32_bf16 v[108:111], v[154:157], v[198:201], v[108:111]
	v_mfma_f32_16x16x32_bf16 v[100:103], v[162:165], v[198:201], v[100:103]
	v_mfma_f32_16x16x32_bf16 v[92:95], v[154:157], v[206:209], v[92:95]
	v_mfma_f32_16x16x32_bf16 v[84:87], v[162:165], v[206:209], v[84:87]
	v_mfma_f32_16x16x32_bf16 v[76:79], v[154:157], v[214:217], v[76:79]
	v_mfma_f32_16x16x32_bf16 v[68:71], v[162:165], v[214:217], v[68:71]
	s_setprio 0
	s_setprio 1
	v_mfma_f32_16x16x32_bf16 v[124:127], v[166:169], v[182:185], v[124:127]
	v_mfma_f32_16x16x32_bf16 v[120:123], v[174:177], v[182:185], v[120:123]
	v_mfma_f32_16x16x32_bf16 v[104:107], v[166:169], v[194:197], v[104:107]
	v_mfma_f32_16x16x32_bf16 v[96:99], v[174:177], v[194:197], v[96:99]
	v_mfma_f32_16x16x32_bf16 v[88:91], v[166:169], v[202:205], v[88:91]
	v_mfma_f32_16x16x32_bf16 v[80:83], v[174:177], v[202:205], v[80:83]
	v_mfma_f32_16x16x32_bf16 v[72:75], v[166:169], v[210:213], v[72:75]
	v_mfma_f32_16x16x32_bf16 v[64:67], v[174:177], v[210:213], v[64:67]
	v_mfma_f32_16x16x32_bf16 v[124:127], v[170:173], v[190:193], v[124:127]
	v_mfma_f32_16x16x32_bf16 v[120:123], v[178:181], v[190:193], v[120:123]
	v_mfma_f32_16x16x32_bf16 v[104:107], v[170:173], v[198:201], v[104:107]
	v_mfma_f32_16x16x32_bf16 v[96:99], v[178:181], v[198:201], v[96:99]
	v_mfma_f32_16x16x32_bf16 v[88:91], v[170:173], v[206:209], v[88:91]
	v_mfma_f32_16x16x32_bf16 v[80:83], v[178:181], v[206:209], v[80:83]
	v_mfma_f32_16x16x32_bf16 v[72:75], v[170:173], v[214:217], v[72:75]
	v_mfma_f32_16x16x32_bf16 v[64:67], v[178:181], v[214:217], v[64:67]
	s_setprio 0
	s_barrier
	s_add_i32 s8, s86, s14
	v_lshl_add_u64 v[186:187], vcc, 0, v[128:129]
	s_mov_b32 m0, s8
	ds_read_b128 v[182:185], v145 offset:16384
	ds_read_b128 v[190:193], v145 offset:17408
	ds_read_b128 v[194:197], v145 offset:18432
	ds_read_b128 v[198:201], v145 offset:19456
	ds_read_b128 v[202:205], v145 offset:20480
	ds_read_b128 v[206:209], v145 offset:21504
	ds_read_b128 v[210:213], v145 offset:22528
	ds_read_b128 v[214:217], v145 offset:23552
	global_load_lds_dwordx4 v[186:187], off
	v_lshl_add_u64 v[220:221], v[186:187], 0, s[4:5]
	s_add_i32 m0, s8, 0x2000
	s_add_i32 s8, s89, s14
	global_load_lds_dwordx4 v[220:221], off
	v_lshl_add_u64 v[220:221], v[186:187], 0, s[6:7]
	s_mov_b32 m0, s8
	s_nop 0
	global_load_lds_dwordx4 v[220:221], off
	v_lshl_add_u64 v[220:221], v[186:187], 0, s[30:31]
	s_add_i32 m0, s8, 0x2000
	s_nop 0
	global_load_lds_dwordx4 v[220:221], off
	v_lshl_add_u64 v[220:221], s[96:97], 0, v[128:129]
	s_mov_b32 m0, s18
	v_lshl_add_u64 v[222:223], v[220:221], 0, s[4:5]
	global_load_lds_dwordx4 v[220:221], off
	s_mov_b32 m0, s19
	s_nop 0
	global_load_lds_dwordx4 v[222:223], off
	s_waitcnt vmcnt(8)
	s_waitcnt lgkmcnt(0)
	s_barrier
	s_setprio 1
	s_waitcnt lgkmcnt(0)
	v_mfma_f32_16x16x32_bf16 v[60:63], v[150:153], v[182:185], v[60:63]
	v_mfma_f32_16x16x32_bf16 v[52:55], v[158:161], v[182:185], v[52:55]
	v_mfma_f32_16x16x32_bf16 v[44:47], v[150:153], v[194:197], v[44:47]
	v_mfma_f32_16x16x32_bf16 v[36:39], v[158:161], v[194:197], v[36:39]
	v_mfma_f32_16x16x32_bf16 v[28:31], v[150:153], v[202:205], v[28:31]
	v_mfma_f32_16x16x32_bf16 v[20:23], v[158:161], v[202:205], v[20:23]
	v_mfma_f32_16x16x32_bf16 v[12:15], v[150:153], v[210:213], v[12:15]
	v_mfma_f32_16x16x32_bf16 v[4:7], v[158:161], v[210:213], v[4:7]
	v_mfma_f32_16x16x32_bf16 v[60:63], v[154:157], v[190:193], v[60:63]
	v_mfma_f32_16x16x32_bf16 v[52:55], v[162:165], v[190:193], v[52:55]
	v_mfma_f32_16x16x32_bf16 v[44:47], v[154:157], v[198:201], v[44:47]
	v_mfma_f32_16x16x32_bf16 v[36:39], v[162:165], v[198:201], v[36:39]
	v_mfma_f32_16x16x32_bf16 v[28:31], v[154:157], v[206:209], v[28:31]
	v_mfma_f32_16x16x32_bf16 v[20:23], v[162:165], v[206:209], v[20:23]
	v_mfma_f32_16x16x32_bf16 v[12:15], v[154:157], v[214:217], v[12:15]
	v_mfma_f32_16x16x32_bf16 v[4:7], v[162:165], v[214:217], v[4:7]
	s_setprio 0
	s_setprio 1
	v_mfma_f32_16x16x32_bf16 v[56:59], v[166:169], v[182:185], v[56:59]
	v_mfma_f32_16x16x32_bf16 v[48:51], v[174:177], v[182:185], v[48:51]
	v_mfma_f32_16x16x32_bf16 v[40:43], v[166:169], v[194:197], v[40:43]
	v_mfma_f32_16x16x32_bf16 v[32:35], v[174:177], v[194:197], v[32:35]
	v_mfma_f32_16x16x32_bf16 v[24:27], v[166:169], v[202:205], v[24:27]
	v_mfma_f32_16x16x32_bf16 v[16:19], v[174:177], v[202:205], v[16:19]
	v_mfma_f32_16x16x32_bf16 v[8:11], v[166:169], v[210:213], v[8:11]
	v_mfma_f32_16x16x32_bf16 v[0:3], v[174:177], v[210:213], v[0:3]
	v_mfma_f32_16x16x32_bf16 v[56:59], v[170:173], v[190:193], v[56:59]
	v_mfma_f32_16x16x32_bf16 v[48:51], v[178:181], v[190:193], v[48:51]
	v_mfma_f32_16x16x32_bf16 v[40:43], v[170:173], v[198:201], v[40:43]
	v_mfma_f32_16x16x32_bf16 v[32:35], v[178:181], v[198:201], v[32:35]
	v_mfma_f32_16x16x32_bf16 v[24:27], v[170:173], v[206:209], v[24:27]
	v_mfma_f32_16x16x32_bf16 v[16:19], v[178:181], v[206:209], v[16:19]
	v_mfma_f32_16x16x32_bf16 v[8:11], v[170:173], v[214:217], v[8:11]
	v_mfma_f32_16x16x32_bf16 v[0:3], v[178:181], v[214:217], v[0:3]
	s_setprio 0
	s_barrier
; #define PG8_STAGE(bufoff, gbase, voff) do { _Pragma("unroll") for (int _i = 0; _i < 2; ++_i) \
;         __builtin_amdgcn_global_load_lds((const unsigned*)((const char*)(gbase) + (voff)[_i]), (PG8_LAS unsigned*)(lds + (bufoff) + ldsw + _i * 8192), 16, 0, 0); } while (0)
; #define PG8_LDA(dst, b, h) do { _Pragma("unroll") for (int m = 0; m < 4; ++m) _Pragma("unroll") for (int k = 0; k < 2; ++k) dst[m][k] = *(const PG8_LAS bf16x8*)(lds + PG8_SA(b, h) + aoff + m * 2048 + k * 1024); } while (0)
; #define PG8_LDB(dst, b, h) do { _Pragma("unroll") for (int n = 0; n < 2; ++n) _Pragma("unroll") for (int k = 0; k < 2; ++k) dst[n][k] = *(const PG8_LAS bf16x8*)(lds + PG8_SB(b, h) + boff + n * 2048 + k * 1024); } while (0)
; #define PG8_MMA(ai, bj, At, Bt) do { __builtin_amdgcn_s_setprio(1); _Pragma("unroll") for (int m = 0; m < 4; ++m) _Pragma("unroll") for (int n = 0; n < 2; ++n) _Pragma("unroll") for (int k = 0; k < 2; ++k) \
;         acc[ai][bj][m][n] = __builtin_amdgcn_mfma_f32_16x16x32_bf16(Bt[n][k], At[m][k], acc[ai][bj][m][n], 0, 0, 0); __builtin_amdgcn_s_setprio(0); } while (0)
; #define PG8_WAIT_V(n) asm volatile("s_waitcnt vmcnt(" #n ")" ::: "memory")
; #define PG8_WAIT_L(n) asm volatile("s_waitcnt lgkmcnt(" #n ")" ::: "memory")
; #define PG8_BAR __builtin_amdgcn_s_barrier()
; #define PG8_SCHED __builtin_amdgcn_sched_barrier(0)
; template <class Epi, class Sched, bool ALIGN_EPI = false, bool SP2 = false>
; __device__ __forceinline__ void gemm_phase(PG8_LAS unsigned char* lds, const Gemm g, const Sched& S, const Epi& E) {
;     ...
;             PG8_LDB(B0, 1, 0); PG8_LDB(B1, 1, 1); PG8_SCHED; PG8_LDA(At, 1, 0); PG8_STAGE(PG8_SA(0, 1), a2 + hstepA, voffA);
;             PG8_WAIT_V(8); PG8_WAIT_L(0); PG8_BAR; PG8_MMA(0, 0, At, B0); PG8_MMA(0, 1, At, B1); PG8_BAR; PG8_SCHED;
;             PG8_LDA(At, 1, 1); PG8_STAGE(PG8_SB(1, 0), b3, voffB); PG8_STAGE(PG8_SB(1, 1), b3 + hstepB, voffB); PG8_STAGE(PG8_SA(1, 0), a3, voffA);
;             PG8_WAIT_V(8); PG8_WAIT_L(0); PG8_BAR; PG8_MMA(1, 0, At, B0); PG8_MMA(1, 1, At, B1); PG8_BAR; PG8_SCHED;
	ds_read_b128 v[150:153], v146
	ds_read_b128 v[154:157], v146 offset:1024
	ds_read_b128 v[158:161], v146 offset:2048
	ds_read_b128 v[162:165], v146 offset:3072
	ds_read_b128 v[166:169], v147
	ds_read_b128 v[170:173], v147 offset:1024
	ds_read_b128 v[174:177], v147 offset:2048
	ds_read_b128 v[178:181], v147 offset:3072
	s_mov_b32 m0, s74
	v_lshl_add_u64 v[222:223], v[220:221], 0, s[6:7]
	ds_read_b128 v[182:185], v145 offset:32768
	ds_read_b128 v[190:193], v145 offset:33792
	ds_read_b128 v[194:197], v145 offset:34816
	ds_read_b128 v[198:201], v145 offset:35840
	ds_read_b128 v[202:205], v145 offset:36864
	ds_read_b128 v[206:209], v145 offset:37888
	ds_read_b128 v[210:213], v145 offset:38912
	ds_read_b128 v[214:217], v145 offset:39936
	global_load_lds_dwordx4 v[222:223], off
	v_lshl_add_u64 v[222:223], v[220:221], 0, s[30:31]
	s_mov_b32 m0, s75
	s_nop 0
	global_load_lds_dwordx4 v[222:223], off
	s_waitcnt vmcnt(8)
	s_waitcnt lgkmcnt(0)
	s_barrier
	s_setprio 1
	s_waitcnt lgkmcnt(0)
	v_mfma_f32_16x16x32_bf16 v[116:119], v[150:153], v[182:185], v[116:119]
	v_mfma_f32_16x16x32_bf16 v[112:115], v[158:161], v[182:185], v[112:115]
	v_mfma_f32_16x16x32_bf16 v[108:111], v[150:153], v[194:197], v[108:111]
	v_mfma_f32_16x16x32_bf16 v[100:103], v[158:161], v[194:197], v[100:103]
	v_mfma_f32_16x16x32_bf16 v[92:95], v[150:153], v[202:205], v[92:95]
	v_mfma_f32_16x16x32_bf16 v[84:87], v[158:161], v[202:205], v[84:87]
	v_mfma_f32_16x16x32_bf16 v[76:79], v[150:153], v[210:213], v[76:79]
	v_mfma_f32_16x16x32_bf16 v[68:71], v[158:161], v[210:213], v[68:71]
	v_mfma_f32_16x16x32_bf16 v[116:119], v[154:157], v[190:193], v[116:119]
	v_mfma_f32_16x16x32_bf16 v[112:115], v[162:165], v[190:193], v[112:115]
	v_mfma_f32_16x16x32_bf16 v[108:111], v[154:157], v[198:201], v[108:111]
	v_mfma_f32_16x16x32_bf16 v[100:103], v[162:165], v[198:201], v[100:103]
	v_mfma_f32_16x16x32_bf16 v[92:95], v[154:157], v[206:209], v[92:95]
	v_mfma_f32_16x16x32_bf16 v[84:87], v[162:165], v[206:209], v[84:87]
	v_mfma_f32_16x16x32_bf16 v[76:79], v[154:157], v[214:217], v[76:79]
	v_mfma_f32_16x16x32_bf16 v[68:71], v[162:165], v[214:217], v[68:71]
	s_setprio 0
	s_setprio 1
	v_mfma_f32_16x16x32_bf16 v[124:127], v[166:169], v[182:185], v[124:127]
	v_mfma_f32_16x16x32_bf16 v[120:123], v[174:177], v[182:185], v[120:123]
	v_mfma_f32_16x16x32_bf16 v[104:107], v[166:169], v[194:197], v[104:107]
	v_mfma_f32_16x16x32_bf16 v[96:99], v[174:177], v[194:197], v[96:99]
	v_mfma_f32_16x16x32_bf16 v[88:91], v[166:169], v[202:205], v[88:91]
	v_mfma_f32_16x16x32_bf16 v[80:83], v[174:177], v[202:205], v[80:83]
	v_mfma_f32_16x16x32_bf16 v[72:75], v[166:169], v[210:213], v[72:75]
	v_mfma_f32_16x16x32_bf16 v[64:67], v[174:177], v[210:213], v[64:67]
	v_mfma_f32_16x16x32_bf16 v[124:127], v[170:173], v[190:193], v[124:127]
	v_mfma_f32_16x16x32_bf16 v[120:123], v[178:181], v[190:193], v[120:123]
	v_mfma_f32_16x16x32_bf16 v[104:107], v[170:173], v[198:201], v[104:107]
	v_mfma_f32_16x16x32_bf16 v[96:99], v[178:181], v[198:201], v[96:99]
	v_mfma_f32_16x16x32_bf16 v[88:91], v[170:173], v[206:209], v[88:91]
	v_mfma_f32_16x16x32_bf16 v[80:83], v[178:181], v[206:209], v[80:83]
	v_mfma_f32_16x16x32_bf16 v[72:75], v[170:173], v[214:217], v[72:75]
	v_mfma_f32_16x16x32_bf16 v[64:67], v[178:181], v[214:217], v[64:67]
	s_setprio 0
	s_barrier
	s_add_i32 s8, s90, s14
	v_lshl_add_u64 v[222:223], v[186:187], 0, s[34:35]
	s_mov_b32 m0, s8
	ds_read_b128 v[182:185], v145 offset:49152
	ds_read_b128 v[190:193], v145 offset:50176
	ds_read_b128 v[194:197], v145 offset:51200
	ds_read_b128 v[198:201], v145 offset:52224
	ds_read_b128 v[202:205], v145 offset:53248
	ds_read_b128 v[206:209], v145 offset:54272
	ds_read_b128 v[210:213], v145 offset:55296
	ds_read_b128 v[214:217], v145 offset:56320
	global_load_lds_dwordx4 v[222:223], off
	v_lshl_add_u64 v[222:223], v[186:187], 0, s[36:37]
	s_add_i32 m0, s8, 0x2000
	s_add_i32 s8, s91, s14
	global_load_lds_dwordx4 v[222:223], off
	v_lshl_add_u64 v[222:223], v[186:187], 0, s[38:39]
	s_mov_b32 m0, s8
	v_lshl_add_u64 v[186:187], v[186:187], 0, s[40:41]
	global_load_lds_dwordx4 v[222:223], off
	s_add_i32 m0, s8, 0x2000
	s_nop 0
	global_load_lds_dwordx4 v[186:187], off
	v_lshl_add_u64 v[186:187], v[220:221], 0, s[34:35]
	s_mov_b32 m0, s76
	s_nop 0
	global_load_lds_dwordx4 v[186:187], off
	v_lshl_add_u64 v[186:187], v[220:221], 0, s[36:37]
	s_mov_b32 m0, s77
	s_nop 0
	global_load_lds_dwordx4 v[186:187], off
	s_waitcnt vmcnt(8)
	s_waitcnt lgkmcnt(0)
	s_barrier
	s_setprio 1
	s_waitcnt lgkmcnt(0)
	v_mfma_f32_16x16x32_bf16 v[60:63], v[150:153], v[182:185], v[60:63]
	v_mfma_f32_16x16x32_bf16 v[52:55], v[158:161], v[182:185], v[52:55]
	v_mfma_f32_16x16x32_bf16 v[44:47], v[150:153], v[194:197], v[44:47]
	v_mfma_f32_16x16x32_bf16 v[36:39], v[158:161], v[194:197], v[36:39]
	v_mfma_f32_16x16x32_bf16 v[28:31], v[150:153], v[202:205], v[28:31]
	v_mfma_f32_16x16x32_bf16 v[20:23], v[158:161], v[202:205], v[20:23]
	v_mfma_f32_16x16x32_bf16 v[12:15], v[150:153], v[210:213], v[12:15]
	v_mfma_f32_16x16x32_bf16 v[4:7], v[158:161], v[210:213], v[4:7]
	v_mfma_f32_16x16x32_bf16 v[60:63], v[154:157], v[190:193], v[60:63]
	v_mfma_f32_16x16x32_bf16 v[52:55], v[162:165], v[190:193], v[52:55]
	v_mfma_f32_16x16x32_bf16 v[44:47], v[154:157], v[198:201], v[44:47]
	v_mfma_f32_16x16x32_bf16 v[36:39], v[162:165], v[198:201], v[36:39]
	v_mfma_f32_16x16x32_bf16 v[28:31], v[154:157], v[206:209], v[28:31]
	v_mfma_f32_16x16x32_bf16 v[20:23], v[162:165], v[206:209], v[20:23]
	v_mfma_f32_16x16x32_bf16 v[12:15], v[154:157], v[214:217], v[12:15]
	v_mfma_f32_16x16x32_bf16 v[4:7], v[162:165], v[214:217], v[4:7]
	s_setprio 0
	s_setprio 1
	v_mfma_f32_16x16x32_bf16 v[56:59], v[166:169], v[182:185], v[56:59]
	v_mfma_f32_16x16x32_bf16 v[48:51], v[174:177], v[182:185], v[48:51]
	v_mfma_f32_16x16x32_bf16 v[40:43], v[166:169], v[194:197], v[40:43]
	v_mfma_f32_16x16x32_bf16 v[32:35], v[174:177], v[194:197], v[32:35]
	v_mfma_f32_16x16x32_bf16 v[24:27], v[166:169], v[202:205], v[24:27]
	v_mfma_f32_16x16x32_bf16 v[16:19], v[174:177], v[202:205], v[16:19]
	v_mfma_f32_16x16x32_bf16 v[8:11], v[166:169], v[210:213], v[8:11]
	v_mfma_f32_16x16x32_bf16 v[0:3], v[174:177], v[210:213], v[0:3]
	v_mfma_f32_16x16x32_bf16 v[56:59], v[170:173], v[190:193], v[56:59]
	v_mfma_f32_16x16x32_bf16 v[48:51], v[178:181], v[190:193], v[48:51]
	v_mfma_f32_16x16x32_bf16 v[40:43], v[170:173], v[198:201], v[40:43]
	v_mfma_f32_16x16x32_bf16 v[32:35], v[178:181], v[198:201], v[32:35]
	v_mfma_f32_16x16x32_bf16 v[24:27], v[170:173], v[206:209], v[24:27]
	v_mfma_f32_16x16x32_bf16 v[16:19], v[178:181], v[206:209], v[16:19]
	v_mfma_f32_16x16x32_bf16 v[8:11], v[170:173], v[214:217], v[8:11]
	v_mfma_f32_16x16x32_bf16 v[0:3], v[178:181], v[214:217], v[0:3]
	s_setprio 0
	s_barrier
	s_add_i32 s94, s94, 2
	s_add_u32 s70, s70, 0x10000
	s_addc_u32 s71, s71, 0
	s_add_u32 s72, s72, 0x10000
	s_addc_u32 s73, s73, 0
	s_cmp_gt_u32 s94, 13
	s_cbranch_scc0 .LBB0_141
	s_and_b64 vcc, exec, s[54:55]
	s_cbranch_vccz .LBB0_144
	s_barrier

; #define PG8_STAGE(bufoff, gbase, voff) do { _Pragma("unroll") for (int _i = 0; _i < 2; ++_i) \
;         __builtin_amdgcn_global_load_lds((const unsigned*)((const char*)(gbase) + (voff)[_i]), (PG8_LAS unsigned*)(lds + (bufoff) + ldsw + _i * 8192), 16, 0, 0); } while (0)
; #define PG8_LDA(dst, b, h) do { _Pragma("unroll") for (int m = 0; m < 4; ++m) _Pragma("unroll") for (int k = 0; k < 2; ++k) dst[m][k] = *(const PG8_LAS bf16x8*)(lds + PG8_SA(b, h) + aoff + m * 2048 + k * 1024); } while (0)
; #define PG8_LDB(dst, b, h) do { _Pragma("unroll") for (int n = 0; n < 2; ++n) _Pragma("unroll") for (int k = 0; k < 2; ++k) dst[n][k] = *(const PG8_LAS bf16x8*)(lds + PG8_SB(b, h) + boff + n * 2048 + k * 1024); } while (0)
; #define PG8_MMA(ai, bj, At, Bt) do { __builtin_amdgcn_s_setprio(1); _Pragma("unroll") for (int m = 0; m < 4; ++m) _Pragma("unroll") for (int n = 0; n < 2; ++n) _Pragma("unroll") for (int k = 0; k < 2; ++k) \
;         acc[ai][bj][m][n] = __builtin_amdgcn_mfma_f32_16x16x32_bf16(Bt[n][k], At[m][k], acc[ai][bj][m][n], 0, 0, 0); __builtin_amdgcn_s_setprio(0); } while (0)
; #define PG8_WAIT_V(n) asm volatile("s_waitcnt vmcnt(" #n ")" ::: "memory")
; template <class Epi, class Sched, bool ALIGN_EPI = false, bool SP2 = false>
; __device__ __forceinline__ void gemm_phase(PG8_LAS unsigned char* lds, const Gemm g, const Sched& S, const Epi& E) {
;     ...
;         for (int t = 0; t < nt; t += 2) {
;             const bool last = (t == nt - 2);
;             const char* a1 = cA + (size_t)(t + 1) * kstepA;
;             const char* a2 = last ? nA : cA + (size_t)(t + 2) * kstepA; const char* b2 = last ? nB : cB + (size_t)(t + 2) * kstep;
;             const char* a3 = a2 + kstepA; const char* b3 = b2 + kstep;
;             if (last && has_next) S.a_ready(nxt);
;             if constexpr (SP2) {
;             PG8_LDB(B0, 0, 0); PG8_LDB(B1, 0, 1); PG8_SCHED; PG8_LDA(At, 0, 0); PG8_STAGE(PG8_SA(1, 1), a1 + hstepA, voffA);
;             PG8_WAIT_V(8); PG8_WAIT_L(0); PG8_BAR; PG8_MMA(0, 0, At, B0); PG8_MMA(0, 1, At, B1); PG8_BAR; PG8_SCHED;
;     ...
; #pragma unroll
;         for (int a = 0; a < 2; ++a)
; #pragma unroll
;             for (int b = 0; b < 2; ++b)
; #pragma unroll
;                 for (int m = 0; m < 4; ++m)
; #pragma unroll
;                     for (int n = 0; n < 2; ++n) acc[a][b][m][n] = (f32x4){0.f, 0.f, 0.f, 0.f};
;         cur = nxt; cA = nA; cB = nB; ++ui;
.LBB0_225:
	s_add_u32 s68, s68, 0x10000
	s_addc_u32 s69, s69, 0
	s_add_u32 s70, s70, 0x10000
	s_addc_u32 s71, s71, 0
	s_mov_b32 s73, -2
	s_waitcnt lgkmcnt(0)
.LBB0_226:
	ds_read_b128 v[112:115], v210
	ds_read_b128 v[124:127], v210 offset:1024
	ds_read_b128 v[136:139], v210 offset:2048
	ds_read_b128 v[140:143], v210 offset:3072
	ds_read_b128 v[144:147], v211
	ds_read_b128 v[148:151], v211 offset:1024
	ds_read_b128 v[152:155], v211 offset:2048
	ds_read_b128 v[156:159], v211 offset:3072
	s_cmp_eq_u32 s73, 40
	s_cselect_b32 s9, s1, s69
	s_cselect_b32 s8, s0, s68
	s_cselect_b32 s75, s63, s71
	s_cselect_b32 s74, s62, s70
	v_lshl_add_u64 v[208:209], s[68:69], 0, v[184:185]
	v_lshl_add_u64 v[216:217], v[208:209], 0, s[96:97]
	s_add_i32 m0, s15, 0xc000
	ds_read_b128 v[160:163], v212
	ds_read_b128 v[164:167], v212 offset:1024
	ds_read_b128 v[168:171], v212 offset:2048
	ds_read_b128 v[172:175], v212 offset:3072
	ds_read_b128 v[176:179], v212 offset:4096
	ds_read_b128 v[180:183], v212 offset:5120
	ds_read_b128 v[220:223], v212 offset:6144
	ds_read_b128 v[224:227], v212 offset:7168
	global_load_lds_dwordx4 v[216:217], off
	v_lshl_add_u64 v[208:209], v[208:209], 0, s[60:61]
	s_add_i32 m0, s15, 0xe000
	s_nop 0
	global_load_lds_dwordx4 v[208:209], off
	s_cmp_lg_u32 s73, -2
	s_cbranch_scc1 .Lzskip_1
	v_mov_b32_e32 v0, 0
	v_mov_b32_e32 v1, 0
	v_mov_b32_e32 v2, 0
	v_mov_b32_e32 v3, 0
	v_mov_b32_e32 v4, 0
	v_mov_b32_e32 v5, 0
	v_mov_b32_e32 v6, 0
	v_mov_b32_e32 v7, 0
	v_mov_b32_e32 v8, 0
	v_mov_b32_e32 v9, 0
	v_mov_b32_e32 v10, 0
	v_mov_b32_e32 v11, 0
	v_mov_b32_e32 v12, 0
	v_mov_b32_e32 v13, 0
	v_mov_b32_e32 v14, 0
	v_mov_b32_e32 v15, 0
	v_mov_b32_e32 v16, 0
	v_mov_b32_e32 v17, 0
	v_mov_b32_e32 v18, 0
	v_mov_b32_e32 v19, 0
	v_mov_b32_e32 v20, 0
	v_mov_b32_e32 v21, 0
	v_mov_b32_e32 v22, 0
	v_mov_b32_e32 v23, 0
	v_mov_b32_e32 v24, 0
	v_mov_b32_e32 v25, 0
	v_mov_b32_e32 v26, 0
	v_mov_b32_e32 v27, 0
	v_mov_b32_e32 v28, 0
	v_mov_b32_e32 v29, 0
	v_mov_b32_e32 v30, 0
	v_mov_b32_e32 v31, 0
	v_mov_b32_e32 v32, 0
	v_mov_b32_e32 v33, 0
	v_mov_b32_e32 v34, 0
	v_mov_b32_e32 v35, 0
	v_mov_b32_e32 v36, 0
	v_mov_b32_e32 v37, 0
	v_mov_b32_e32 v38, 0
	v_mov_b32_e32 v39, 0
	v_mov_b32_e32 v40, 0
	v_mov_b32_e32 v41, 0
	v_mov_b32_e32 v42, 0
	v_mov_b32_e32 v43, 0
	v_mov_b32_e32 v44, 0
	v_mov_b32_e32 v45, 0
	v_mov_b32_e32 v46, 0
	v_mov_b32_e32 v47, 0
	v_mov_b32_e32 v48, 0
	v_mov_b32_e32 v49, 0
	v_mov_b32_e32 v50, 0
	v_mov_b32_e32 v51, 0
	v_mov_b32_e32 v52, 0
	v_mov_b32_e32 v53, 0
	v_mov_b32_e32 v54, 0
	v_mov_b32_e32 v55, 0
	v_mov_b32_e32 v56, 0
	v_mov_b32_e32 v57, 0
	v_mov_b32_e32 v58, 0
	v_mov_b32_e32 v59, 0
	v_mov_b32_e32 v60, 0
	v_mov_b32_e32 v61, 0
	v_mov_b32_e32 v62, 0
	v_mov_b32_e32 v63, 0
	v_mov_b32_e32 v64, 0
	v_mov_b32_e32 v65, 0
	v_mov_b32_e32 v66, 0
	v_mov_b32_e32 v67, 0
	v_mov_b32_e32 v68, 0
	v_mov_b32_e32 v69, 0
	v_mov_b32_e32 v70, 0
	v_mov_b32_e32 v71, 0
	v_mov_b32_e32 v72, 0
	v_mov_b32_e32 v73, 0
	v_mov_b32_e32 v74, 0
	v_mov_b32_e32 v75, 0
	v_mov_b32_e32 v76, 0
	v_mov_b32_e32 v77, 0
	v_mov_b32_e32 v78, 0
	v_mov_b32_e32 v79, 0
	v_mov_b32_e32 v80, 0
	v_mov_b32_e32 v81, 0
	v_mov_b32_e32 v82, 0
	v_mov_b32_e32 v83, 0
	v_mov_b32_e32 v84, 0
	v_mov_b32_e32 v85, 0
	v_mov_b32_e32 v86, 0
	v_mov_b32_e32 v87, 0
	v_mov_b32_e32 v88, 0
	v_mov_b32_e32 v89, 0
	v_mov_b32_e32 v90, 0
	v_mov_b32_e32 v91, 0
	v_mov_b32_e32 v92, 0
	v_mov_b32_e32 v93, 0
	v_mov_b32_e32 v94, 0
	v_mov_b32_e32 v95, 0
	v_mov_b32_e32 v96, 0
	v_mov_b32_e32 v97, 0
	v_mov_b32_e32 v98, 0
	v_mov_b32_e32 v99, 0
	v_mov_b32_e32 v100, 0
	v_mov_b32_e32 v101, 0
	v_mov_b32_e32 v102, 0
	v_mov_b32_e32 v103, 0
	v_mov_b32_e32 v104, 0
	v_mov_b32_e32 v105, 0
	v_mov_b32_e32 v106, 0
	v_mov_b32_e32 v107, 0
	v_mov_b32_e32 v108, 0
	v_mov_b32_e32 v109, 0
	v_mov_b32_e32 v110, 0
	v_mov_b32_e32 v111, 0
	v_mov_b32_e32 v116, 0
	v_mov_b32_e32 v117, 0
	v_mov_b32_e32 v118, 0
	v_mov_b32_e32 v119, 0
	v_mov_b32_e32 v120, 0
	v_mov_b32_e32 v121, 0
	v_mov_b32_e32 v122, 0
	v_mov_b32_e32 v123, 0
	v_mov_b32_e32 v128, 0
	v_mov_b32_e32 v129, 0
	v_mov_b32_e32 v130, 0
	v_mov_b32_e32 v131, 0
	v_mov_b32_e32 v132, 0
	v_mov_b32_e32 v133, 0
	v_mov_b32_e32 v134, 0
	v_mov_b32_e32 v135, 0
.Lzskip_1:
	s_waitcnt vmcnt(8)
	s_waitcnt lgkmcnt(0)
	s_barrier
	s_setprio 1
	s_waitcnt lgkmcnt(0)
	v_mfma_f32_16x16x32_bf16 v[132:135], v[112:115], v[160:163], v[132:135]
	v_mfma_f32_16x16x32_bf16 v[128:131], v[136:139], v[160:163], v[128:131]
	v_mfma_f32_16x16x32_bf16 v[108:111], v[112:115], v[168:171], v[108:111]
	v_mfma_f32_16x16x32_bf16 v[104:107], v[136:139], v[168:171], v[104:107]
	v_mfma_f32_16x16x32_bf16 v[92:95], v[112:115], v[176:179], v[92:95]
	v_mfma_f32_16x16x32_bf16 v[88:91], v[136:139], v[176:179], v[88:91]
	v_mfma_f32_16x16x32_bf16 v[76:79], v[112:115], v[220:223], v[76:79]
	v_mfma_f32_16x16x32_bf16 v[72:75], v[136:139], v[220:223], v[72:75]
	v_mfma_f32_16x16x32_bf16 v[132:135], v[124:127], v[164:167], v[132:135]
	v_mfma_f32_16x16x32_bf16 v[128:131], v[140:143], v[164:167], v[128:131]
	v_mfma_f32_16x16x32_bf16 v[108:111], v[124:127], v[172:175], v[108:111]
	v_mfma_f32_16x16x32_bf16 v[104:107], v[140:143], v[172:175], v[104:107]
	v_mfma_f32_16x16x32_bf16 v[92:95], v[124:127], v[180:183], v[92:95]
	v_mfma_f32_16x16x32_bf16 v[88:91], v[140:143], v[180:183], v[88:91]
	v_mfma_f32_16x16x32_bf16 v[76:79], v[124:127], v[224:227], v[76:79]
	v_mfma_f32_16x16x32_bf16 v[72:75], v[140:143], v[224:227], v[72:75]
	s_setprio 0
	s_setprio 1
	v_mfma_f32_16x16x32_bf16 v[120:123], v[144:147], v[160:163], v[120:123]
	v_mfma_f32_16x16x32_bf16 v[116:119], v[152:155], v[160:163], v[116:119]
	v_mfma_f32_16x16x32_bf16 v[100:103], v[144:147], v[168:171], v[100:103]
	v_mfma_f32_16x16x32_bf16 v[96:99], v[152:155], v[168:171], v[96:99]
	v_mfma_f32_16x16x32_bf16 v[84:87], v[144:147], v[176:179], v[84:87]
	v_mfma_f32_16x16x32_bf16 v[80:83], v[152:155], v[176:179], v[80:83]
	v_mfma_f32_16x16x32_bf16 v[68:71], v[144:147], v[220:223], v[68:71]
	v_mfma_f32_16x16x32_bf16 v[64:67], v[152:155], v[220:223], v[64:67]
	v_mfma_f32_16x16x32_bf16 v[120:123], v[148:151], v[164:167], v[120:123]
	v_mfma_f32_16x16x32_bf16 v[116:119], v[156:159], v[164:167], v[116:119]
	v_mfma_f32_16x16x32_bf16 v[100:103], v[148:151], v[172:175], v[100:103]
	v_mfma_f32_16x16x32_bf16 v[96:99], v[156:159], v[172:175], v[96:99]
	v_mfma_f32_16x16x32_bf16 v[84:87], v[148:151], v[180:183], v[84:87]
	v_mfma_f32_16x16x32_bf16 v[80:83], v[156:159], v[180:183], v[80:83]
	v_mfma_f32_16x16x32_bf16 v[68:71], v[148:151], v[224:227], v[68:71]
	v_mfma_f32_16x16x32_bf16 v[64:67], v[156:159], v[224:227], v[64:67]
	s_setprio 0
	s_barrier
; #define PG8_STAGE(bufoff, gbase, voff) do { _Pragma("unroll") for (int _i = 0; _i < 2; ++_i) \
;         __builtin_amdgcn_global_load_lds((const unsigned*)((const char*)(gbase) + (voff)[_i]), (PG8_LAS unsigned*)(lds + (bufoff) + ldsw + _i * 8192), 16, 0, 0); } while (0)
; #define PG8_LDA(dst, b, h) do { _Pragma("unroll") for (int m = 0; m < 4; ++m) _Pragma("unroll") for (int k = 0; k < 2; ++k) dst[m][k] = *(const PG8_LAS bf16x8*)(lds + PG8_SA(b, h) + aoff + m * 2048 + k * 1024); } while (0)
; #define PG8_LDB(dst, b, h) do { _Pragma("unroll") for (int n = 0; n < 2; ++n) _Pragma("unroll") for (int k = 0; k < 2; ++k) dst[n][k] = *(const PG8_LAS bf16x8*)(lds + PG8_SB(b, h) + boff + n * 2048 + k * 1024); } while (0)
; #define PG8_MMA(ai, bj, At, Bt) do { __builtin_amdgcn_s_setprio(1); _Pragma("unroll") for (int m = 0; m < 4; ++m) _Pragma("unroll") for (int n = 0; n < 2; ++n) _Pragma("unroll") for (int k = 0; k < 2; ++k) \
;         acc[ai][bj][m][n] = __builtin_amdgcn_mfma_f32_16x16x32_bf16(Bt[n][k], At[m][k], acc[ai][bj][m][n], 0, 0, 0); __builtin_amdgcn_s_setprio(0); } while (0)
; #define PG8_WAIT_V(n) asm volatile("s_waitcnt vmcnt(" #n ")" ::: "memory")
; #define PG8_WAIT_L(n) asm volatile("s_waitcnt lgkmcnt(" #n ")" ::: "memory")
; #define PG8_BAR __builtin_amdgcn_s_barrier()
; #define PG8_SCHED __builtin_amdgcn_sched_barrier(0)
; template <class Epi, class Sched, bool ALIGN_EPI = false, bool SP2 = false>
; __device__ __forceinline__ void gemm_phase(PG8_LAS unsigned char* lds, const Gemm g, const Sched& S, const Epi& E) {
;     ...
;             PG8_LDA(At, 0, 1); PG8_STAGE(PG8_SB(0, 0), b2, voffB); PG8_STAGE(PG8_SB(0, 1), b2 + hstepB, voffB); PG8_STAGE(PG8_SA(0, 0), a2, voffA);
;             PG8_WAIT_V(8); PG8_WAIT_L(0); PG8_BAR; PG8_MMA(1, 0, At, B0); PG8_MMA(1, 1, At, B1); PG8_BAR; PG8_SCHED;
;             PG8_LDB(B0, 1, 0); PG8_LDB(B1, 1, 1); PG8_SCHED; PG8_LDA(At, 1, 0); PG8_STAGE(PG8_SA(0, 1), a2 + hstepA, voffA);
;             PG8_WAIT_V(8); PG8_WAIT_L(0); PG8_BAR; PG8_MMA(0, 0, At, B0); PG8_MMA(0, 1, At, B1); PG8_BAR; PG8_SCHED;
	s_add_i32 s33, s89, s14
	v_lshl_add_u64 v[208:209], s[74:75], 0, v[184:185]
	s_mov_b32 m0, s33
	ds_read_b128 v[160:163], v212 offset:16384
	ds_read_b128 v[164:167], v212 offset:17408
	ds_read_b128 v[168:171], v212 offset:18432
	ds_read_b128 v[172:175], v212 offset:19456
	ds_read_b128 v[176:179], v212 offset:20480
	ds_read_b128 v[180:183], v212 offset:21504
	ds_read_b128 v[220:223], v212 offset:22528
	ds_read_b128 v[224:227], v212 offset:23552
	global_load_lds_dwordx4 v[208:209], off
	v_lshl_add_u64 v[216:217], v[208:209], 0, s[30:31]
	s_add_i32 m0, s33, 0x2000
	s_add_i32 s33, s90, s14
	global_load_lds_dwordx4 v[216:217], off
	v_lshl_add_u64 v[216:217], v[208:209], 0, s[34:35]
	s_mov_b32 m0, s33
	s_nop 0
	global_load_lds_dwordx4 v[216:217], off
	v_lshl_add_u64 v[216:217], v[208:209], 0, s[36:37]
	s_add_i32 m0, s33, 0x2000
	s_nop 0
	global_load_lds_dwordx4 v[216:217], off
	v_lshl_add_u64 v[216:217], s[8:9], 0, v[184:185]
	s_mov_b32 m0, s15
	v_lshl_add_u64 v[228:229], v[216:217], 0, s[30:31]
	global_load_lds_dwordx4 v[216:217], off
	s_mov_b32 m0, s17
	s_nop 0
	global_load_lds_dwordx4 v[228:229], off
	s_waitcnt vmcnt(8)
	s_waitcnt lgkmcnt(0)
	s_barrier
	s_setprio 1
	s_waitcnt lgkmcnt(0)
	v_mfma_f32_16x16x32_bf16 v[60:63], v[112:115], v[160:163], v[60:63]
	v_mfma_f32_16x16x32_bf16 v[56:59], v[136:139], v[160:163], v[56:59]
	v_mfma_f32_16x16x32_bf16 v[44:47], v[112:115], v[168:171], v[44:47]
	v_mfma_f32_16x16x32_bf16 v[40:43], v[136:139], v[168:171], v[40:43]
	v_mfma_f32_16x16x32_bf16 v[28:31], v[112:115], v[176:179], v[28:31]
	v_mfma_f32_16x16x32_bf16 v[24:27], v[136:139], v[176:179], v[24:27]
	v_mfma_f32_16x16x32_bf16 v[12:15], v[112:115], v[220:223], v[12:15]
	v_mfma_f32_16x16x32_bf16 v[8:11], v[136:139], v[220:223], v[8:11]
	v_mfma_f32_16x16x32_bf16 v[60:63], v[124:127], v[164:167], v[60:63]
	v_mfma_f32_16x16x32_bf16 v[56:59], v[140:143], v[164:167], v[56:59]
	v_mfma_f32_16x16x32_bf16 v[44:47], v[124:127], v[172:175], v[44:47]
	v_mfma_f32_16x16x32_bf16 v[40:43], v[140:143], v[172:175], v[40:43]
	v_mfma_f32_16x16x32_bf16 v[28:31], v[124:127], v[180:183], v[28:31]
	v_mfma_f32_16x16x32_bf16 v[24:27], v[140:143], v[180:183], v[24:27]
	v_mfma_f32_16x16x32_bf16 v[12:15], v[124:127], v[224:227], v[12:15]
	v_mfma_f32_16x16x32_bf16 v[8:11], v[140:143], v[224:227], v[8:11]
	s_setprio 0
	s_setprio 1
	v_mfma_f32_16x16x32_bf16 v[52:55], v[144:147], v[160:163], v[52:55]
	v_mfma_f32_16x16x32_bf16 v[48:51], v[152:155], v[160:163], v[48:51]
	v_mfma_f32_16x16x32_bf16 v[36:39], v[144:147], v[168:171], v[36:39]
	v_mfma_f32_16x16x32_bf16 v[32:35], v[152:155], v[168:171], v[32:35]
	v_mfma_f32_16x16x32_bf16 v[20:23], v[144:147], v[176:179], v[20:23]
	v_mfma_f32_16x16x32_bf16 v[16:19], v[152:155], v[176:179], v[16:19]
	v_mfma_f32_16x16x32_bf16 v[4:7], v[144:147], v[220:223], v[4:7]
	v_mfma_f32_16x16x32_bf16 v[0:3], v[152:155], v[220:223], v[0:3]
	v_mfma_f32_16x16x32_bf16 v[52:55], v[148:151], v[164:167], v[52:55]
	v_mfma_f32_16x16x32_bf16 v[48:51], v[156:159], v[164:167], v[48:51]
	v_mfma_f32_16x16x32_bf16 v[36:39], v[148:151], v[172:175], v[36:39]
	v_mfma_f32_16x16x32_bf16 v[32:35], v[156:159], v[172:175], v[32:35]
	v_mfma_f32_16x16x32_bf16 v[20:23], v[148:151], v[180:183], v[20:23]
	v_mfma_f32_16x16x32_bf16 v[16:19], v[156:159], v[180:183], v[16:19]
	v_mfma_f32_16x16x32_bf16 v[4:7], v[148:151], v[224:227], v[4:7]
	v_mfma_f32_16x16x32_bf16 v[0:3], v[156:159], v[224:227], v[0:3]
	s_setprio 0
	s_barrier
	ds_read_b128 v[112:115], v213
	ds_read_b128 v[124:127], v213 offset:1024
	ds_read_b128 v[136:139], v213 offset:2048
	ds_read_b128 v[140:143], v213 offset:3072
	ds_read_b128 v[144:147], v214
	ds_read_b128 v[148:151], v214 offset:1024
	ds_read_b128 v[152:155], v214 offset:2048
	ds_read_b128 v[156:159], v214 offset:3072
	s_mov_b32 m0, s18
	v_lshl_add_u64 v[228:229], v[216:217], 0, s[34:35]
	ds_read_b128 v[160:163], v212 offset:32768
	ds_read_b128 v[164:167], v212 offset:33792
	ds_read_b128 v[168:171], v212 offset:34816
	ds_read_b128 v[172:175], v212 offset:35840
	ds_read_b128 v[176:179], v212 offset:36864
	ds_read_b128 v[180:183], v212 offset:37888
	ds_read_b128 v[220:223], v212 offset:38912
	ds_read_b128 v[224:227], v212 offset:39936
	global_load_lds_dwordx4 v[228:229], off
	v_lshl_add_u64 v[228:229], v[216:217], 0, s[36:37]
	s_mov_b32 m0, s19
	s_nop 0
	global_load_lds_dwordx4 v[228:229], off
	s_waitcnt vmcnt(8)
	s_waitcnt lgkmcnt(0)
	s_barrier
; #define PG8_STAGE(bufoff, gbase, voff) do { _Pragma("unroll") for (int _i = 0; _i < 2; ++_i) \
;         __builtin_amdgcn_global_load_lds((const unsigned*)((const char*)(gbase) + (voff)[_i]), (PG8_LAS unsigned*)(lds + (bufoff) + ldsw + _i * 8192), 16, 0, 0); } while (0)
; #define PG8_LDA(dst, b, h) do { _Pragma("unroll") for (int m = 0; m < 4; ++m) _Pragma("unroll") for (int k = 0; k < 2; ++k) dst[m][k] = *(const PG8_LAS bf16x8*)(lds + PG8_SA(b, h) + aoff + m * 2048 + k * 1024); } while (0)
; #define PG8_MMA(ai, bj, At, Bt) do { __builtin_amdgcn_s_setprio(1); _Pragma("unroll") for (int m = 0; m < 4; ++m) _Pragma("unroll") for (int n = 0; n < 2; ++n) _Pragma("unroll") for (int k = 0; k < 2; ++k) \
;         acc[ai][bj][m][n] = __builtin_amdgcn_mfma_f32_16x16x32_bf16(Bt[n][k], At[m][k], acc[ai][bj][m][n], 0, 0, 0); __builtin_amdgcn_s_setprio(0); } while (0)
; #define PG8_WAIT_V(n) asm volatile("s_waitcnt vmcnt(" #n ")" ::: "memory")
; #define PG8_WAIT_L(n) asm volatile("s_waitcnt lgkmcnt(" #n ")" ::: "memory")
; #define PG8_BAR __builtin_amdgcn_s_barrier()
; #define PG8_SCHED __builtin_amdgcn_sched_barrier(0)
; template <class Epi, class Sched, bool ALIGN_EPI = false, bool SP2 = false>
; __device__ __forceinline__ void gemm_phase(PG8_LAS unsigned char* lds, const Gemm g, const Sched& S, const Epi& E) {
;     ...
;         for (int t = 0; t < nt; t += 2) {
;             const bool last = (t == nt - 2);
;             const char* a1 = cA + (size_t)(t + 1) * kstepA;
;             const char* a2 = last ? nA : cA + (size_t)(t + 2) * kstepA; const char* b2 = last ? nB : cB + (size_t)(t + 2) * kstep;
;             const char* a3 = a2 + kstepA; const char* b3 = b2 + kstep;
;     ...
;             PG8_WAIT_V(8); PG8_WAIT_L(0); PG8_BAR; PG8_MMA(0, 0, At, B0); PG8_MMA(0, 1, At, B1); PG8_BAR; PG8_SCHED;
;             PG8_LDA(At, 1, 1); PG8_STAGE(PG8_SB(1, 0), b3, voffB); PG8_STAGE(PG8_SB(1, 1), b3 + hstepB, voffB); PG8_STAGE(PG8_SA(1, 0), a3, voffA);
;             PG8_WAIT_V(8); PG8_WAIT_L(0); PG8_BAR; PG8_MMA(1, 0, At, B0); PG8_MMA(1, 1, At, B1); PG8_BAR; PG8_SCHED;
	s_setprio 1
	s_waitcnt lgkmcnt(0)
	v_mfma_f32_16x16x32_bf16 v[132:135], v[112:115], v[160:163], v[132:135]
	v_mfma_f32_16x16x32_bf16 v[128:131], v[136:139], v[160:163], v[128:131]
	v_mfma_f32_16x16x32_bf16 v[108:111], v[112:115], v[168:171], v[108:111]
	v_mfma_f32_16x16x32_bf16 v[104:107], v[136:139], v[168:171], v[104:107]
	v_mfma_f32_16x16x32_bf16 v[92:95], v[112:115], v[176:179], v[92:95]
	v_mfma_f32_16x16x32_bf16 v[88:91], v[136:139], v[176:179], v[88:91]
	v_mfma_f32_16x16x32_bf16 v[76:79], v[112:115], v[220:223], v[76:79]
	v_mfma_f32_16x16x32_bf16 v[72:75], v[136:139], v[220:223], v[72:75]
	v_mfma_f32_16x16x32_bf16 v[132:135], v[124:127], v[164:167], v[132:135]
	v_mfma_f32_16x16x32_bf16 v[128:131], v[140:143], v[164:167], v[128:131]
	v_mfma_f32_16x16x32_bf16 v[108:111], v[124:127], v[172:175], v[108:111]
	v_mfma_f32_16x16x32_bf16 v[104:107], v[140:143], v[172:175], v[104:107]
	v_mfma_f32_16x16x32_bf16 v[92:95], v[124:127], v[180:183], v[92:95]
	v_mfma_f32_16x16x32_bf16 v[88:91], v[140:143], v[180:183], v[88:91]
	v_mfma_f32_16x16x32_bf16 v[76:79], v[124:127], v[224:227], v[76:79]
	v_mfma_f32_16x16x32_bf16 v[72:75], v[140:143], v[224:227], v[72:75]
	s_setprio 0
	s_setprio 1
	v_mfma_f32_16x16x32_bf16 v[120:123], v[144:147], v[160:163], v[120:123]
	v_mfma_f32_16x16x32_bf16 v[116:119], v[152:155], v[160:163], v[116:119]
	v_mfma_f32_16x16x32_bf16 v[100:103], v[144:147], v[168:171], v[100:103]
	v_mfma_f32_16x16x32_bf16 v[96:99], v[152:155], v[168:171], v[96:99]
	v_mfma_f32_16x16x32_bf16 v[84:87], v[144:147], v[176:179], v[84:87]
	v_mfma_f32_16x16x32_bf16 v[80:83], v[152:155], v[176:179], v[80:83]
	v_mfma_f32_16x16x32_bf16 v[68:71], v[144:147], v[220:223], v[68:71]
	v_mfma_f32_16x16x32_bf16 v[64:67], v[152:155], v[220:223], v[64:67]
	v_mfma_f32_16x16x32_bf16 v[120:123], v[148:151], v[164:167], v[120:123]
	v_mfma_f32_16x16x32_bf16 v[116:119], v[156:159], v[164:167], v[116:119]
	v_mfma_f32_16x16x32_bf16 v[100:103], v[148:151], v[172:175], v[100:103]
	v_mfma_f32_16x16x32_bf16 v[96:99], v[156:159], v[172:175], v[96:99]
	v_mfma_f32_16x16x32_bf16 v[84:87], v[148:151], v[180:183], v[84:87]
	v_mfma_f32_16x16x32_bf16 v[80:83], v[156:159], v[180:183], v[80:83]
	v_mfma_f32_16x16x32_bf16 v[68:71], v[148:151], v[224:227], v[68:71]
	v_mfma_f32_16x16x32_bf16 v[64:67], v[156:159], v[224:227], v[64:67]
	s_setprio 0
	s_barrier
	s_add_i32 s8, s91, s14
	v_lshl_add_u64 v[228:229], v[208:209], 0, s[38:39]
	s_mov_b32 m0, s8
	ds_read_b128 v[160:163], v212 offset:49152
	ds_read_b128 v[164:167], v212 offset:50176
	ds_read_b128 v[168:171], v212 offset:51200
	ds_read_b128 v[172:175], v212 offset:52224
	ds_read_b128 v[176:179], v212 offset:53248
	ds_read_b128 v[180:183], v212 offset:54272
	ds_read_b128 v[220:223], v212 offset:55296
	ds_read_b128 v[224:227], v212 offset:56320
	global_load_lds_dwordx4 v[228:229], off
	v_lshl_add_u64 v[228:229], v[208:209], 0, s[40:41]
	s_add_i32 m0, s8, 0x2000
	s_add_i32 s8, s92, s14
	global_load_lds_dwordx4 v[228:229], off
	v_lshl_add_u64 v[228:229], v[208:209], 0, s[52:53]
	s_mov_b32 m0, s8
	v_lshl_add_u64 v[208:209], v[208:209], 0, s[54:55]
	global_load_lds_dwordx4 v[228:229], off
	s_add_i32 m0, s8, 0x2000
	s_nop 0
	global_load_lds_dwordx4 v[208:209], off
	v_lshl_add_u64 v[208:209], v[216:217], 0, s[38:39]
	s_mov_b32 m0, s78
	s_nop 0
	global_load_lds_dwordx4 v[208:209], off
	v_lshl_add_u64 v[208:209], v[216:217], 0, s[40:41]
	s_mov_b32 m0, s79
	s_nop 0
	global_load_lds_dwordx4 v[208:209], off
	s_waitcnt vmcnt(8)
	s_waitcnt lgkmcnt(0)
	s_barrier
	s_setprio 1
	s_waitcnt lgkmcnt(0)
	v_mfma_f32_16x16x32_bf16 v[60:63], v[112:115], v[160:163], v[60:63]
	v_mfma_f32_16x16x32_bf16 v[56:59], v[136:139], v[160:163], v[56:59]
	v_mfma_f32_16x16x32_bf16 v[44:47], v[112:115], v[168:171], v[44:47]
	v_mfma_f32_16x16x32_bf16 v[40:43], v[136:139], v[168:171], v[40:43]
	v_mfma_f32_16x16x32_bf16 v[28:31], v[112:115], v[176:179], v[28:31]
	v_mfma_f32_16x16x32_bf16 v[24:27], v[136:139], v[176:179], v[24:27]
	v_mfma_f32_16x16x32_bf16 v[12:15], v[112:115], v[220:223], v[12:15]
	v_mfma_f32_16x16x32_bf16 v[8:11], v[136:139], v[220:223], v[8:11]
	v_mfma_f32_16x16x32_bf16 v[60:63], v[124:127], v[164:167], v[60:63]
	v_mfma_f32_16x16x32_bf16 v[56:59], v[140:143], v[164:167], v[56:59]
	v_mfma_f32_16x16x32_bf16 v[44:47], v[124:127], v[172:175], v[44:47]
	v_mfma_f32_16x16x32_bf16 v[40:43], v[140:143], v[172:175], v[40:43]
	v_mfma_f32_16x16x32_bf16 v[28:31], v[124:127], v[180:183], v[28:31]
	v_mfma_f32_16x16x32_bf16 v[24:27], v[140:143], v[180:183], v[24:27]
	v_mfma_f32_16x16x32_bf16 v[12:15], v[124:127], v[224:227], v[12:15]
	v_mfma_f32_16x16x32_bf16 v[8:11], v[140:143], v[224:227], v[8:11]
	s_setprio 0
	s_setprio 1
	v_mfma_f32_16x16x32_bf16 v[52:55], v[144:147], v[160:163], v[52:55]
	v_mfma_f32_16x16x32_bf16 v[48:51], v[152:155], v[160:163], v[48:51]
	v_mfma_f32_16x16x32_bf16 v[36:39], v[144:147], v[168:171], v[36:39]
	v_mfma_f32_16x16x32_bf16 v[32:35], v[152:155], v[168:171], v[32:35]
	v_mfma_f32_16x16x32_bf16 v[20:23], v[144:147], v[176:179], v[20:23]
	v_mfma_f32_16x16x32_bf16 v[16:19], v[152:155], v[176:179], v[16:19]
	v_mfma_f32_16x16x32_bf16 v[4:7], v[144:147], v[220:223], v[4:7]
	v_mfma_f32_16x16x32_bf16 v[0:3], v[152:155], v[220:223], v[0:3]
	v_mfma_f32_16x16x32_bf16 v[52:55], v[148:151], v[164:167], v[52:55]
	v_mfma_f32_16x16x32_bf16 v[48:51], v[156:159], v[164:167], v[48:51]
	v_mfma_f32_16x16x32_bf16 v[36:39], v[148:151], v[172:175], v[36:39]
	v_mfma_f32_16x16x32_bf16 v[32:35], v[156:159], v[172:175], v[32:35]
	v_mfma_f32_16x16x32_bf16 v[20:23], v[148:151], v[180:183], v[20:23]
	v_mfma_f32_16x16x32_bf16 v[16:19], v[156:159], v[180:183], v[16:19]
	v_mfma_f32_16x16x32_bf16 v[4:7], v[148:151], v[224:227], v[4:7]
	v_mfma_f32_16x16x32_bf16 v[0:3], v[156:159], v[224:227], v[0:3]
	s_setprio 0
	s_barrier
	s_add_i32 s73, s73, 2
	s_add_u32 s68, s68, 0x10000
	s_addc_u32 s69, s69, 0
	s_add_u32 s70, s70, 0x10000
	s_addc_u32 s71, s71, 0
	s_cmp_gt_u32 s73, 41
	s_cbranch_scc0 .LBB0_226
	s_and_b64 vcc, exec, s[58:59]
	s_cbranch_vccz .LBB0_229
	s_barrier

; #define PG8_STAGE(bufoff, gbase, voff) do { _Pragma("unroll") for (int _i = 0; _i < 2; ++_i) \
;         __builtin_amdgcn_global_load_lds((const unsigned*)((const char*)(gbase) + (voff)[_i]), (PG8_LAS unsigned*)(lds + (bufoff) + ldsw + _i * 8192), 16, 0, 0); } while (0)
; #define PG8_LDA(dst, b, h) do { _Pragma("unroll") for (int m = 0; m < 4; ++m) _Pragma("unroll") for (int k = 0; k < 2; ++k) dst[m][k] = *(const PG8_LAS bf16x8*)(lds + PG8_SA(b, h) + aoff + m * 2048 + k * 1024); } while (0)
; #define PG8_LDB(dst, b, h) do { _Pragma("unroll") for (int n = 0; n < 2; ++n) _Pragma("unroll") for (int k = 0; k < 2; ++k) dst[n][k] = *(const PG8_LAS bf16x8*)(lds + PG8_SB(b, h) + boff + n * 2048 + k * 1024); } while (0)
; #define PG8_WAIT_V(n) asm volatile("s_waitcnt vmcnt(" #n ")" ::: "memory")
; #define PG8_WAIT_L(n) asm volatile("s_waitcnt lgkmcnt(" #n ")" ::: "memory")
; #define PG8_BAR __builtin_amdgcn_s_barrier()
; #define PG8_SCHED __builtin_amdgcn_sched_barrier(0)
; template <class Epi, class Sched, bool ALIGN_EPI = false, bool SP2 = false>
; __device__ __forceinline__ void gemm_phase(PG8_LAS unsigned char* lds, const Gemm g, const Sched& S, const Epi& E) {
;     ...
;         const bool has_next = S.next(ui + 1, nxt);
;         const char* nA = has_next ? (const char*)g.A + (size_t)nxt.pm * tstepA : cA; const char* nB = has_next ? (const char*)g.Bt + (size_t)nxt.pn * tstepB : cB;
;         for (int t = 0; t < nt; t += 2) {
;             const bool last = (t == nt - 2);
;             const char* a1 = cA + (size_t)(t + 1) * kstepA;
;             const char* a2 = last ? nA : cA + (size_t)(t + 2) * kstepA; const char* b2 = last ? nB : cB + (size_t)(t + 2) * kstep;
;             const char* a3 = a2 + kstepA; const char* b3 = b2 + kstep;
;             if (last && has_next) S.a_ready(nxt);
;             if constexpr (SP2) {
;             PG8_LDB(B0, 0, 0); PG8_LDB(B1, 0, 1); PG8_SCHED; PG8_LDA(At, 0, 0); PG8_STAGE(PG8_SA(1, 1), a1 + hstepA, voffA);
;             PG8_WAIT_V(8); PG8_WAIT_L(0); PG8_BAR; PG8_MMA(0, 0, At, B0); PG8_MMA(0, 1, At, B1); PG8_BAR; PG8_SCHED;
;     ...
; #pragma unroll
;         for (int a = 0; a < 2; ++a)
; #pragma unroll
;             for (int b = 0; b < 2; ++b)
; #pragma unroll
;                 for (int m = 0; m < 4; ++m)
; #pragma unroll
;                     for (int n = 0; n < 2; ++n) acc[a][b][m][n] = (f32x4){0.f, 0.f, 0.f, 0.f};
.LBB0_314:
	s_ashr_i32 s63, s62, 31
	s_lshl_b64 s[8:9], s[62:63], 19
	s_add_u32 s68, s12, s8
	s_addc_u32 s69, s13, s9
	s_and_b64 s[8:9], s[2:3], exec
	s_cselect_b32 s7, s69, s5
	s_cselect_b32 s63, s68, s4
	s_ashr_i32 s61, s60, 31
	s_lshl_b64 s[8:9], s[60:61], 19
	s_add_u32 s70, s87, s8
	s_addc_u32 s71, s88, s9
	s_and_b64 s[8:9], s[2:3], exec
	s_cselect_b32 s61, s71, s75
	s_cselect_b32 s73, s70, s74
	s_add_u32 s4, s4, 0x10000
	s_addc_u32 s5, s5, 0
	s_add_u32 s74, s74, 0x10000
	s_addc_u32 s75, s75, 0
	s_mov_b32 s76, -2
.LBB0_315:
	ds_read_b128 v[140:143], v159
	ds_read_b128 v[144:147], v159 offset:1024
	ds_read_b128 v[148:151], v159 offset:2048
	ds_read_b128 v[166:169], v159 offset:3072
	ds_read_b128 v[170:173], v160
	ds_read_b128 v[174:177], v160 offset:1024
	ds_read_b128 v[178:181], v160 offset:2048
	ds_read_b128 v[182:185], v160 offset:3072
	s_cmp_eq_u32 s76, 12
	s_cselect_b32 s9, s7, s5
	s_cselect_b32 s8, s63, s4
	s_cselect_b32 vcc_hi, s61, s75
	s_cselect_b32 vcc_lo, s73, s74
	s_movk_i32 s78, 0xc000
	v_lshl_add_u64 v[2:3], s[4:5], 0, v[132:133]
	s_mov_b32 s79, -1
	v_lshl_add_u64 v[152:153], v[2:3], 0, s[78:79]
	s_movk_i32 s78, 0xe000
	s_add_i32 m0, s90, 0xc000
	s_mov_b32 s79, -1
	ds_read_b128 v[190:193], v161
	ds_read_b128 v[194:197], v161 offset:1024
	ds_read_b128 v[198:201], v161 offset:2048
	ds_read_b128 v[202:205], v161 offset:3072
	ds_read_b128 v[206:209], v161 offset:4096
	ds_read_b128 v[210:213], v161 offset:5120
	ds_read_b128 v[214:217], v161 offset:6144
	ds_read_b128 v[220:223], v161 offset:7168
	global_load_lds_dwordx4 v[152:153], off
	v_lshl_add_u64 v[2:3], v[2:3], 0, s[78:79]
	s_add_i32 m0, s90, 0xe000
	s_nop 0
	global_load_lds_dwordx4 v[2:3], off
	s_cmp_lg_u32 s76, -2
	s_cbranch_scc1 .Lzskip_2
	v_mov_b32_e32 v4, 0
	v_mov_b32_e32 v5, 0
	v_mov_b32_e32 v6, 0
	v_mov_b32_e32 v7, 0
	v_mov_b32_e32 v8, 0
	v_mov_b32_e32 v9, 0
	v_mov_b32_e32 v10, 0
	v_mov_b32_e32 v11, 0
	v_mov_b32_e32 v12, 0
	v_mov_b32_e32 v13, 0
	v_mov_b32_e32 v14, 0
	v_mov_b32_e32 v15, 0
	v_mov_b32_e32 v16, 0
	v_mov_b32_e32 v17, 0
	v_mov_b32_e32 v18, 0
	v_mov_b32_e32 v19, 0
	v_mov_b32_e32 v20, 0
	v_mov_b32_e32 v21, 0
	v_mov_b32_e32 v22, 0
	v_mov_b32_e32 v23, 0
	v_mov_b32_e32 v24, 0
	v_mov_b32_e32 v25, 0
	v_mov_b32_e32 v26, 0
	v_mov_b32_e32 v27, 0
	v_mov_b32_e32 v28, 0
	v_mov_b32_e32 v29, 0
	v_mov_b32_e32 v30, 0
	v_mov_b32_e32 v31, 0
	v_mov_b32_e32 v32, 0
	v_mov_b32_e32 v33, 0
	v_mov_b32_e32 v34, 0
	v_mov_b32_e32 v35, 0
	v_mov_b32_e32 v36, 0
	v_mov_b32_e32 v37, 0
	v_mov_b32_e32 v38, 0
	v_mov_b32_e32 v39, 0
	v_mov_b32_e32 v40, 0
	v_mov_b32_e32 v41, 0
	v_mov_b32_e32 v42, 0
	v_mov_b32_e32 v43, 0
	v_mov_b32_e32 v44, 0
	v_mov_b32_e32 v45, 0
	v_mov_b32_e32 v46, 0
	v_mov_b32_e32 v47, 0
	v_mov_b32_e32 v48, 0
	v_mov_b32_e32 v49, 0
	v_mov_b32_e32 v50, 0
	v_mov_b32_e32 v51, 0
	v_mov_b32_e32 v52, 0
	v_mov_b32_e32 v53, 0
	v_mov_b32_e32 v54, 0
	v_mov_b32_e32 v55, 0
	v_mov_b32_e32 v56, 0
	v_mov_b32_e32 v57, 0
	v_mov_b32_e32 v58, 0
	v_mov_b32_e32 v59, 0
	v_mov_b32_e32 v60, 0
	v_mov_b32_e32 v61, 0
	v_mov_b32_e32 v62, 0
	v_mov_b32_e32 v63, 0
	v_mov_b32_e32 v64, 0
	v_mov_b32_e32 v65, 0
	v_mov_b32_e32 v66, 0
	v_mov_b32_e32 v67, 0
	v_mov_b32_e32 v68, 0
	v_mov_b32_e32 v69, 0
	v_mov_b32_e32 v70, 0
	v_mov_b32_e32 v71, 0
	v_mov_b32_e32 v72, 0
	v_mov_b32_e32 v73, 0
	v_mov_b32_e32 v74, 0
	v_mov_b32_e32 v75, 0
	v_mov_b32_e32 v76, 0
	v_mov_b32_e32 v77, 0
	v_mov_b32_e32 v78, 0
	v_mov_b32_e32 v79, 0
	v_mov_b32_e32 v80, 0
	v_mov_b32_e32 v81, 0
	v_mov_b32_e32 v82, 0
	v_mov_b32_e32 v83, 0
	v_mov_b32_e32 v84, 0
	v_mov_b32_e32 v85, 0
	v_mov_b32_e32 v86, 0
	v_mov_b32_e32 v87, 0
	v_mov_b32_e32 v88, 0
	v_mov_b32_e32 v89, 0
	v_mov_b32_e32 v90, 0
	v_mov_b32_e32 v91, 0
	v_mov_b32_e32 v92, 0
	v_mov_b32_e32 v93, 0
	v_mov_b32_e32 v94, 0
	v_mov_b32_e32 v95, 0
	v_mov_b32_e32 v96, 0
	v_mov_b32_e32 v97, 0
	v_mov_b32_e32 v98, 0
	v_mov_b32_e32 v99, 0
	v_mov_b32_e32 v100, 0
	v_mov_b32_e32 v101, 0
	v_mov_b32_e32 v102, 0
	v_mov_b32_e32 v103, 0
	v_mov_b32_e32 v104, 0
	v_mov_b32_e32 v105, 0
	v_mov_b32_e32 v106, 0
	v_mov_b32_e32 v107, 0
	v_mov_b32_e32 v108, 0
	v_mov_b32_e32 v109, 0
	v_mov_b32_e32 v110, 0
	v_mov_b32_e32 v111, 0
	v_mov_b32_e32 v112, 0
	v_mov_b32_e32 v113, 0
	v_mov_b32_e32 v114, 0
	v_mov_b32_e32 v115, 0
	v_mov_b32_e32 v116, 0
	v_mov_b32_e32 v117, 0
	v_mov_b32_e32 v118, 0
	v_mov_b32_e32 v119, 0
	v_mov_b32_e32 v120, 0
	v_mov_b32_e32 v121, 0
	v_mov_b32_e32 v122, 0
	v_mov_b32_e32 v123, 0
	v_mov_b32_e32 v124, 0
	v_mov_b32_e32 v125, 0
	v_mov_b32_e32 v126, 0
	v_mov_b32_e32 v127, 0
	v_mov_b32_e32 v128, 0
	v_mov_b32_e32 v129, 0
	v_mov_b32_e32 v130, 0
	v_mov_b32_e32 v131, 0
; #define PG8_STAGE(bufoff, gbase, voff) do { _Pragma("unroll") for (int _i = 0; _i < 2; ++_i) \
;         __builtin_amdgcn_global_load_lds((const unsigned*)((const char*)(gbase) + (voff)[_i]), (PG8_LAS unsigned*)(lds + (bufoff) + ldsw + _i * 8192), 16, 0, 0); } while (0)
; #define PG8_LDA(dst, b, h) do { _Pragma("unroll") for (int m = 0; m < 4; ++m) _Pragma("unroll") for (int k = 0; k < 2; ++k) dst[m][k] = *(const PG8_LAS bf16x8*)(lds + PG8_SA(b, h) + aoff + m * 2048 + k * 1024); } while (0)
; #define PG8_MMA(ai, bj, At, Bt) do { __builtin_amdgcn_s_setprio(1); _Pragma("unroll") for (int m = 0; m < 4; ++m) _Pragma("unroll") for (int n = 0; n < 2; ++n) _Pragma("unroll") for (int k = 0; k < 2; ++k) \
;         acc[ai][bj][m][n] = __builtin_amdgcn_mfma_f32_16x16x32_bf16(Bt[n][k], At[m][k], acc[ai][bj][m][n], 0, 0, 0); __builtin_amdgcn_s_setprio(0); } while (0)
; #define PG8_WAIT_V(n) asm volatile("s_waitcnt vmcnt(" #n ")" ::: "memory")
; #define PG8_WAIT_L(n) asm volatile("s_waitcnt lgkmcnt(" #n ")" ::: "memory")
; #define PG8_BAR __builtin_amdgcn_s_barrier()
; #define PG8_SCHED __builtin_amdgcn_sched_barrier(0)
; template <class Epi, class Sched, bool ALIGN_EPI = false, bool SP2 = false>
; __device__ __forceinline__ void gemm_phase(PG8_LAS unsigned char* lds, const Gemm g, const Sched& S, const Epi& E) {
;     ...
;             PG8_WAIT_V(8); PG8_WAIT_L(0); PG8_BAR; PG8_MMA(0, 0, At, B0); PG8_MMA(0, 1, At, B1); PG8_BAR; PG8_SCHED;
;             PG8_LDA(At, 0, 1); PG8_STAGE(PG8_SB(0, 0), b2, voffB); PG8_STAGE(PG8_SB(0, 1), b2 + hstepB, voffB); PG8_STAGE(PG8_SA(0, 0), a2, voffA);
;             PG8_WAIT_V(8); PG8_WAIT_L(0); PG8_BAR; PG8_MMA(1, 0, At, B0); PG8_MMA(1, 1, At, B1); PG8_BAR; PG8_SCHED;
.Lzskip_2:
	s_waitcnt vmcnt(8)
	s_waitcnt lgkmcnt(0)
	s_barrier
	s_setprio 1
	s_waitcnt lgkmcnt(0)
	v_mfma_f32_16x16x32_bf16 v[128:131], v[140:143], v[190:193], v[128:131]
	v_mfma_f32_16x16x32_bf16 v[124:127], v[148:151], v[190:193], v[124:127]
	v_mfma_f32_16x16x32_bf16 v[112:115], v[140:143], v[198:201], v[112:115]
	v_mfma_f32_16x16x32_bf16 v[108:111], v[148:151], v[198:201], v[108:111]
	v_mfma_f32_16x16x32_bf16 v[96:99], v[140:143], v[206:209], v[96:99]
	v_mfma_f32_16x16x32_bf16 v[92:95], v[148:151], v[206:209], v[92:95]
	v_mfma_f32_16x16x32_bf16 v[80:83], v[140:143], v[214:217], v[80:83]
	v_mfma_f32_16x16x32_bf16 v[76:79], v[148:151], v[214:217], v[76:79]
	v_mfma_f32_16x16x32_bf16 v[128:131], v[144:147], v[194:197], v[128:131]
	v_mfma_f32_16x16x32_bf16 v[124:127], v[166:169], v[194:197], v[124:127]
	v_mfma_f32_16x16x32_bf16 v[112:115], v[144:147], v[202:205], v[112:115]
	v_mfma_f32_16x16x32_bf16 v[108:111], v[166:169], v[202:205], v[108:111]
	v_mfma_f32_16x16x32_bf16 v[96:99], v[144:147], v[210:213], v[96:99]
	v_mfma_f32_16x16x32_bf16 v[92:95], v[166:169], v[210:213], v[92:95]
	v_mfma_f32_16x16x32_bf16 v[80:83], v[144:147], v[220:223], v[80:83]
	v_mfma_f32_16x16x32_bf16 v[76:79], v[166:169], v[220:223], v[76:79]
	s_setprio 0
	s_setprio 1
	v_mfma_f32_16x16x32_bf16 v[120:123], v[170:173], v[190:193], v[120:123]
	v_mfma_f32_16x16x32_bf16 v[116:119], v[178:181], v[190:193], v[116:119]
	v_mfma_f32_16x16x32_bf16 v[104:107], v[170:173], v[198:201], v[104:107]
	v_mfma_f32_16x16x32_bf16 v[100:103], v[178:181], v[198:201], v[100:103]
	v_mfma_f32_16x16x32_bf16 v[88:91], v[170:173], v[206:209], v[88:91]
	v_mfma_f32_16x16x32_bf16 v[84:87], v[178:181], v[206:209], v[84:87]
	v_mfma_f32_16x16x32_bf16 v[72:75], v[170:173], v[214:217], v[72:75]
	v_mfma_f32_16x16x32_bf16 v[68:71], v[178:181], v[214:217], v[68:71]
	v_mfma_f32_16x16x32_bf16 v[120:123], v[174:177], v[194:197], v[120:123]
	v_mfma_f32_16x16x32_bf16 v[116:119], v[182:185], v[194:197], v[116:119]
	v_mfma_f32_16x16x32_bf16 v[104:107], v[174:177], v[202:205], v[104:107]
	v_mfma_f32_16x16x32_bf16 v[100:103], v[182:185], v[202:205], v[100:103]
	v_mfma_f32_16x16x32_bf16 v[88:91], v[174:177], v[210:213], v[88:91]
	v_mfma_f32_16x16x32_bf16 v[84:87], v[182:185], v[210:213], v[84:87]
	v_mfma_f32_16x16x32_bf16 v[72:75], v[174:177], v[220:223], v[72:75]
	v_mfma_f32_16x16x32_bf16 v[68:71], v[182:185], v[220:223], v[68:71]
	s_setprio 0
	s_barrier
	s_add_i32 s77, s15, s89
	v_lshl_add_u64 v[152:153], vcc, 0, v[132:133]
	s_mov_b32 m0, s77
	ds_read_b128 v[190:193], v161 offset:16384
	ds_read_b128 v[194:197], v161 offset:17408
	ds_read_b128 v[198:201], v161 offset:18432
	ds_read_b128 v[202:205], v161 offset:19456
	ds_read_b128 v[206:209], v161 offset:20480
	ds_read_b128 v[210:213], v161 offset:21504
	ds_read_b128 v[214:217], v161 offset:22528
	ds_read_b128 v[220:223], v161 offset:23552
	global_load_lds_dwordx4 v[152:153], off
	v_lshl_add_u64 v[2:3], v[152:153], 0, s[30:31]
	s_add_i32 m0, s77, 0x2000
	s_add_i32 s77, s18, s89
	global_load_lds_dwordx4 v[2:3], off
	v_lshl_add_u64 v[2:3], v[152:153], 0, s[34:35]
	s_mov_b32 m0, s77
	v_lshl_add_u64 v[186:187], s[8:9], 0, v[132:133]
	global_load_lds_dwordx4 v[2:3], off
	v_lshl_add_u64 v[2:3], v[152:153], 0, s[36:37]
	s_add_i32 m0, s77, 0x2000
	s_nop 0
	global_load_lds_dwordx4 v[2:3], off
	s_mov_b32 m0, s90
	v_lshl_add_u64 v[2:3], v[186:187], 0, s[30:31]
	global_load_lds_dwordx4 v[186:187], off
	s_mov_b32 m0, s91
	s_nop 0
	global_load_lds_dwordx4 v[2:3], off
	s_waitcnt vmcnt(8)
	s_waitcnt lgkmcnt(0)
	s_barrier
	s_setprio 1
	s_waitcnt lgkmcnt(0)
	v_mfma_f32_16x16x32_bf16 v[64:67], v[140:143], v[190:193], v[64:67]
	v_mfma_f32_16x16x32_bf16 v[60:63], v[148:151], v[190:193], v[60:63]
	v_mfma_f32_16x16x32_bf16 v[48:51], v[140:143], v[198:201], v[48:51]
	v_mfma_f32_16x16x32_bf16 v[44:47], v[148:151], v[198:201], v[44:47]
	v_mfma_f32_16x16x32_bf16 v[32:35], v[140:143], v[206:209], v[32:35]
	v_mfma_f32_16x16x32_bf16 v[28:31], v[148:151], v[206:209], v[28:31]
	v_mfma_f32_16x16x32_bf16 v[16:19], v[140:143], v[214:217], v[16:19]
	v_mfma_f32_16x16x32_bf16 v[12:15], v[148:151], v[214:217], v[12:15]
	v_mfma_f32_16x16x32_bf16 v[64:67], v[144:147], v[194:197], v[64:67]
	v_mfma_f32_16x16x32_bf16 v[60:63], v[166:169], v[194:197], v[60:63]
	v_mfma_f32_16x16x32_bf16 v[48:51], v[144:147], v[202:205], v[48:51]
	v_mfma_f32_16x16x32_bf16 v[44:47], v[166:169], v[202:205], v[44:47]
	v_mfma_f32_16x16x32_bf16 v[32:35], v[144:147], v[210:213], v[32:35]
	v_mfma_f32_16x16x32_bf16 v[28:31], v[166:169], v[210:213], v[28:31]
	v_mfma_f32_16x16x32_bf16 v[16:19], v[144:147], v[220:223], v[16:19]
	v_mfma_f32_16x16x32_bf16 v[12:15], v[166:169], v[220:223], v[12:15]
	s_setprio 0
	s_setprio 1
	v_mfma_f32_16x16x32_bf16 v[56:59], v[170:173], v[190:193], v[56:59]
	v_mfma_f32_16x16x32_bf16 v[52:55], v[178:181], v[190:193], v[52:55]
	v_mfma_f32_16x16x32_bf16 v[40:43], v[170:173], v[198:201], v[40:43]
	v_mfma_f32_16x16x32_bf16 v[36:39], v[178:181], v[198:201], v[36:39]
	v_mfma_f32_16x16x32_bf16 v[24:27], v[170:173], v[206:209], v[24:27]
	v_mfma_f32_16x16x32_bf16 v[20:23], v[178:181], v[206:209], v[20:23]
	v_mfma_f32_16x16x32_bf16 v[8:11], v[170:173], v[214:217], v[8:11]
	v_mfma_f32_16x16x32_bf16 v[2:5], v[178:181], v[214:217], v[4:7]
	v_mfma_f32_16x16x32_bf16 v[56:59], v[174:177], v[194:197], v[56:59]
	v_mfma_f32_16x16x32_bf16 v[52:55], v[182:185], v[194:197], v[52:55]
	v_mfma_f32_16x16x32_bf16 v[40:43], v[174:177], v[202:205], v[40:43]
	v_mfma_f32_16x16x32_bf16 v[36:39], v[182:185], v[202:205], v[36:39]
	v_mfma_f32_16x16x32_bf16 v[24:27], v[174:177], v[210:213], v[24:27]
	v_mfma_f32_16x16x32_bf16 v[20:23], v[182:185], v[210:213], v[20:23]
	v_mfma_f32_16x16x32_bf16 v[8:11], v[174:177], v[220:223], v[8:11]
	v_mfma_f32_16x16x32_bf16 v[2:5], v[182:185], v[220:223], v[2:5]
	s_setprio 0
	s_barrier
; #define PG8_STAGE(bufoff, gbase, voff) do { _Pragma("unroll") for (int _i = 0; _i < 2; ++_i) \
;         __builtin_amdgcn_global_load_lds((const unsigned*)((const char*)(gbase) + (voff)[_i]), (PG8_LAS unsigned*)(lds + (bufoff) + ldsw + _i * 8192), 16, 0, 0); } while (0)
; #define PG8_LDA(dst, b, h) do { _Pragma("unroll") for (int m = 0; m < 4; ++m) _Pragma("unroll") for (int k = 0; k < 2; ++k) dst[m][k] = *(const PG8_LAS bf16x8*)(lds + PG8_SA(b, h) + aoff + m * 2048 + k * 1024); } while (0)
; #define PG8_LDB(dst, b, h) do { _Pragma("unroll") for (int n = 0; n < 2; ++n) _Pragma("unroll") for (int k = 0; k < 2; ++k) dst[n][k] = *(const PG8_LAS bf16x8*)(lds + PG8_SB(b, h) + boff + n * 2048 + k * 1024); } while (0)
; #define PG8_MMA(ai, bj, At, Bt) do { __builtin_amdgcn_s_setprio(1); _Pragma("unroll") for (int m = 0; m < 4; ++m) _Pragma("unroll") for (int n = 0; n < 2; ++n) _Pragma("unroll") for (int k = 0; k < 2; ++k) \
;         acc[ai][bj][m][n] = __builtin_amdgcn_mfma_f32_16x16x32_bf16(Bt[n][k], At[m][k], acc[ai][bj][m][n], 0, 0, 0); __builtin_amdgcn_s_setprio(0); } while (0)
; #define PG8_WAIT_V(n) asm volatile("s_waitcnt vmcnt(" #n ")" ::: "memory")
; #define PG8_WAIT_L(n) asm volatile("s_waitcnt lgkmcnt(" #n ")" ::: "memory")
; #define PG8_BAR __builtin_amdgcn_s_barrier()
; #define PG8_SCHED __builtin_amdgcn_sched_barrier(0)
; template <class Epi, class Sched, bool ALIGN_EPI = false, bool SP2 = false>
; __device__ __forceinline__ void gemm_phase(PG8_LAS unsigned char* lds, const Gemm g, const Sched& S, const Epi& E) {
;     ...
;             PG8_LDB(B0, 1, 0); PG8_LDB(B1, 1, 1); PG8_SCHED; PG8_LDA(At, 1, 0); PG8_STAGE(PG8_SA(0, 1), a2 + hstepA, voffA);
;             PG8_WAIT_V(8); PG8_WAIT_L(0); PG8_BAR; PG8_MMA(0, 0, At, B0); PG8_MMA(0, 1, At, B1); PG8_BAR; PG8_SCHED;
;             PG8_LDA(At, 1, 1); PG8_STAGE(PG8_SB(1, 0), b3, voffB); PG8_STAGE(PG8_SB(1, 1), b3 + hstepB, voffB); PG8_STAGE(PG8_SA(1, 0), a3, voffA);
;             PG8_WAIT_V(8); PG8_WAIT_L(0); PG8_BAR; PG8_MMA(1, 0, At, B0); PG8_MMA(1, 1, At, B1); PG8_BAR; PG8_SCHED;
	ds_read_b128 v[140:143], v162
	ds_read_b128 v[144:147], v162 offset:1024
	ds_read_b128 v[148:151], v162 offset:2048
	ds_read_b128 v[166:169], v162 offset:3072
	ds_read_b128 v[170:173], v163
	ds_read_b128 v[174:177], v163 offset:1024
	ds_read_b128 v[178:181], v163 offset:2048
	ds_read_b128 v[182:185], v163 offset:3072
	s_mov_b32 m0, s92
	v_lshl_add_u64 v[6:7], v[186:187], 0, s[34:35]
	ds_read_b128 v[190:193], v161 offset:32768
	ds_read_b128 v[194:197], v161 offset:33792
	ds_read_b128 v[198:201], v161 offset:34816
	ds_read_b128 v[202:205], v161 offset:35840
	ds_read_b128 v[206:209], v161 offset:36864
	ds_read_b128 v[210:213], v161 offset:37888
	ds_read_b128 v[214:217], v161 offset:38912
	ds_read_b128 v[220:223], v161 offset:39936
	global_load_lds_dwordx4 v[6:7], off
	v_lshl_add_u64 v[6:7], v[186:187], 0, s[36:37]
	s_mov_b32 m0, s93
	s_nop 0
	global_load_lds_dwordx4 v[6:7], off
	s_waitcnt vmcnt(8)
	s_waitcnt lgkmcnt(0)
	s_barrier
	s_setprio 1
	s_waitcnt lgkmcnt(0)
	v_mfma_f32_16x16x32_bf16 v[128:131], v[140:143], v[190:193], v[128:131]
	v_mfma_f32_16x16x32_bf16 v[124:127], v[148:151], v[190:193], v[124:127]
	v_mfma_f32_16x16x32_bf16 v[112:115], v[140:143], v[198:201], v[112:115]
	v_mfma_f32_16x16x32_bf16 v[108:111], v[148:151], v[198:201], v[108:111]
	v_mfma_f32_16x16x32_bf16 v[96:99], v[140:143], v[206:209], v[96:99]
	v_mfma_f32_16x16x32_bf16 v[92:95], v[148:151], v[206:209], v[92:95]
	v_mfma_f32_16x16x32_bf16 v[80:83], v[140:143], v[214:217], v[80:83]
	v_mfma_f32_16x16x32_bf16 v[76:79], v[148:151], v[214:217], v[76:79]
	v_mfma_f32_16x16x32_bf16 v[128:131], v[144:147], v[194:197], v[128:131]
	v_mfma_f32_16x16x32_bf16 v[124:127], v[166:169], v[194:197], v[124:127]
	v_mfma_f32_16x16x32_bf16 v[112:115], v[144:147], v[202:205], v[112:115]
	v_mfma_f32_16x16x32_bf16 v[108:111], v[166:169], v[202:205], v[108:111]
	v_mfma_f32_16x16x32_bf16 v[96:99], v[144:147], v[210:213], v[96:99]
	v_mfma_f32_16x16x32_bf16 v[92:95], v[166:169], v[210:213], v[92:95]
	v_mfma_f32_16x16x32_bf16 v[80:83], v[144:147], v[220:223], v[80:83]
	v_mfma_f32_16x16x32_bf16 v[76:79], v[166:169], v[220:223], v[76:79]
	s_setprio 0
	s_setprio 1
	v_mfma_f32_16x16x32_bf16 v[120:123], v[170:173], v[190:193], v[120:123]
	v_mfma_f32_16x16x32_bf16 v[116:119], v[178:181], v[190:193], v[116:119]
	v_mfma_f32_16x16x32_bf16 v[104:107], v[170:173], v[198:201], v[104:107]
	v_mfma_f32_16x16x32_bf16 v[100:103], v[178:181], v[198:201], v[100:103]
	v_mfma_f32_16x16x32_bf16 v[88:91], v[170:173], v[206:209], v[88:91]
	v_mfma_f32_16x16x32_bf16 v[84:87], v[178:181], v[206:209], v[84:87]
	v_mfma_f32_16x16x32_bf16 v[72:75], v[170:173], v[214:217], v[72:75]
	v_mfma_f32_16x16x32_bf16 v[68:71], v[178:181], v[214:217], v[68:71]
	v_mfma_f32_16x16x32_bf16 v[120:123], v[174:177], v[194:197], v[120:123]
	v_mfma_f32_16x16x32_bf16 v[116:119], v[182:185], v[194:197], v[116:119]
	v_mfma_f32_16x16x32_bf16 v[104:107], v[174:177], v[202:205], v[104:107]
	v_mfma_f32_16x16x32_bf16 v[100:103], v[182:185], v[202:205], v[100:103]
	v_mfma_f32_16x16x32_bf16 v[88:91], v[174:177], v[210:213], v[88:91]
	v_mfma_f32_16x16x32_bf16 v[84:87], v[182:185], v[210:213], v[84:87]
	v_mfma_f32_16x16x32_bf16 v[72:75], v[174:177], v[220:223], v[72:75]
	v_mfma_f32_16x16x32_bf16 v[68:71], v[182:185], v[220:223], v[68:71]
	s_setprio 0
	s_barrier
	s_add_i32 s8, s19, s89
	v_lshl_add_u64 v[6:7], v[152:153], 0, s[38:39]
	s_mov_b32 m0, s8
	ds_read_b128 v[190:193], v161 offset:49152
	ds_read_b128 v[194:197], v161 offset:50176
	ds_read_b128 v[198:201], v161 offset:51200
	ds_read_b128 v[202:205], v161 offset:52224
	ds_read_b128 v[206:209], v161 offset:53248
	ds_read_b128 v[210:213], v161 offset:54272
	ds_read_b128 v[214:217], v161 offset:55296
	ds_read_b128 v[220:223], v161 offset:56320
	global_load_lds_dwordx4 v[6:7], off
	v_lshl_add_u64 v[6:7], v[152:153], 0, s[40:41]
	s_add_i32 m0, s8, 0x2000
	s_add_i32 s8, s80, s89
	global_load_lds_dwordx4 v[6:7], off
	v_lshl_add_u64 v[6:7], v[152:153], 0, s[52:53]
	s_mov_b32 m0, s8
	s_nop 0
	global_load_lds_dwordx4 v[6:7], off
	v_lshl_add_u64 v[6:7], v[152:153], 0, s[54:55]
	s_add_i32 m0, s8, 0x2000
	s_nop 0
	global_load_lds_dwordx4 v[6:7], off
	v_lshl_add_u64 v[6:7], v[186:187], 0, s[38:39]
	s_mov_b32 m0, s94
	s_nop 0
	global_load_lds_dwordx4 v[6:7], off
	v_lshl_add_u64 v[6:7], v[186:187], 0, s[40:41]
	s_mov_b32 m0, s95
	s_nop 0
	global_load_lds_dwordx4 v[6:7], off
	s_waitcnt vmcnt(8)
	s_waitcnt lgkmcnt(0)
	s_barrier
	s_setprio 1
	s_waitcnt lgkmcnt(0)
	v_mfma_f32_16x16x32_bf16 v[64:67], v[140:143], v[190:193], v[64:67]
	v_mfma_f32_16x16x32_bf16 v[60:63], v[148:151], v[190:193], v[60:63]
	v_mfma_f32_16x16x32_bf16 v[48:51], v[140:143], v[198:201], v[48:51]
	v_mfma_f32_16x16x32_bf16 v[44:47], v[148:151], v[198:201], v[44:47]
	v_mfma_f32_16x16x32_bf16 v[32:35], v[140:143], v[206:209], v[32:35]
	v_mfma_f32_16x16x32_bf16 v[28:31], v[148:151], v[206:209], v[28:31]
	v_mfma_f32_16x16x32_bf16 v[16:19], v[140:143], v[214:217], v[16:19]
	v_mfma_f32_16x16x32_bf16 v[12:15], v[148:151], v[214:217], v[12:15]
	v_mfma_f32_16x16x32_bf16 v[64:67], v[144:147], v[194:197], v[64:67]
	v_mfma_f32_16x16x32_bf16 v[60:63], v[166:169], v[194:197], v[60:63]
	v_mfma_f32_16x16x32_bf16 v[48:51], v[144:147], v[202:205], v[48:51]
	v_mfma_f32_16x16x32_bf16 v[44:47], v[166:169], v[202:205], v[44:47]
	v_mfma_f32_16x16x32_bf16 v[32:35], v[144:147], v[210:213], v[32:35]
	v_mfma_f32_16x16x32_bf16 v[28:31], v[166:169], v[210:213], v[28:31]
	v_mfma_f32_16x16x32_bf16 v[16:19], v[144:147], v[220:223], v[16:19]
	v_mfma_f32_16x16x32_bf16 v[12:15], v[166:169], v[220:223], v[12:15]
	s_setprio 0
	s_setprio 1
	v_mfma_f32_16x16x32_bf16 v[56:59], v[170:173], v[190:193], v[56:59]
	v_mfma_f32_16x16x32_bf16 v[52:55], v[178:181], v[190:193], v[52:55]
	v_mfma_f32_16x16x32_bf16 v[40:43], v[170:173], v[198:201], v[40:43]
	v_mfma_f32_16x16x32_bf16 v[36:39], v[178:181], v[198:201], v[36:39]
	v_mfma_f32_16x16x32_bf16 v[24:27], v[170:173], v[206:209], v[24:27]
	v_mfma_f32_16x16x32_bf16 v[20:23], v[178:181], v[206:209], v[20:23]
	v_mfma_f32_16x16x32_bf16 v[6:9], v[170:173], v[214:217], v[8:11]
	v_mfma_f32_16x16x32_bf16 v[2:5], v[178:181], v[214:217], v[2:5]
	v_mfma_f32_16x16x32_bf16 v[56:59], v[174:177], v[194:197], v[56:59]
	v_mfma_f32_16x16x32_bf16 v[52:55], v[182:185], v[194:197], v[52:55]
	v_mfma_f32_16x16x32_bf16 v[40:43], v[174:177], v[202:205], v[40:43]
	v_mfma_f32_16x16x32_bf16 v[36:39], v[182:185], v[202:205], v[36:39]
	v_mfma_f32_16x16x32_bf16 v[24:27], v[174:177], v[210:213], v[24:27]
	v_mfma_f32_16x16x32_bf16 v[20:23], v[182:185], v[210:213], v[20:23]
	v_mfma_f32_16x16x32_bf16 v[8:11], v[174:177], v[220:223], v[6:9]
	v_mfma_f32_16x16x32_bf16 v[4:7], v[182:185], v[220:223], v[2:5]
	s_setprio 0
	s_barrier
	s_add_i32 s76, s76, 2
	s_add_u32 s4, s4, 0x10000
	s_addc_u32 s5, s5, 0
	s_add_u32 s74, s74, 0x10000
	s_addc_u32 s75, s75, 0
	s_cmp_gt_u32 s76, 13
	s_cbranch_scc0 .LBB0_315
	s_and_b64 vcc, exec, s[58:59]
	s_cbranch_vccz .LBB0_318
	s_barrier

; #define PG8_STAGE(bufoff, gbase, voff) do { _Pragma("unroll") for (int _i = 0; _i < 2; ++_i) \
;         __builtin_amdgcn_global_load_lds((const unsigned*)((const char*)(gbase) + (voff)[_i]), (PG8_LAS unsigned*)(lds + (bufoff) + ldsw + _i * 8192), 16, 0, 0); } while (0)
; #define PG8_LDA(dst, b, h) do { _Pragma("unroll") for (int m = 0; m < 4; ++m) _Pragma("unroll") for (int k = 0; k < 2; ++k) dst[m][k] = *(const PG8_LAS bf16x8*)(lds + PG8_SA(b, h) + aoff + m * 2048 + k * 1024); } while (0)
; #define PG8_LDB(dst, b, h) do { _Pragma("unroll") for (int n = 0; n < 2; ++n) _Pragma("unroll") for (int k = 0; k < 2; ++k) dst[n][k] = *(const PG8_LAS bf16x8*)(lds + PG8_SB(b, h) + boff + n * 2048 + k * 1024); } while (0)
; #define PG8_SCHED __builtin_amdgcn_sched_barrier(0)
; template <class Epi, class Sched, bool ALIGN_EPI = false, bool SP2 = false>
; __device__ __forceinline__ void gemm_phase(PG8_LAS unsigned char* lds, const Gemm g, const Sched& S, const Epi& E) {
;     ...
;         const bool has_next = S.next(ui + 1, nxt);
;         const char* nA = has_next ? (const char*)g.A + (size_t)nxt.pm * tstepA : cA; const char* nB = has_next ? (const char*)g.Bt + (size_t)nxt.pn * tstepB : cB;
;         for (int t = 0; t < nt; t += 2) {
;             const bool last = (t == nt - 2);
;             const char* a1 = cA + (size_t)(t + 1) * kstepA;
;             const char* a2 = last ? nA : cA + (size_t)(t + 2) * kstepA; const char* b2 = last ? nB : cB + (size_t)(t + 2) * kstep;
;             const char* a3 = a2 + kstepA; const char* b3 = b2 + kstep;
;             if (last && has_next) S.a_ready(nxt);
;             if constexpr (SP2) {
;             PG8_LDB(B0, 0, 0); PG8_LDB(B1, 0, 1); PG8_SCHED; PG8_LDA(At, 0, 0); PG8_STAGE(PG8_SA(1, 1), a1 + hstepA, voffA);
;     ...
; #pragma unroll
;         for (int a = 0; a < 2; ++a)
; #pragma unroll
;             for (int b = 0; b < 2; ++b)
; #pragma unroll
;                 for (int m = 0; m < 4; ++m)
; #pragma unroll
;                     for (int n = 0; n < 2; ++n) acc[a][b][m][n] = (f32x4){0.f, 0.f, 0.f, 0.f};
.LBB0_645:
	s_ashr_i32 s61, s60, 31
	s_lshl_b64 s[8:9], s[60:61], 19
	s_add_u32 s64, s85, s8
	s_addc_u32 s65, s86, s9
	s_and_b64 s[0:1], s[0:1], exec
	s_cselect_b32 s61, s65, s67
	s_cselect_b32 s90, s64, s66
	s_add_u32 s91, s66, 0x10000
	s_addc_u32 s92, s67, 0
	s_add_u32 s0, s68, 0xf0080
	s_addc_u32 s1, s69, 0
	s_mov_b32 s68, -2
.LBB0_646:
	ds_read_b128 v[128:131], v197
	ds_read_b128 v[132:135], v197 offset:1024
	ds_read_b128 v[136:139], v197 offset:2048
	ds_read_b128 v[140:143], v197 offset:3072
	ds_read_b128 v[144:147], v198
	ds_read_b128 v[148:151], v198 offset:1024
	ds_read_b128 v[152:155], v198 offset:2048
	ds_read_b128 v[156:159], v198 offset:3072
	s_add_u32 s8, s0, 0xfff10080
	s_addc_u32 s9, s1, -1
	s_cmp_eq_u32 s68, 12
	s_cselect_b32 s67, s63, s9
	s_cselect_b32 s66, s62, s8
	s_cselect_b32 s9, s61, s92
	s_cselect_b32 s8, s90, s91
	v_lshl_add_u64 v[236:237], s[0:1], 0, v[174:175]
	s_add_i32 m0, s17, 0xc000
	ds_read_b128 v[202:205], v199
	ds_read_b128 v[206:209], v199 offset:1024
	ds_read_b128 v[210:213], v199 offset:2048
	ds_read_b128 v[214:217], v199 offset:3072
	ds_read_b128 v[220:223], v199 offset:4096
	ds_read_b128 v[224:227], v199 offset:5120
	ds_read_b128 v[228:231], v199 offset:6144
	ds_read_b128 v[232:235], v199 offset:7168
	global_load_lds_dwordx4 v[236:237], off
	v_lshl_add_u64 v[236:237], s[0:1], 0, v[176:177]
	s_add_i32 m0, s17, 0xe000
	s_nop 0
	global_load_lds_dwordx4 v[236:237], off
	s_cmp_lg_u32 s68, -2
	s_cbranch_scc1 .Lzskip_3
	v_mov_b32_e32 v0, 0
	v_mov_b32_e32 v1, 0
	v_mov_b32_e32 v2, 0
	v_mov_b32_e32 v3, 0
	v_mov_b32_e32 v4, 0
	v_mov_b32_e32 v5, 0
	v_mov_b32_e32 v6, 0
	v_mov_b32_e32 v7, 0
	v_mov_b32_e32 v8, 0
	v_mov_b32_e32 v9, 0
	v_mov_b32_e32 v10, 0
	v_mov_b32_e32 v11, 0
	v_mov_b32_e32 v12, 0
	v_mov_b32_e32 v13, 0
	v_mov_b32_e32 v14, 0
	v_mov_b32_e32 v15, 0
	v_mov_b32_e32 v16, 0
	v_mov_b32_e32 v17, 0
	v_mov_b32_e32 v18, 0
	v_mov_b32_e32 v19, 0
	v_mov_b32_e32 v20, 0
	v_mov_b32_e32 v21, 0
	v_mov_b32_e32 v22, 0
	v_mov_b32_e32 v23, 0
	v_mov_b32_e32 v24, 0
	v_mov_b32_e32 v25, 0
	v_mov_b32_e32 v26, 0
	v_mov_b32_e32 v27, 0
	v_mov_b32_e32 v28, 0
	v_mov_b32_e32 v29, 0
	v_mov_b32_e32 v30, 0
	v_mov_b32_e32 v31, 0
	v_mov_b32_e32 v32, 0
	v_mov_b32_e32 v33, 0
	v_mov_b32_e32 v34, 0
	v_mov_b32_e32 v35, 0
	v_mov_b32_e32 v36, 0
	v_mov_b32_e32 v37, 0
	v_mov_b32_e32 v38, 0
	v_mov_b32_e32 v39, 0
	v_mov_b32_e32 v40, 0
	v_mov_b32_e32 v41, 0
	v_mov_b32_e32 v42, 0
	v_mov_b32_e32 v43, 0
	v_mov_b32_e32 v44, 0
	v_mov_b32_e32 v45, 0
	v_mov_b32_e32 v46, 0
	v_mov_b32_e32 v47, 0
	v_mov_b32_e32 v48, 0
	v_mov_b32_e32 v49, 0
	v_mov_b32_e32 v50, 0
	v_mov_b32_e32 v51, 0
	v_mov_b32_e32 v52, 0
	v_mov_b32_e32 v53, 0
	v_mov_b32_e32 v54, 0
	v_mov_b32_e32 v55, 0
	v_mov_b32_e32 v56, 0
	v_mov_b32_e32 v57, 0
	v_mov_b32_e32 v58, 0
	v_mov_b32_e32 v59, 0
	v_mov_b32_e32 v60, 0
	v_mov_b32_e32 v61, 0
	v_mov_b32_e32 v62, 0
	v_mov_b32_e32 v63, 0
	v_mov_b32_e32 v64, 0
	v_mov_b32_e32 v65, 0
	v_mov_b32_e32 v66, 0
	v_mov_b32_e32 v67, 0
	v_mov_b32_e32 v68, 0
	v_mov_b32_e32 v69, 0
	v_mov_b32_e32 v70, 0
	v_mov_b32_e32 v71, 0
	v_mov_b32_e32 v72, 0
	v_mov_b32_e32 v73, 0
	v_mov_b32_e32 v74, 0
	v_mov_b32_e32 v75, 0
	v_mov_b32_e32 v76, 0
	v_mov_b32_e32 v77, 0
	v_mov_b32_e32 v78, 0
	v_mov_b32_e32 v79, 0
	v_mov_b32_e32 v80, 0
	v_mov_b32_e32 v81, 0
	v_mov_b32_e32 v82, 0
	v_mov_b32_e32 v83, 0
	v_mov_b32_e32 v84, 0
	v_mov_b32_e32 v85, 0
	v_mov_b32_e32 v86, 0
	v_mov_b32_e32 v87, 0
	v_mov_b32_e32 v88, 0
	v_mov_b32_e32 v89, 0
	v_mov_b32_e32 v90, 0
	v_mov_b32_e32 v91, 0
	v_mov_b32_e32 v92, 0
	v_mov_b32_e32 v93, 0
	v_mov_b32_e32 v94, 0
	v_mov_b32_e32 v95, 0
	v_mov_b32_e32 v96, 0
	v_mov_b32_e32 v97, 0
	v_mov_b32_e32 v98, 0
	v_mov_b32_e32 v99, 0
	v_mov_b32_e32 v100, 0
	v_mov_b32_e32 v101, 0
	v_mov_b32_e32 v102, 0
	v_mov_b32_e32 v103, 0
	v_mov_b32_e32 v104, 0
	v_mov_b32_e32 v105, 0
	v_mov_b32_e32 v106, 0
	v_mov_b32_e32 v107, 0
	v_mov_b32_e32 v108, 0
	v_mov_b32_e32 v109, 0
	v_mov_b32_e32 v110, 0
	v_mov_b32_e32 v111, 0
	v_mov_b32_e32 v112, 0
	v_mov_b32_e32 v113, 0
	v_mov_b32_e32 v114, 0
	v_mov_b32_e32 v115, 0
	v_mov_b32_e32 v116, 0
	v_mov_b32_e32 v117, 0
	v_mov_b32_e32 v118, 0
	v_mov_b32_e32 v119, 0
	v_mov_b32_e32 v120, 0
	v_mov_b32_e32 v121, 0
	v_mov_b32_e32 v122, 0
	v_mov_b32_e32 v123, 0
	v_mov_b32_e32 v124, 0
	v_mov_b32_e32 v125, 0
	v_mov_b32_e32 v126, 0
	v_mov_b32_e32 v127, 0
; #define PG8_STAGE(bufoff, gbase, voff) do { _Pragma("unroll") for (int _i = 0; _i < 2; ++_i) \
;         __builtin_amdgcn_global_load_lds((const unsigned*)((const char*)(gbase) + (voff)[_i]), (PG8_LAS unsigned*)(lds + (bufoff) + ldsw + _i * 8192), 16, 0, 0); } while (0)
; #define PG8_LDA(dst, b, h) do { _Pragma("unroll") for (int m = 0; m < 4; ++m) _Pragma("unroll") for (int k = 0; k < 2; ++k) dst[m][k] = *(const PG8_LAS bf16x8*)(lds + PG8_SA(b, h) + aoff + m * 2048 + k * 1024); } while (0)
; #define PG8_MMA(ai, bj, At, Bt) do { __builtin_amdgcn_s_setprio(1); _Pragma("unroll") for (int m = 0; m < 4; ++m) _Pragma("unroll") for (int n = 0; n < 2; ++n) _Pragma("unroll") for (int k = 0; k < 2; ++k) \
;         acc[ai][bj][m][n] = __builtin_amdgcn_mfma_f32_16x16x32_bf16(Bt[n][k], At[m][k], acc[ai][bj][m][n], 0, 0, 0); __builtin_amdgcn_s_setprio(0); } while (0)
; #define PG8_WAIT_V(n) asm volatile("s_waitcnt vmcnt(" #n ")" ::: "memory")
; #define PG8_WAIT_L(n) asm volatile("s_waitcnt lgkmcnt(" #n ")" ::: "memory")
; #define PG8_BAR __builtin_amdgcn_s_barrier()
; #define PG8_SCHED __builtin_amdgcn_sched_barrier(0)
; template <class Epi, class Sched, bool ALIGN_EPI = false, bool SP2 = false>
; __device__ __forceinline__ void gemm_phase(PG8_LAS unsigned char* lds, const Gemm g, const Sched& S, const Epi& E) {
;     ...
;             PG8_WAIT_V(8); PG8_WAIT_L(0); PG8_BAR; PG8_MMA(0, 0, At, B0); PG8_MMA(0, 1, At, B1); PG8_BAR; PG8_SCHED;
;             PG8_LDA(At, 0, 1); PG8_STAGE(PG8_SB(0, 0), b2, voffB); PG8_STAGE(PG8_SB(0, 1), b2 + hstepB, voffB); PG8_STAGE(PG8_SA(0, 0), a2, voffA);
;             PG8_WAIT_V(8); PG8_WAIT_L(0); PG8_BAR; PG8_MMA(1, 0, At, B0); PG8_MMA(1, 1, At, B1); PG8_BAR; PG8_SCHED;
.Lzskip_3:
	s_waitcnt vmcnt(8)
	s_waitcnt lgkmcnt(0)
	s_barrier
	s_setprio 1
	s_waitcnt lgkmcnt(0)
	v_mfma_f32_16x16x32_bf16 v[124:127], v[128:131], v[202:205], v[124:127]
	v_mfma_f32_16x16x32_bf16 v[120:123], v[136:139], v[202:205], v[120:123]
	v_mfma_f32_16x16x32_bf16 v[108:111], v[128:131], v[210:213], v[108:111]
	v_mfma_f32_16x16x32_bf16 v[104:107], v[136:139], v[210:213], v[104:107]
	v_mfma_f32_16x16x32_bf16 v[96:99], v[128:131], v[220:223], v[96:99]
	v_mfma_f32_16x16x32_bf16 v[88:91], v[136:139], v[220:223], v[88:91]
	v_mfma_f32_16x16x32_bf16 v[80:83], v[128:131], v[228:231], v[80:83]
	v_mfma_f32_16x16x32_bf16 v[72:75], v[136:139], v[228:231], v[72:75]
	v_mfma_f32_16x16x32_bf16 v[124:127], v[132:135], v[206:209], v[124:127]
	v_mfma_f32_16x16x32_bf16 v[120:123], v[140:143], v[206:209], v[120:123]
	v_mfma_f32_16x16x32_bf16 v[108:111], v[132:135], v[214:217], v[108:111]
	v_mfma_f32_16x16x32_bf16 v[104:107], v[140:143], v[214:217], v[104:107]
	v_mfma_f32_16x16x32_bf16 v[96:99], v[132:135], v[224:227], v[96:99]
	v_mfma_f32_16x16x32_bf16 v[88:91], v[140:143], v[224:227], v[88:91]
	v_mfma_f32_16x16x32_bf16 v[80:83], v[132:135], v[232:235], v[80:83]
	v_mfma_f32_16x16x32_bf16 v[72:75], v[140:143], v[232:235], v[72:75]
	s_setprio 0
	s_setprio 1
	v_mfma_f32_16x16x32_bf16 v[116:119], v[144:147], v[202:205], v[116:119]
	v_mfma_f32_16x16x32_bf16 v[112:115], v[152:155], v[202:205], v[112:115]
	v_mfma_f32_16x16x32_bf16 v[100:103], v[144:147], v[210:213], v[100:103]
	v_mfma_f32_16x16x32_bf16 v[92:95], v[152:155], v[210:213], v[92:95]
	v_mfma_f32_16x16x32_bf16 v[84:87], v[144:147], v[220:223], v[84:87]
	v_mfma_f32_16x16x32_bf16 v[76:79], v[152:155], v[220:223], v[76:79]
	v_mfma_f32_16x16x32_bf16 v[68:71], v[144:147], v[228:231], v[68:71]
	v_mfma_f32_16x16x32_bf16 v[64:67], v[152:155], v[228:231], v[64:67]
	v_mfma_f32_16x16x32_bf16 v[116:119], v[148:151], v[206:209], v[116:119]
	v_mfma_f32_16x16x32_bf16 v[112:115], v[156:159], v[206:209], v[112:115]
	v_mfma_f32_16x16x32_bf16 v[100:103], v[148:151], v[214:217], v[100:103]
	v_mfma_f32_16x16x32_bf16 v[92:95], v[156:159], v[214:217], v[92:95]
	v_mfma_f32_16x16x32_bf16 v[84:87], v[148:151], v[224:227], v[84:87]
	v_mfma_f32_16x16x32_bf16 v[76:79], v[156:159], v[224:227], v[76:79]
	v_mfma_f32_16x16x32_bf16 v[68:71], v[148:151], v[232:235], v[68:71]
	v_mfma_f32_16x16x32_bf16 v[64:67], v[156:159], v[232:235], v[64:67]
	s_setprio 0
	s_barrier
	v_lshl_add_u64 v[236:237], s[8:9], 0, v[190:191]
	s_add_i32 s8, s77, s15
	s_mov_b32 m0, s8
	ds_read_b128 v[202:205], v199 offset:16384
	ds_read_b128 v[206:209], v199 offset:17408
	ds_read_b128 v[210:213], v199 offset:18432
	ds_read_b128 v[214:217], v199 offset:19456
	ds_read_b128 v[220:223], v199 offset:20480
	ds_read_b128 v[224:227], v199 offset:21504
	ds_read_b128 v[228:231], v199 offset:22528
	ds_read_b128 v[232:235], v199 offset:23552
	global_load_lds_dwordx4 v[236:237], off
	v_lshl_add_u64 v[238:239], v[236:237], 0, s[36:37]
	s_add_i32 m0, s8, 0x2000
	s_add_i32 s8, s80, s15
	global_load_lds_dwordx4 v[238:239], off
	v_lshl_add_u64 v[238:239], v[236:237], 0, s[38:39]
	s_mov_b32 m0, s8
	v_lshl_add_u64 v[240:241], s[66:67], 0, v[162:163]
	global_load_lds_dwordx4 v[238:239], off
	v_lshl_add_u64 v[238:239], v[236:237], 0, s[40:41]
	s_add_i32 m0, s8, 0x2000
	s_nop 0
	global_load_lds_dwordx4 v[238:239], off
	v_lshl_add_u64 v[238:239], s[66:67], 0, v[160:161]
	s_mov_b32 m0, s17
	s_nop 0
	global_load_lds_dwordx4 v[238:239], off
	s_mov_b32 m0, s18
	s_nop 0
	global_load_lds_dwordx4 v[240:241], off
	s_waitcnt vmcnt(8)
	s_waitcnt lgkmcnt(0)
	s_barrier
	s_setprio 1
	s_waitcnt lgkmcnt(0)
	v_mfma_f32_16x16x32_bf16 v[60:63], v[128:131], v[202:205], v[60:63]
	v_mfma_f32_16x16x32_bf16 v[56:59], v[136:139], v[202:205], v[56:59]
	v_mfma_f32_16x16x32_bf16 v[48:51], v[128:131], v[210:213], v[48:51]
	v_mfma_f32_16x16x32_bf16 v[40:43], v[136:139], v[210:213], v[40:43]
	v_mfma_f32_16x16x32_bf16 v[32:35], v[128:131], v[220:223], v[32:35]
	v_mfma_f32_16x16x32_bf16 v[24:27], v[136:139], v[220:223], v[24:27]
	v_mfma_f32_16x16x32_bf16 v[16:19], v[128:131], v[228:231], v[16:19]
	v_mfma_f32_16x16x32_bf16 v[8:11], v[136:139], v[228:231], v[8:11]
	v_mfma_f32_16x16x32_bf16 v[60:63], v[132:135], v[206:209], v[60:63]
	v_mfma_f32_16x16x32_bf16 v[56:59], v[140:143], v[206:209], v[56:59]
	v_mfma_f32_16x16x32_bf16 v[48:51], v[132:135], v[214:217], v[48:51]
	v_mfma_f32_16x16x32_bf16 v[40:43], v[140:143], v[214:217], v[40:43]
	v_mfma_f32_16x16x32_bf16 v[32:35], v[132:135], v[224:227], v[32:35]
	v_mfma_f32_16x16x32_bf16 v[24:27], v[140:143], v[224:227], v[24:27]
	v_mfma_f32_16x16x32_bf16 v[16:19], v[132:135], v[232:235], v[16:19]
	v_mfma_f32_16x16x32_bf16 v[8:11], v[140:143], v[232:235], v[8:11]
	s_setprio 0
	s_setprio 1
	v_mfma_f32_16x16x32_bf16 v[52:55], v[144:147], v[202:205], v[52:55]
	v_mfma_f32_16x16x32_bf16 v[44:47], v[152:155], v[202:205], v[44:47]
	v_mfma_f32_16x16x32_bf16 v[36:39], v[144:147], v[210:213], v[36:39]
	v_mfma_f32_16x16x32_bf16 v[28:31], v[152:155], v[210:213], v[28:31]
	v_mfma_f32_16x16x32_bf16 v[20:23], v[144:147], v[220:223], v[20:23]
	v_mfma_f32_16x16x32_bf16 v[12:15], v[152:155], v[220:223], v[12:15]
	v_mfma_f32_16x16x32_bf16 v[4:7], v[144:147], v[228:231], v[4:7]
	v_mfma_f32_16x16x32_bf16 v[0:3], v[152:155], v[228:231], v[0:3]
	v_mfma_f32_16x16x32_bf16 v[52:55], v[148:151], v[206:209], v[52:55]
	v_mfma_f32_16x16x32_bf16 v[44:47], v[156:159], v[206:209], v[44:47]
	v_mfma_f32_16x16x32_bf16 v[36:39], v[148:151], v[214:217], v[36:39]
	v_mfma_f32_16x16x32_bf16 v[28:31], v[156:159], v[214:217], v[28:31]
	v_mfma_f32_16x16x32_bf16 v[20:23], v[148:151], v[224:227], v[20:23]
	v_mfma_f32_16x16x32_bf16 v[12:15], v[156:159], v[224:227], v[12:15]
	v_mfma_f32_16x16x32_bf16 v[4:7], v[148:151], v[232:235], v[4:7]
	v_mfma_f32_16x16x32_bf16 v[0:3], v[156:159], v[232:235], v[0:3]
	s_setprio 0
	s_barrier
; #define PG8_STAGE(bufoff, gbase, voff) do { _Pragma("unroll") for (int _i = 0; _i < 2; ++_i) \
;         __builtin_amdgcn_global_load_lds((const unsigned*)((const char*)(gbase) + (voff)[_i]), (PG8_LAS unsigned*)(lds + (bufoff) + ldsw + _i * 8192), 16, 0, 0); } while (0)
; #define PG8_LDA(dst, b, h) do { _Pragma("unroll") for (int m = 0; m < 4; ++m) _Pragma("unroll") for (int k = 0; k < 2; ++k) dst[m][k] = *(const PG8_LAS bf16x8*)(lds + PG8_SA(b, h) + aoff + m * 2048 + k * 1024); } while (0)
; #define PG8_LDB(dst, b, h) do { _Pragma("unroll") for (int n = 0; n < 2; ++n) _Pragma("unroll") for (int k = 0; k < 2; ++k) dst[n][k] = *(const PG8_LAS bf16x8*)(lds + PG8_SB(b, h) + boff + n * 2048 + k * 1024); } while (0)
; #define PG8_MMA(ai, bj, At, Bt) do { __builtin_amdgcn_s_setprio(1); _Pragma("unroll") for (int m = 0; m < 4; ++m) _Pragma("unroll") for (int n = 0; n < 2; ++n) _Pragma("unroll") for (int k = 0; k < 2; ++k) \
;         acc[ai][bj][m][n] = __builtin_amdgcn_mfma_f32_16x16x32_bf16(Bt[n][k], At[m][k], acc[ai][bj][m][n], 0, 0, 0); __builtin_amdgcn_s_setprio(0); } while (0)
; #define PG8_WAIT_V(n) asm volatile("s_waitcnt vmcnt(" #n ")" ::: "memory")
; #define PG8_WAIT_L(n) asm volatile("s_waitcnt lgkmcnt(" #n ")" ::: "memory")
; #define PG8_BAR __builtin_amdgcn_s_barrier()
; #define PG8_SCHED __builtin_amdgcn_sched_barrier(0)
; template <class Epi, class Sched, bool ALIGN_EPI = false, bool SP2 = false>
; __device__ __forceinline__ void gemm_phase(PG8_LAS unsigned char* lds, const Gemm g, const Sched& S, const Epi& E) {
;     ...
;             PG8_LDB(B0, 1, 0); PG8_LDB(B1, 1, 1); PG8_SCHED; PG8_LDA(At, 1, 0); PG8_STAGE(PG8_SA(0, 1), a2 + hstepA, voffA);
;             PG8_WAIT_V(8); PG8_WAIT_L(0); PG8_BAR; PG8_MMA(0, 0, At, B0); PG8_MMA(0, 1, At, B1); PG8_BAR; PG8_SCHED;
;             PG8_LDA(At, 1, 1); PG8_STAGE(PG8_SB(1, 0), b3, voffB); PG8_STAGE(PG8_SB(1, 1), b3 + hstepB, voffB); PG8_STAGE(PG8_SA(1, 0), a3, voffA);
;             PG8_WAIT_V(8); PG8_WAIT_L(0); PG8_BAR; PG8_MMA(1, 0, At, B0); PG8_MMA(1, 1, At, B1); PG8_BAR; PG8_SCHED;
	ds_read_b128 v[128:131], v200
	ds_read_b128 v[132:135], v200 offset:1024
	ds_read_b128 v[136:139], v200 offset:2048
	ds_read_b128 v[140:143], v200 offset:3072
	ds_read_b128 v[144:147], v201
	ds_read_b128 v[148:151], v201 offset:1024
	ds_read_b128 v[152:155], v201 offset:2048
	ds_read_b128 v[156:159], v201 offset:3072
	s_add_u32 s8, s66, 0xf0000
	s_addc_u32 s9, s67, 0
	s_mov_b32 m0, s19
	v_lshl_add_u64 v[242:243], s[8:9], 0, v[160:161]
	ds_read_b128 v[202:205], v199 offset:32768
	ds_read_b128 v[206:209], v199 offset:33792
	ds_read_b128 v[210:213], v199 offset:34816
	ds_read_b128 v[214:217], v199 offset:35840
	ds_read_b128 v[220:223], v199 offset:36864
	ds_read_b128 v[224:227], v199 offset:37888
	ds_read_b128 v[228:231], v199 offset:38912
	ds_read_b128 v[232:235], v199 offset:39936
	global_load_lds_dwordx4 v[242:243], off
	v_lshl_add_u64 v[242:243], s[8:9], 0, v[162:163]
	s_mov_b32 m0, s59
	s_nop 0
	global_load_lds_dwordx4 v[242:243], off
	s_waitcnt vmcnt(8)
	s_waitcnt lgkmcnt(0)
	s_barrier
	s_setprio 1
	s_waitcnt lgkmcnt(0)
	v_mfma_f32_16x16x32_bf16 v[124:127], v[128:131], v[202:205], v[124:127]
	v_mfma_f32_16x16x32_bf16 v[120:123], v[136:139], v[202:205], v[120:123]
	v_mfma_f32_16x16x32_bf16 v[108:111], v[128:131], v[210:213], v[108:111]
	v_mfma_f32_16x16x32_bf16 v[104:107], v[136:139], v[210:213], v[104:107]
	v_mfma_f32_16x16x32_bf16 v[96:99], v[128:131], v[220:223], v[96:99]
	v_mfma_f32_16x16x32_bf16 v[88:91], v[136:139], v[220:223], v[88:91]
	v_mfma_f32_16x16x32_bf16 v[80:83], v[128:131], v[228:231], v[80:83]
	v_mfma_f32_16x16x32_bf16 v[72:75], v[136:139], v[228:231], v[72:75]
	v_mfma_f32_16x16x32_bf16 v[124:127], v[132:135], v[206:209], v[124:127]
	v_mfma_f32_16x16x32_bf16 v[120:123], v[140:143], v[206:209], v[120:123]
	v_mfma_f32_16x16x32_bf16 v[108:111], v[132:135], v[214:217], v[108:111]
	v_mfma_f32_16x16x32_bf16 v[104:107], v[140:143], v[214:217], v[104:107]
	v_mfma_f32_16x16x32_bf16 v[96:99], v[132:135], v[224:227], v[96:99]
	v_mfma_f32_16x16x32_bf16 v[88:91], v[140:143], v[224:227], v[88:91]
	v_mfma_f32_16x16x32_bf16 v[80:83], v[132:135], v[232:235], v[80:83]
	v_mfma_f32_16x16x32_bf16 v[72:75], v[140:143], v[232:235], v[72:75]
	s_setprio 0
	s_setprio 1
	v_mfma_f32_16x16x32_bf16 v[116:119], v[144:147], v[202:205], v[116:119]
	v_mfma_f32_16x16x32_bf16 v[112:115], v[152:155], v[202:205], v[112:115]
	v_mfma_f32_16x16x32_bf16 v[100:103], v[144:147], v[210:213], v[100:103]
	v_mfma_f32_16x16x32_bf16 v[92:95], v[152:155], v[210:213], v[92:95]
	v_mfma_f32_16x16x32_bf16 v[84:87], v[144:147], v[220:223], v[84:87]
	v_mfma_f32_16x16x32_bf16 v[76:79], v[152:155], v[220:223], v[76:79]
	v_mfma_f32_16x16x32_bf16 v[68:71], v[144:147], v[228:231], v[68:71]
	v_mfma_f32_16x16x32_bf16 v[64:67], v[152:155], v[228:231], v[64:67]
	v_mfma_f32_16x16x32_bf16 v[116:119], v[148:151], v[206:209], v[116:119]
	v_mfma_f32_16x16x32_bf16 v[112:115], v[156:159], v[206:209], v[112:115]
	v_mfma_f32_16x16x32_bf16 v[100:103], v[148:151], v[214:217], v[100:103]
	v_mfma_f32_16x16x32_bf16 v[92:95], v[156:159], v[214:217], v[92:95]
	v_mfma_f32_16x16x32_bf16 v[84:87], v[148:151], v[224:227], v[84:87]
	v_mfma_f32_16x16x32_bf16 v[76:79], v[156:159], v[224:227], v[76:79]
	v_mfma_f32_16x16x32_bf16 v[68:71], v[148:151], v[232:235], v[68:71]
	v_mfma_f32_16x16x32_bf16 v[64:67], v[156:159], v[232:235], v[64:67]
	s_setprio 0
	s_barrier
	s_add_i32 s8, s81, s15
	v_lshl_add_u64 v[242:243], v[236:237], 0, s[42:43]
	s_mov_b32 m0, s8
	ds_read_b128 v[202:205], v199 offset:49152
	ds_read_b128 v[206:209], v199 offset:50176
	ds_read_b128 v[210:213], v199 offset:51200
	ds_read_b128 v[214:217], v199 offset:52224
	ds_read_b128 v[220:223], v199 offset:53248
	ds_read_b128 v[224:227], v199 offset:54272
	ds_read_b128 v[228:231], v199 offset:55296
	ds_read_b128 v[232:235], v199 offset:56320
	global_load_lds_dwordx4 v[242:243], off
	v_lshl_add_u64 v[242:243], v[236:237], 0, s[44:45]
	s_add_i32 m0, s8, 0x2000
	s_add_i32 s8, s82, s15
	global_load_lds_dwordx4 v[242:243], off
	v_lshl_add_u64 v[242:243], v[236:237], 0, s[48:49]
	s_mov_b32 m0, s8
	v_lshl_add_u64 v[236:237], v[236:237], 0, s[52:53]
	global_load_lds_dwordx4 v[242:243], off
	s_add_i32 m0, s8, 0x2000
	s_nop 0
	global_load_lds_dwordx4 v[236:237], off
	v_lshl_add_u64 v[236:237], v[238:239], 0, s[46:47]
	s_mov_b32 m0, s70
	s_nop 0
	global_load_lds_dwordx4 v[236:237], off
	v_lshl_add_u64 v[236:237], v[240:241], 0, s[46:47]
	s_mov_b32 m0, s71
	s_nop 0
	global_load_lds_dwordx4 v[236:237], off
	s_waitcnt vmcnt(8)
	s_waitcnt lgkmcnt(0)
	s_barrier
	s_setprio 1
	s_waitcnt lgkmcnt(0)
	v_mfma_f32_16x16x32_bf16 v[60:63], v[128:131], v[202:205], v[60:63]
	v_mfma_f32_16x16x32_bf16 v[56:59], v[136:139], v[202:205], v[56:59]
	v_mfma_f32_16x16x32_bf16 v[48:51], v[128:131], v[210:213], v[48:51]
	v_mfma_f32_16x16x32_bf16 v[40:43], v[136:139], v[210:213], v[40:43]
	v_mfma_f32_16x16x32_bf16 v[32:35], v[128:131], v[220:223], v[32:35]
	v_mfma_f32_16x16x32_bf16 v[24:27], v[136:139], v[220:223], v[24:27]
	v_mfma_f32_16x16x32_bf16 v[16:19], v[128:131], v[228:231], v[16:19]
	v_mfma_f32_16x16x32_bf16 v[8:11], v[136:139], v[228:231], v[8:11]
	v_mfma_f32_16x16x32_bf16 v[60:63], v[132:135], v[206:209], v[60:63]
	v_mfma_f32_16x16x32_bf16 v[56:59], v[140:143], v[206:209], v[56:59]
	v_mfma_f32_16x16x32_bf16 v[48:51], v[132:135], v[214:217], v[48:51]
	v_mfma_f32_16x16x32_bf16 v[40:43], v[140:143], v[214:217], v[40:43]
	v_mfma_f32_16x16x32_bf16 v[32:35], v[132:135], v[224:227], v[32:35]
	v_mfma_f32_16x16x32_bf16 v[24:27], v[140:143], v[224:227], v[24:27]
	v_mfma_f32_16x16x32_bf16 v[16:19], v[132:135], v[232:235], v[16:19]
	v_mfma_f32_16x16x32_bf16 v[8:11], v[140:143], v[232:235], v[8:11]
	s_setprio 0
	s_setprio 1
	v_mfma_f32_16x16x32_bf16 v[52:55], v[144:147], v[202:205], v[52:55]
	v_mfma_f32_16x16x32_bf16 v[44:47], v[152:155], v[202:205], v[44:47]
	v_mfma_f32_16x16x32_bf16 v[36:39], v[144:147], v[210:213], v[36:39]
	v_mfma_f32_16x16x32_bf16 v[28:31], v[152:155], v[210:213], v[28:31]
	v_mfma_f32_16x16x32_bf16 v[20:23], v[144:147], v[220:223], v[20:23]
	v_mfma_f32_16x16x32_bf16 v[12:15], v[152:155], v[220:223], v[12:15]
	v_mfma_f32_16x16x32_bf16 v[4:7], v[144:147], v[228:231], v[4:7]
	v_mfma_f32_16x16x32_bf16 v[0:3], v[152:155], v[228:231], v[0:3]
	v_mfma_f32_16x16x32_bf16 v[52:55], v[148:151], v[206:209], v[52:55]
	v_mfma_f32_16x16x32_bf16 v[44:47], v[156:159], v[206:209], v[44:47]
	v_mfma_f32_16x16x32_bf16 v[36:39], v[148:151], v[214:217], v[36:39]
	v_mfma_f32_16x16x32_bf16 v[28:31], v[156:159], v[214:217], v[28:31]
	v_mfma_f32_16x16x32_bf16 v[20:23], v[148:151], v[224:227], v[20:23]
	v_mfma_f32_16x16x32_bf16 v[12:15], v[156:159], v[224:227], v[12:15]
	v_mfma_f32_16x16x32_bf16 v[4:7], v[148:151], v[232:235], v[4:7]
	v_mfma_f32_16x16x32_bf16 v[0:3], v[156:159], v[232:235], v[0:3]
	s_setprio 0
	s_barrier
	s_add_i32 s68, s68, 2
	s_add_u32 s91, s91, 0x10000
	s_addc_u32 s92, s92, 0
	s_add_u32 s0, s0, 0x100
	s_addc_u32 s1, s1, 0
	s_cmp_gt_u32 s68, 13
	s_cbranch_scc0 .LBB0_646
	s_and_b64 vcc, exec, s[56:57]
	s_cbranch_vccz .LBB0_649
	s_barrier

; #define PG8_STAGE(bufoff, gbase, voff) do { _Pragma("unroll") for (int _i = 0; _i < 2; ++_i) \
;         __builtin_amdgcn_global_load_lds((const unsigned*)((const char*)(gbase) + (voff)[_i]), (PG8_LAS unsigned*)(lds + (bufoff) + ldsw + _i * 8192), 16, 0, 0); } while (0)
; #define PG8_LDA(dst, b, h) do { _Pragma("unroll") for (int m = 0; m < 4; ++m) _Pragma("unroll") for (int k = 0; k < 2; ++k) dst[m][k] = *(const PG8_LAS bf16x8*)(lds + PG8_SA(b, h) + aoff + m * 2048 + k * 1024); } while (0)
; #define PG8_LDB(dst, b, h) do { _Pragma("unroll") for (int n = 0; n < 2; ++n) _Pragma("unroll") for (int k = 0; k < 2; ++k) dst[n][k] = *(const PG8_LAS bf16x8*)(lds + PG8_SB(b, h) + boff + n * 2048 + k * 1024); } while (0)
; #define PG8_SCHED __builtin_amdgcn_sched_barrier(0)
; template <class Epi, class Sched, bool ALIGN_EPI = false, bool SP2 = false>
; __device__ __forceinline__ void gemm_phase(PG8_LAS unsigned char* lds, const Gemm g, const Sched& S, const Epi& E) {
;     ...
;         const bool has_next = S.next(ui + 1, nxt);
;         const char* nA = has_next ? (const char*)g.A + (size_t)nxt.pm * tstepA : cA; const char* nB = has_next ? (const char*)g.Bt + (size_t)nxt.pn * tstepB : cB;
;         for (int t = 0; t < nt; t += 2) {
;             const bool last = (t == nt - 2);
;             const char* a1 = cA + (size_t)(t + 1) * kstepA;
;             const char* a2 = last ? nA : cA + (size_t)(t + 2) * kstepA; const char* b2 = last ? nB : cB + (size_t)(t + 2) * kstep;
;             const char* a3 = a2 + kstepA; const char* b3 = b2 + kstep;
;             if (last && has_next) S.a_ready(nxt);
;             if constexpr (SP2) {
;             PG8_LDB(B0, 0, 0); PG8_LDB(B1, 0, 1); PG8_SCHED; PG8_LDA(At, 0, 0); PG8_STAGE(PG8_SA(1, 1), a1 + hstepA, voffA);
;     ...
; #pragma unroll
;         for (int a = 0; a < 2; ++a)
; #pragma unroll
;             for (int b = 0; b < 2; ++b)
; #pragma unroll
;                 for (int m = 0; m < 4; ++m)
; #pragma unroll
;                     for (int n = 0; n < 2; ++n) acc[a][b][m][n] = (f32x4){0.f, 0.f, 0.f, 0.f};
.LBB0_669:
	s_ashr_i32 s57, s56, 31
	s_lshl_b64 s[8:9], s[56:57], 18
	s_add_u32 s58, s30, s8
	s_addc_u32 s59, s31, s9
	s_and_b64 s[8:9], s[2:3], exec
	s_cselect_b32 s57, s59, s67
	s_cselect_b32 s68, s58, s66
	s_ashr_i32 s55, s54, 31
	s_lshl_b64 s[8:9], s[54:55], 18
	v_readlane_b32 s60, v246, 7
	v_readlane_b32 s61, v246, 8
	s_add_u32 s60, s60, s8
	s_addc_u32 s61, s61, s9
	s_and_b64 s[8:9], s[2:3], exec
	s_cselect_b32 s55, s61, s65
	s_cselect_b32 s69, s60, s64
	s_add_u32 s82, s64, 0x10000
	s_addc_u32 s85, s65, 0
	s_add_u32 s64, s66, 0x20080
	s_addc_u32 s65, s67, 0
	s_mov_b32 s86, -2
.LBB0_670:
	ds_read_b128 v[108:111], v200
	ds_read_b128 v[132:135], v200 offset:1024
	ds_read_b128 v[136:139], v200 offset:2048
	ds_read_b128 v[140:143], v200 offset:3072
	ds_read_b128 v[144:147], v201
	ds_read_b128 v[148:151], v201 offset:1024
	ds_read_b128 v[152:155], v201 offset:2048
	ds_read_b128 v[156:159], v201 offset:3072
	s_add_u32 s8, s64, 0xfffe0080
	s_addc_u32 s9, s65, -1
	s_cmp_eq_u32 s86, 4
	s_cselect_b32 s67, s57, s9
	s_cselect_b32 s66, s68, s8
	s_cselect_b32 s9, s55, s85
	s_cselect_b32 s8, s69, s82
	v_lshl_add_u64 v[216:217], s[64:65], 0, v[186:187]
	s_add_i32 m0, s17, 0xc000
	ds_read_b128 v[160:163], v202
	ds_read_b128 v[164:167], v202 offset:1024
	ds_read_b128 v[168:171], v202 offset:2048
	ds_read_b128 v[204:207], v202 offset:3072
	ds_read_b128 v[208:211], v202 offset:4096
	ds_read_b128 v[212:215], v202 offset:5120
	ds_read_b128 v[220:223], v202 offset:6144
	ds_read_b128 v[224:227], v202 offset:7168
	global_load_lds_dwordx4 v[216:217], off
	v_lshl_add_u64 v[216:217], s[64:65], 0, v[192:193]
	s_add_i32 m0, s17, 0xe000
	s_nop 0
	global_load_lds_dwordx4 v[216:217], off
	s_cmp_lg_u32 s86, -2
	s_cbranch_scc1 .Lzskip_4
	v_mov_b32_e32 v0, 0
	v_mov_b32_e32 v1, 0
	v_mov_b32_e32 v2, 0
	v_mov_b32_e32 v3, 0
	v_mov_b32_e32 v4, 0
	v_mov_b32_e32 v5, 0
	v_mov_b32_e32 v6, 0
	v_mov_b32_e32 v7, 0
	v_mov_b32_e32 v8, 0
	v_mov_b32_e32 v9, 0
	v_mov_b32_e32 v10, 0
	v_mov_b32_e32 v11, 0
	v_mov_b32_e32 v12, 0
	v_mov_b32_e32 v13, 0
	v_mov_b32_e32 v14, 0
	v_mov_b32_e32 v15, 0
	v_mov_b32_e32 v16, 0
	v_mov_b32_e32 v17, 0
	v_mov_b32_e32 v18, 0
	v_mov_b32_e32 v19, 0
	v_mov_b32_e32 v20, 0
	v_mov_b32_e32 v21, 0
	v_mov_b32_e32 v22, 0
	v_mov_b32_e32 v23, 0
	v_mov_b32_e32 v24, 0
	v_mov_b32_e32 v25, 0
	v_mov_b32_e32 v26, 0
	v_mov_b32_e32 v27, 0
	v_mov_b32_e32 v28, 0
	v_mov_b32_e32 v29, 0
	v_mov_b32_e32 v30, 0
	v_mov_b32_e32 v31, 0
	v_mov_b32_e32 v32, 0
	v_mov_b32_e32 v33, 0
	v_mov_b32_e32 v34, 0
	v_mov_b32_e32 v35, 0
	v_mov_b32_e32 v36, 0
	v_mov_b32_e32 v37, 0
	v_mov_b32_e32 v38, 0
	v_mov_b32_e32 v39, 0
	v_mov_b32_e32 v40, 0
	v_mov_b32_e32 v41, 0
	v_mov_b32_e32 v42, 0
	v_mov_b32_e32 v43, 0
	v_mov_b32_e32 v44, 0
	v_mov_b32_e32 v45, 0
	v_mov_b32_e32 v46, 0
	v_mov_b32_e32 v47, 0
	v_mov_b32_e32 v48, 0
	v_mov_b32_e32 v49, 0
	v_mov_b32_e32 v50, 0
	v_mov_b32_e32 v51, 0
	v_mov_b32_e32 v52, 0
	v_mov_b32_e32 v53, 0
	v_mov_b32_e32 v54, 0
	v_mov_b32_e32 v55, 0
	v_mov_b32_e32 v56, 0
	v_mov_b32_e32 v57, 0
	v_mov_b32_e32 v58, 0
	v_mov_b32_e32 v59, 0
	v_mov_b32_e32 v60, 0
	v_mov_b32_e32 v61, 0
	v_mov_b32_e32 v62, 0
	v_mov_b32_e32 v63, 0
	v_mov_b32_e32 v64, 0
	v_mov_b32_e32 v65, 0
	v_mov_b32_e32 v66, 0
	v_mov_b32_e32 v67, 0
	v_mov_b32_e32 v68, 0
	v_mov_b32_e32 v69, 0
	v_mov_b32_e32 v70, 0
	v_mov_b32_e32 v71, 0
	v_mov_b32_e32 v72, 0
	v_mov_b32_e32 v73, 0
	v_mov_b32_e32 v74, 0
	v_mov_b32_e32 v75, 0
	v_mov_b32_e32 v76, 0
	v_mov_b32_e32 v77, 0
	v_mov_b32_e32 v78, 0
	v_mov_b32_e32 v79, 0
	v_mov_b32_e32 v80, 0
	v_mov_b32_e32 v81, 0
	v_mov_b32_e32 v82, 0
	v_mov_b32_e32 v83, 0
	v_mov_b32_e32 v84, 0
	v_mov_b32_e32 v85, 0
	v_mov_b32_e32 v86, 0
	v_mov_b32_e32 v87, 0
	v_mov_b32_e32 v88, 0
	v_mov_b32_e32 v89, 0
	v_mov_b32_e32 v90, 0
	v_mov_b32_e32 v91, 0
	v_mov_b32_e32 v92, 0
	v_mov_b32_e32 v93, 0
	v_mov_b32_e32 v94, 0
	v_mov_b32_e32 v95, 0
	v_mov_b32_e32 v96, 0
	v_mov_b32_e32 v97, 0
	v_mov_b32_e32 v98, 0
	v_mov_b32_e32 v99, 0
	v_mov_b32_e32 v100, 0
	v_mov_b32_e32 v101, 0
	v_mov_b32_e32 v102, 0
	v_mov_b32_e32 v103, 0
	v_mov_b32_e32 v104, 0
	v_mov_b32_e32 v105, 0
	v_mov_b32_e32 v106, 0
	v_mov_b32_e32 v107, 0
	v_mov_b32_e32 v112, 0
	v_mov_b32_e32 v113, 0
	v_mov_b32_e32 v114, 0
	v_mov_b32_e32 v115, 0
	v_mov_b32_e32 v116, 0
	v_mov_b32_e32 v117, 0
	v_mov_b32_e32 v118, 0
	v_mov_b32_e32 v119, 0
	v_mov_b32_e32 v120, 0
	v_mov_b32_e32 v121, 0
	v_mov_b32_e32 v122, 0
	v_mov_b32_e32 v123, 0
	v_mov_b32_e32 v124, 0
	v_mov_b32_e32 v125, 0
	v_mov_b32_e32 v126, 0
	v_mov_b32_e32 v127, 0
	v_mov_b32_e32 v128, 0
	v_mov_b32_e32 v129, 0
	v_mov_b32_e32 v130, 0
	v_mov_b32_e32 v131, 0
; #define PG8_STAGE(bufoff, gbase, voff) do { _Pragma("unroll") for (int _i = 0; _i < 2; ++_i) \
;         __builtin_amdgcn_global_load_lds((const unsigned*)((const char*)(gbase) + (voff)[_i]), (PG8_LAS unsigned*)(lds + (bufoff) + ldsw + _i * 8192), 16, 0, 0); } while (0)
; #define PG8_LDA(dst, b, h) do { _Pragma("unroll") for (int m = 0; m < 4; ++m) _Pragma("unroll") for (int k = 0; k < 2; ++k) dst[m][k] = *(const PG8_LAS bf16x8*)(lds + PG8_SA(b, h) + aoff + m * 2048 + k * 1024); } while (0)
; #define PG8_MMA(ai, bj, At, Bt) do { __builtin_amdgcn_s_setprio(1); _Pragma("unroll") for (int m = 0; m < 4; ++m) _Pragma("unroll") for (int n = 0; n < 2; ++n) _Pragma("unroll") for (int k = 0; k < 2; ++k) \
;         acc[ai][bj][m][n] = __builtin_amdgcn_mfma_f32_16x16x32_bf16(Bt[n][k], At[m][k], acc[ai][bj][m][n], 0, 0, 0); __builtin_amdgcn_s_setprio(0); } while (0)
; #define PG8_WAIT_V(n) asm volatile("s_waitcnt vmcnt(" #n ")" ::: "memory")
; #define PG8_WAIT_L(n) asm volatile("s_waitcnt lgkmcnt(" #n ")" ::: "memory")
; #define PG8_BAR __builtin_amdgcn_s_barrier()
; #define PG8_SCHED __builtin_amdgcn_sched_barrier(0)
; template <class Epi, class Sched, bool ALIGN_EPI = false, bool SP2 = false>
; __device__ __forceinline__ void gemm_phase(PG8_LAS unsigned char* lds, const Gemm g, const Sched& S, const Epi& E) {
;     ...
;             PG8_WAIT_V(8); PG8_WAIT_L(0); PG8_BAR; PG8_MMA(0, 0, At, B0); PG8_MMA(0, 1, At, B1); PG8_BAR; PG8_SCHED;
;             PG8_LDA(At, 0, 1); PG8_STAGE(PG8_SB(0, 0), b2, voffB); PG8_STAGE(PG8_SB(0, 1), b2 + hstepB, voffB); PG8_STAGE(PG8_SA(0, 0), a2, voffA);
;             PG8_WAIT_V(8); PG8_WAIT_L(0); PG8_BAR; PG8_MMA(1, 0, At, B0); PG8_MMA(1, 1, At, B1); PG8_BAR; PG8_SCHED;
.Lzskip_4:
	s_waitcnt vmcnt(8)
	s_waitcnt lgkmcnt(0)
	s_barrier
	s_setprio 1
	s_waitcnt lgkmcnt(0)
	v_mfma_f32_16x16x32_bf16 v[128:131], v[108:111], v[160:163], v[128:131]
	v_mfma_f32_16x16x32_bf16 v[124:127], v[136:139], v[160:163], v[124:127]
	v_mfma_f32_16x16x32_bf16 v[112:115], v[108:111], v[168:171], v[112:115]
	v_mfma_f32_16x16x32_bf16 v[104:107], v[136:139], v[168:171], v[104:107]
	v_mfma_f32_16x16x32_bf16 v[92:95], v[108:111], v[208:211], v[92:95]
	v_mfma_f32_16x16x32_bf16 v[88:91], v[136:139], v[208:211], v[88:91]
	v_mfma_f32_16x16x32_bf16 v[76:79], v[108:111], v[220:223], v[76:79]
	v_mfma_f32_16x16x32_bf16 v[72:75], v[136:139], v[220:223], v[72:75]
	v_mfma_f32_16x16x32_bf16 v[128:131], v[132:135], v[164:167], v[128:131]
	v_mfma_f32_16x16x32_bf16 v[124:127], v[140:143], v[164:167], v[124:127]
	v_mfma_f32_16x16x32_bf16 v[112:115], v[132:135], v[204:207], v[112:115]
	v_mfma_f32_16x16x32_bf16 v[104:107], v[140:143], v[204:207], v[104:107]
	v_mfma_f32_16x16x32_bf16 v[92:95], v[132:135], v[212:215], v[92:95]
	v_mfma_f32_16x16x32_bf16 v[88:91], v[140:143], v[212:215], v[88:91]
	v_mfma_f32_16x16x32_bf16 v[76:79], v[132:135], v[224:227], v[76:79]
	v_mfma_f32_16x16x32_bf16 v[72:75], v[140:143], v[224:227], v[72:75]
	s_setprio 0
	s_setprio 1
	v_mfma_f32_16x16x32_bf16 v[120:123], v[144:147], v[160:163], v[120:123]
	v_mfma_f32_16x16x32_bf16 v[116:119], v[152:155], v[160:163], v[116:119]
	v_mfma_f32_16x16x32_bf16 v[100:103], v[144:147], v[168:171], v[100:103]
	v_mfma_f32_16x16x32_bf16 v[96:99], v[152:155], v[168:171], v[96:99]
	v_mfma_f32_16x16x32_bf16 v[84:87], v[144:147], v[208:211], v[84:87]
	v_mfma_f32_16x16x32_bf16 v[80:83], v[152:155], v[208:211], v[80:83]
	v_mfma_f32_16x16x32_bf16 v[68:71], v[144:147], v[220:223], v[68:71]
	v_mfma_f32_16x16x32_bf16 v[64:67], v[152:155], v[220:223], v[64:67]
	v_mfma_f32_16x16x32_bf16 v[120:123], v[148:151], v[164:167], v[120:123]
	v_mfma_f32_16x16x32_bf16 v[116:119], v[156:159], v[164:167], v[116:119]
	v_mfma_f32_16x16x32_bf16 v[100:103], v[148:151], v[204:207], v[100:103]
	v_mfma_f32_16x16x32_bf16 v[96:99], v[156:159], v[204:207], v[96:99]
	v_mfma_f32_16x16x32_bf16 v[84:87], v[148:151], v[212:215], v[84:87]
	v_mfma_f32_16x16x32_bf16 v[80:83], v[156:159], v[212:215], v[80:83]
	v_mfma_f32_16x16x32_bf16 v[68:71], v[148:151], v[224:227], v[68:71]
	v_mfma_f32_16x16x32_bf16 v[64:67], v[156:159], v[224:227], v[64:67]
	s_setprio 0
	s_barrier
	v_lshl_add_u64 v[216:217], s[8:9], 0, v[190:191]
	s_add_i32 s8, s11, s15
	s_mov_b32 m0, s8
	ds_read_b128 v[160:163], v202 offset:16384
	ds_read_b128 v[164:167], v202 offset:17408
	ds_read_b128 v[168:171], v202 offset:18432
	ds_read_b128 v[204:207], v202 offset:19456
	ds_read_b128 v[208:211], v202 offset:20480
	ds_read_b128 v[212:215], v202 offset:21504
	ds_read_b128 v[220:223], v202 offset:22528
	ds_read_b128 v[224:227], v202 offset:23552
	global_load_lds_dwordx4 v[216:217], off
	v_lshl_add_u64 v[228:229], v[216:217], 0, s[0:1]
	s_add_i32 m0, s8, 0x2000
	s_add_i32 s8, s80, s15
	global_load_lds_dwordx4 v[228:229], off
	v_lshl_add_u64 v[228:229], v[216:217], 0, s[34:35]
	s_mov_b32 m0, s8
	v_lshl_add_u64 v[230:231], s[66:67], 0, v[174:175]
	global_load_lds_dwordx4 v[228:229], off
	v_lshl_add_u64 v[228:229], v[216:217], 0, s[36:37]
	s_add_i32 m0, s8, 0x2000
	s_nop 0
	global_load_lds_dwordx4 v[228:229], off
	v_lshl_add_u64 v[228:229], s[66:67], 0, v[172:173]
	s_mov_b32 m0, s17
	s_nop 0
	global_load_lds_dwordx4 v[228:229], off
	s_mov_b32 m0, s18
	s_nop 0
	global_load_lds_dwordx4 v[230:231], off
	s_waitcnt vmcnt(8)
	s_waitcnt lgkmcnt(0)
	s_barrier
	s_setprio 1
	s_waitcnt lgkmcnt(0)
	v_mfma_f32_16x16x32_bf16 v[60:63], v[108:111], v[160:163], v[60:63]
	v_mfma_f32_16x16x32_bf16 v[56:59], v[136:139], v[160:163], v[56:59]
	v_mfma_f32_16x16x32_bf16 v[44:47], v[108:111], v[168:171], v[44:47]
	v_mfma_f32_16x16x32_bf16 v[40:43], v[136:139], v[168:171], v[40:43]
	v_mfma_f32_16x16x32_bf16 v[28:31], v[108:111], v[208:211], v[28:31]
	v_mfma_f32_16x16x32_bf16 v[24:27], v[136:139], v[208:211], v[24:27]
	v_mfma_f32_16x16x32_bf16 v[12:15], v[108:111], v[220:223], v[12:15]
	v_mfma_f32_16x16x32_bf16 v[8:11], v[136:139], v[220:223], v[8:11]
	v_mfma_f32_16x16x32_bf16 v[60:63], v[132:135], v[164:167], v[60:63]
	v_mfma_f32_16x16x32_bf16 v[56:59], v[140:143], v[164:167], v[56:59]
	v_mfma_f32_16x16x32_bf16 v[44:47], v[132:135], v[204:207], v[44:47]
	v_mfma_f32_16x16x32_bf16 v[40:43], v[140:143], v[204:207], v[40:43]
	v_mfma_f32_16x16x32_bf16 v[28:31], v[132:135], v[212:215], v[28:31]
	v_mfma_f32_16x16x32_bf16 v[24:27], v[140:143], v[212:215], v[24:27]
	v_mfma_f32_16x16x32_bf16 v[12:15], v[132:135], v[224:227], v[12:15]
	v_mfma_f32_16x16x32_bf16 v[8:11], v[140:143], v[224:227], v[8:11]
	s_setprio 0
	s_setprio 1
	v_mfma_f32_16x16x32_bf16 v[52:55], v[144:147], v[160:163], v[52:55]
	v_mfma_f32_16x16x32_bf16 v[48:51], v[152:155], v[160:163], v[48:51]
	v_mfma_f32_16x16x32_bf16 v[36:39], v[144:147], v[168:171], v[36:39]
	v_mfma_f32_16x16x32_bf16 v[32:35], v[152:155], v[168:171], v[32:35]
	v_mfma_f32_16x16x32_bf16 v[20:23], v[144:147], v[208:211], v[20:23]
	v_mfma_f32_16x16x32_bf16 v[16:19], v[152:155], v[208:211], v[16:19]
	v_mfma_f32_16x16x32_bf16 v[4:7], v[144:147], v[220:223], v[4:7]
	v_mfma_f32_16x16x32_bf16 v[0:3], v[152:155], v[220:223], v[0:3]
	v_mfma_f32_16x16x32_bf16 v[52:55], v[148:151], v[164:167], v[52:55]
	v_mfma_f32_16x16x32_bf16 v[48:51], v[156:159], v[164:167], v[48:51]
	v_mfma_f32_16x16x32_bf16 v[36:39], v[148:151], v[204:207], v[36:39]
	v_mfma_f32_16x16x32_bf16 v[32:35], v[156:159], v[204:207], v[32:35]
	v_mfma_f32_16x16x32_bf16 v[20:23], v[148:151], v[212:215], v[20:23]
	v_mfma_f32_16x16x32_bf16 v[16:19], v[156:159], v[212:215], v[16:19]
	v_mfma_f32_16x16x32_bf16 v[4:7], v[148:151], v[224:227], v[4:7]
	v_mfma_f32_16x16x32_bf16 v[0:3], v[156:159], v[224:227], v[0:3]
	s_setprio 0
	s_barrier
; #define PG8_STAGE(bufoff, gbase, voff) do { _Pragma("unroll") for (int _i = 0; _i < 2; ++_i) \
;         __builtin_amdgcn_global_load_lds((const unsigned*)((const char*)(gbase) + (voff)[_i]), (PG8_LAS unsigned*)(lds + (bufoff) + ldsw + _i * 8192), 16, 0, 0); } while (0)
; #define PG8_LDA(dst, b, h) do { _Pragma("unroll") for (int m = 0; m < 4; ++m) _Pragma("unroll") for (int k = 0; k < 2; ++k) dst[m][k] = *(const PG8_LAS bf16x8*)(lds + PG8_SA(b, h) + aoff + m * 2048 + k * 1024); } while (0)
; #define PG8_LDB(dst, b, h) do { _Pragma("unroll") for (int n = 0; n < 2; ++n) _Pragma("unroll") for (int k = 0; k < 2; ++k) dst[n][k] = *(const PG8_LAS bf16x8*)(lds + PG8_SB(b, h) + boff + n * 2048 + k * 1024); } while (0)
; #define PG8_MMA(ai, bj, At, Bt) do { __builtin_amdgcn_s_setprio(1); _Pragma("unroll") for (int m = 0; m < 4; ++m) _Pragma("unroll") for (int n = 0; n < 2; ++n) _Pragma("unroll") for (int k = 0; k < 2; ++k) \
;         acc[ai][bj][m][n] = __builtin_amdgcn_mfma_f32_16x16x32_bf16(Bt[n][k], At[m][k], acc[ai][bj][m][n], 0, 0, 0); __builtin_amdgcn_s_setprio(0); } while (0)
; #define PG8_WAIT_V(n) asm volatile("s_waitcnt vmcnt(" #n ")" ::: "memory")
; #define PG8_WAIT_L(n) asm volatile("s_waitcnt lgkmcnt(" #n ")" ::: "memory")
; #define PG8_BAR __builtin_amdgcn_s_barrier()
; #define PG8_SCHED __builtin_amdgcn_sched_barrier(0)
; template <class Epi, class Sched, bool ALIGN_EPI = false, bool SP2 = false>
; __device__ __forceinline__ void gemm_phase(PG8_LAS unsigned char* lds, const Gemm g, const Sched& S, const Epi& E) {
;     ...
;             PG8_LDB(B0, 1, 0); PG8_LDB(B1, 1, 1); PG8_SCHED; PG8_LDA(At, 1, 0); PG8_STAGE(PG8_SA(0, 1), a2 + hstepA, voffA);
;             PG8_WAIT_V(8); PG8_WAIT_L(0); PG8_BAR; PG8_MMA(0, 0, At, B0); PG8_MMA(0, 1, At, B1); PG8_BAR; PG8_SCHED;
	s_add_i32 s78, 0, 0x1c000
	v_add_u32_e32 v156, s78, v199
	ds_read_b128 v[108:111], v203
	ds_read_b128 v[132:135], v203 offset:1024
	ds_read_b128 v[136:139], v203 offset:2048
	ds_read_b128 v[140:143], v203 offset:3072
	ds_read_b128 v[144:147], v156
	ds_read_b128 v[148:151], v156 offset:1024
	ds_read_b128 v[152:155], v156 offset:2048
	ds_read_b128 v[156:159], v156 offset:3072
	s_add_u32 s8, s66, 0x20000
	s_addc_u32 s9, s67, 0
	s_mov_b32 m0, s19
	v_lshl_add_u64 v[232:233], s[8:9], 0, v[172:173]
	ds_read_b128 v[160:163], v202 offset:32768
	ds_read_b128 v[164:167], v202 offset:33792
	ds_read_b128 v[168:171], v202 offset:34816
	ds_read_b128 v[204:207], v202 offset:35840
	ds_read_b128 v[208:211], v202 offset:36864
	ds_read_b128 v[212:215], v202 offset:37888
	ds_read_b128 v[220:223], v202 offset:38912
	ds_read_b128 v[224:227], v202 offset:39936
	global_load_lds_dwordx4 v[232:233], off
	v_lshl_add_u64 v[232:233], s[8:9], 0, v[174:175]
	s_mov_b32 m0, s70
	s_nop 0
	global_load_lds_dwordx4 v[232:233], off
	s_waitcnt vmcnt(8)
	s_waitcnt lgkmcnt(0)
	s_barrier
	s_setprio 1
	s_waitcnt lgkmcnt(0)
	v_mfma_f32_16x16x32_bf16 v[128:131], v[108:111], v[160:163], v[128:131]
	v_mfma_f32_16x16x32_bf16 v[124:127], v[136:139], v[160:163], v[124:127]
	v_mfma_f32_16x16x32_bf16 v[112:115], v[108:111], v[168:171], v[112:115]
	v_mfma_f32_16x16x32_bf16 v[104:107], v[136:139], v[168:171], v[104:107]
	v_mfma_f32_16x16x32_bf16 v[92:95], v[108:111], v[208:211], v[92:95]
	v_mfma_f32_16x16x32_bf16 v[88:91], v[136:139], v[208:211], v[88:91]
	v_mfma_f32_16x16x32_bf16 v[76:79], v[108:111], v[220:223], v[76:79]
	v_mfma_f32_16x16x32_bf16 v[72:75], v[136:139], v[220:223], v[72:75]
	v_mfma_f32_16x16x32_bf16 v[128:131], v[132:135], v[164:167], v[128:131]
	v_mfma_f32_16x16x32_bf16 v[124:127], v[140:143], v[164:167], v[124:127]
	v_mfma_f32_16x16x32_bf16 v[112:115], v[132:135], v[204:207], v[112:115]
	v_mfma_f32_16x16x32_bf16 v[104:107], v[140:143], v[204:207], v[104:107]
	v_mfma_f32_16x16x32_bf16 v[92:95], v[132:135], v[212:215], v[92:95]
	v_mfma_f32_16x16x32_bf16 v[88:91], v[140:143], v[212:215], v[88:91]
	v_mfma_f32_16x16x32_bf16 v[76:79], v[132:135], v[224:227], v[76:79]
	v_mfma_f32_16x16x32_bf16 v[72:75], v[140:143], v[224:227], v[72:75]
	s_setprio 0
	s_setprio 1
	v_mfma_f32_16x16x32_bf16 v[120:123], v[144:147], v[160:163], v[120:123]
	v_mfma_f32_16x16x32_bf16 v[116:119], v[152:155], v[160:163], v[116:119]
	v_mfma_f32_16x16x32_bf16 v[100:103], v[144:147], v[168:171], v[100:103]
	v_mfma_f32_16x16x32_bf16 v[96:99], v[152:155], v[168:171], v[96:99]
	v_mfma_f32_16x16x32_bf16 v[84:87], v[144:147], v[208:211], v[84:87]
	v_mfma_f32_16x16x32_bf16 v[80:83], v[152:155], v[208:211], v[80:83]
	v_mfma_f32_16x16x32_bf16 v[68:71], v[144:147], v[220:223], v[68:71]
	v_mfma_f32_16x16x32_bf16 v[64:67], v[152:155], v[220:223], v[64:67]
	v_mfma_f32_16x16x32_bf16 v[120:123], v[148:151], v[164:167], v[120:123]
	v_mfma_f32_16x16x32_bf16 v[116:119], v[156:159], v[164:167], v[116:119]
	v_mfma_f32_16x16x32_bf16 v[100:103], v[148:151], v[204:207], v[100:103]
	v_mfma_f32_16x16x32_bf16 v[96:99], v[156:159], v[204:207], v[96:99]
	v_mfma_f32_16x16x32_bf16 v[84:87], v[148:151], v[212:215], v[84:87]
	v_mfma_f32_16x16x32_bf16 v[80:83], v[156:159], v[212:215], v[80:83]
	v_mfma_f32_16x16x32_bf16 v[68:71], v[148:151], v[224:227], v[68:71]
	v_mfma_f32_16x16x32_bf16 v[64:67], v[156:159], v[224:227], v[64:67]
	s_setprio 0
	s_barrier
; #define PG8_STAGE(bufoff, gbase, voff) do { _Pragma("unroll") for (int _i = 0; _i < 2; ++_i) \
;         __builtin_amdgcn_global_load_lds((const unsigned*)((const char*)(gbase) + (voff)[_i]), (PG8_LAS unsigned*)(lds + (bufoff) + ldsw + _i * 8192), 16, 0, 0); } while (0)
; #define PG8_LDA(dst, b, h) do { _Pragma("unroll") for (int m = 0; m < 4; ++m) _Pragma("unroll") for (int k = 0; k < 2; ++k) dst[m][k] = *(const PG8_LAS bf16x8*)(lds + PG8_SA(b, h) + aoff + m * 2048 + k * 1024); } while (0)
; #define PG8_MMA(ai, bj, At, Bt) do { __builtin_amdgcn_s_setprio(1); _Pragma("unroll") for (int m = 0; m < 4; ++m) _Pragma("unroll") for (int n = 0; n < 2; ++n) _Pragma("unroll") for (int k = 0; k < 2; ++k) \
;         acc[ai][bj][m][n] = __builtin_amdgcn_mfma_f32_16x16x32_bf16(Bt[n][k], At[m][k], acc[ai][bj][m][n], 0, 0, 0); __builtin_amdgcn_s_setprio(0); } while (0)
; #define PG8_WAIT_V(n) asm volatile("s_waitcnt vmcnt(" #n ")" ::: "memory")
; #define PG8_WAIT_L(n) asm volatile("s_waitcnt lgkmcnt(" #n ")" ::: "memory")
; #define PG8_BAR __builtin_amdgcn_s_barrier()
; #define PG8_SCHED __builtin_amdgcn_sched_barrier(0)
; template <class Epi, class Sched, bool ALIGN_EPI = false, bool SP2 = false>
; __device__ __forceinline__ void gemm_phase(PG8_LAS unsigned char* lds, const Gemm g, const Sched& S, const Epi& E) {
;     ...
;             PG8_LDA(At, 1, 1); PG8_STAGE(PG8_SB(1, 0), b3, voffB); PG8_STAGE(PG8_SB(1, 1), b3 + hstepB, voffB); PG8_STAGE(PG8_SA(1, 0), a3, voffA);
;             PG8_WAIT_V(8); PG8_WAIT_L(0); PG8_BAR; PG8_MMA(1, 0, At, B0); PG8_MMA(1, 1, At, B1); PG8_BAR; PG8_SCHED;
	s_add_i32 s8, s81, s15
	v_lshl_add_u64 v[232:233], v[216:217], 0, s[38:39]
	s_mov_b32 m0, s8
	ds_read_b128 v[160:163], v202 offset:49152
	ds_read_b128 v[164:167], v202 offset:50176
	ds_read_b128 v[168:171], v202 offset:51200
	ds_read_b128 v[204:207], v202 offset:52224
	ds_read_b128 v[208:211], v202 offset:53248
	ds_read_b128 v[212:215], v202 offset:54272
	ds_read_b128 v[220:223], v202 offset:55296
	ds_read_b128 v[224:227], v202 offset:56320
	global_load_lds_dwordx4 v[232:233], off
	v_lshl_add_u64 v[232:233], v[216:217], 0, s[40:41]
	s_add_i32 m0, s8, 0x2000
	s_add_i32 s8, s78, s15
	global_load_lds_dwordx4 v[232:233], off
	v_lshl_add_u64 v[232:233], v[216:217], 0, s[44:45]
	s_mov_b32 m0, s8
	v_lshl_add_u64 v[216:217], v[216:217], 0, s[46:47]
	global_load_lds_dwordx4 v[232:233], off
	s_add_i32 m0, s8, 0x2000
	s_nop 0
	global_load_lds_dwordx4 v[216:217], off
	v_lshl_add_u64 v[216:217], v[228:229], 0, s[42:43]
	s_mov_b32 m0, s71
	s_nop 0
	global_load_lds_dwordx4 v[216:217], off
	v_lshl_add_u64 v[216:217], v[230:231], 0, s[42:43]
	s_mov_b32 m0, s72
	s_nop 0
	global_load_lds_dwordx4 v[216:217], off
	s_waitcnt vmcnt(8)
	s_waitcnt lgkmcnt(0)
	s_barrier
	s_setprio 1
	s_waitcnt lgkmcnt(0)
	v_mfma_f32_16x16x32_bf16 v[60:63], v[108:111], v[160:163], v[60:63]
	v_mfma_f32_16x16x32_bf16 v[56:59], v[136:139], v[160:163], v[56:59]
	v_mfma_f32_16x16x32_bf16 v[44:47], v[108:111], v[168:171], v[44:47]
	v_mfma_f32_16x16x32_bf16 v[40:43], v[136:139], v[168:171], v[40:43]
	v_mfma_f32_16x16x32_bf16 v[28:31], v[108:111], v[208:211], v[28:31]
	v_mfma_f32_16x16x32_bf16 v[24:27], v[136:139], v[208:211], v[24:27]
	v_mfma_f32_16x16x32_bf16 v[12:15], v[108:111], v[220:223], v[12:15]
	v_mfma_f32_16x16x32_bf16 v[8:11], v[136:139], v[220:223], v[8:11]
	v_mfma_f32_16x16x32_bf16 v[60:63], v[132:135], v[164:167], v[60:63]
	v_mfma_f32_16x16x32_bf16 v[56:59], v[140:143], v[164:167], v[56:59]
	v_mfma_f32_16x16x32_bf16 v[44:47], v[132:135], v[204:207], v[44:47]
	v_mfma_f32_16x16x32_bf16 v[40:43], v[140:143], v[204:207], v[40:43]
	v_mfma_f32_16x16x32_bf16 v[28:31], v[132:135], v[212:215], v[28:31]
	v_mfma_f32_16x16x32_bf16 v[24:27], v[140:143], v[212:215], v[24:27]
	v_mfma_f32_16x16x32_bf16 v[12:15], v[132:135], v[224:227], v[12:15]
	v_mfma_f32_16x16x32_bf16 v[8:11], v[140:143], v[224:227], v[8:11]
	s_setprio 0
	s_setprio 1
	v_mfma_f32_16x16x32_bf16 v[52:55], v[144:147], v[160:163], v[52:55]
	v_mfma_f32_16x16x32_bf16 v[48:51], v[152:155], v[160:163], v[48:51]
	v_mfma_f32_16x16x32_bf16 v[36:39], v[144:147], v[168:171], v[36:39]
	v_mfma_f32_16x16x32_bf16 v[32:35], v[152:155], v[168:171], v[32:35]
	v_mfma_f32_16x16x32_bf16 v[20:23], v[144:147], v[208:211], v[20:23]
	v_mfma_f32_16x16x32_bf16 v[16:19], v[152:155], v[208:211], v[16:19]
	v_mfma_f32_16x16x32_bf16 v[4:7], v[144:147], v[220:223], v[4:7]
	v_mfma_f32_16x16x32_bf16 v[0:3], v[152:155], v[220:223], v[0:3]
	v_mfma_f32_16x16x32_bf16 v[52:55], v[148:151], v[164:167], v[52:55]
	v_mfma_f32_16x16x32_bf16 v[48:51], v[156:159], v[164:167], v[48:51]
	v_mfma_f32_16x16x32_bf16 v[36:39], v[148:151], v[204:207], v[36:39]
	v_mfma_f32_16x16x32_bf16 v[32:35], v[156:159], v[204:207], v[32:35]
	v_mfma_f32_16x16x32_bf16 v[20:23], v[148:151], v[212:215], v[20:23]
	v_mfma_f32_16x16x32_bf16 v[16:19], v[156:159], v[212:215], v[16:19]
	v_mfma_f32_16x16x32_bf16 v[4:7], v[148:151], v[224:227], v[4:7]
	v_mfma_f32_16x16x32_bf16 v[0:3], v[156:159], v[224:227], v[0:3]
	s_setprio 0
	s_barrier
	s_add_i32 s86, s86, 2
	s_add_u32 s82, s82, 0x10000
	s_addc_u32 s85, s85, 0
	s_add_u32 s64, s64, 0x100
	s_addc_u32 s65, s65, 0
	s_cmp_gt_u32 s86, 5
	s_cbranch_scc0 .LBB0_670
	s_and_b64 vcc, exec, s[52:53]
	s_cbranch_vccz .LBB0_673
	s_barrier

; #define PG8_STAGE(bufoff, gbase, voff) do { _Pragma("unroll") for (int _i = 0; _i < 2; ++_i) \
;         __builtin_amdgcn_global_load_lds((const unsigned*)((const char*)(gbase) + (voff)[_i]), (PG8_LAS unsigned*)(lds + (bufoff) + ldsw + _i * 8192), 16, 0, 0); } while (0)
; #define PG8_LDA(dst, b, h) do { _Pragma("unroll") for (int m = 0; m < 4; ++m) _Pragma("unroll") for (int k = 0; k < 2; ++k) dst[m][k] = *(const PG8_LAS bf16x8*)(lds + PG8_SA(b, h) + aoff + m * 2048 + k * 1024); } while (0)
; #define PG8_LDB(dst, b, h) do { _Pragma("unroll") for (int n = 0; n < 2; ++n) _Pragma("unroll") for (int k = 0; k < 2; ++k) dst[n][k] = *(const PG8_LAS bf16x8*)(lds + PG8_SB(b, h) + boff + n * 2048 + k * 1024); } while (0)
; #define PG8_SCHED __builtin_amdgcn_sched_barrier(0)
; template <class Epi, class Sched, bool ALIGN_EPI = false, bool SP2 = false>
; __device__ __forceinline__ void gemm_phase(PG8_LAS unsigned char* lds, const Gemm g, const Sched& S, const Epi& E) {
;     ...
;         const bool has_next = S.next(ui + 1, nxt);
;         const char* nA = has_next ? (const char*)g.A + (size_t)nxt.pm * tstepA : cA; const char* nB = has_next ? (const char*)g.Bt + (size_t)nxt.pn * tstepB : cB;
;         for (int t = 0; t < nt; t += 2) {
;             const bool last = (t == nt - 2);
;             const char* a1 = cA + (size_t)(t + 1) * kstepA;
;             const char* a2 = last ? nA : cA + (size_t)(t + 2) * kstepA; const char* b2 = last ? nB : cB + (size_t)(t + 2) * kstep;
;             const char* a3 = a2 + kstepA; const char* b3 = b2 + kstep;
;             if (last && has_next) S.a_ready(nxt);
;             if constexpr (SP2) {
;             PG8_LDB(B0, 0, 0); PG8_LDB(B1, 0, 1); PG8_SCHED; PG8_LDA(At, 0, 0); PG8_STAGE(PG8_SA(1, 1), a1 + hstepA, voffA);
;     ...
; #pragma unroll
;         for (int a = 0; a < 2; ++a)
; #pragma unroll
;             for (int b = 0; b < 2; ++b)
; #pragma unroll
;                 for (int m = 0; m < 4; ++m)
; #pragma unroll
;                     for (int n = 0; n < 2; ++n) acc[a][b][m][n] = (f32x4){0.f, 0.f, 0.f, 0.f};
.LBB0_750:
	s_ashr_i32 s59, s58, 31
	s_lshl_b64 s[60:61], s[58:59], 19
	s_add_u32 s60, s6, s60
	s_addc_u32 s61, s7, s61
	s_and_b64 s[62:63], s[4:5], exec
	s_cselect_b32 s59, s61, s69
	s_cselect_b32 s65, s60, s68
	s_ashr_i32 s57, s56, 31
	s_lshl_b64 s[62:63], s[56:57], 19
	s_add_u32 s62, s93, s62
	s_addc_u32 s63, s84, s63
	s_and_b64 s[72:73], s[4:5], exec
	s_cselect_b32 s57, s63, s71
	s_cselect_b32 s67, s62, s70
	s_add_u32 s68, s68, 0x10000
	s_addc_u32 s69, s69, 0
	s_add_u32 s70, s70, 0x10000
	s_addc_u32 s71, s71, 0
	s_mov_b32 s72, -2
	s_waitcnt lgkmcnt(0)
.LBB0_751:
	ds_read_b128 v[128:131], v211
	ds_read_b128 v[132:135], v211 offset:1024
	ds_read_b128 v[136:139], v211 offset:2048
	ds_read_b128 v[140:143], v211 offset:3072
	ds_read_b128 v[144:147], v212
	ds_read_b128 v[148:151], v212 offset:1024
	ds_read_b128 v[152:155], v212 offset:2048
	ds_read_b128 v[156:159], v212 offset:3072
	s_cmp_eq_u32 s72, 12
	s_cselect_b32 s79, s59, s69
	s_cselect_b32 s78, s65, s68
	s_cselect_b32 s91, s57, s71
	s_cselect_b32 s90, s67, s70
	v_lshl_add_u64 v[208:209], s[68:69], 0, v[190:191]
	v_lshl_add_u64 v[228:229], v[208:209], 0, s[52:53]
	s_add_i32 m0, s15, 0xc000
	ds_read_b128 v[160:163], v213
	ds_read_b128 v[164:167], v213 offset:1024
	ds_read_b128 v[168:171], v213 offset:2048
	ds_read_b128 v[172:175], v213 offset:3072
	ds_read_b128 v[176:179], v213 offset:4096
	ds_read_b128 v[180:183], v213 offset:5120
	ds_read_b128 v[220:223], v213 offset:6144
	ds_read_b128 v[224:227], v213 offset:7168
	global_load_lds_dwordx4 v[228:229], off
	v_lshl_add_u64 v[208:209], v[208:209], 0, s[54:55]
	s_add_i32 m0, s15, 0xe000
	s_nop 0
	global_load_lds_dwordx4 v[208:209], off
	s_cmp_lg_u32 s72, -2
	s_cbranch_scc1 .Lzskip_5
	v_mov_b32_e32 v0, 0
	v_mov_b32_e32 v1, 0
	v_mov_b32_e32 v2, 0
	v_mov_b32_e32 v3, 0
	v_mov_b32_e32 v4, 0
	v_mov_b32_e32 v5, 0
	v_mov_b32_e32 v6, 0
	v_mov_b32_e32 v7, 0
	v_mov_b32_e32 v8, 0
	v_mov_b32_e32 v9, 0
	v_mov_b32_e32 v10, 0
	v_mov_b32_e32 v11, 0
	v_mov_b32_e32 v12, 0
	v_mov_b32_e32 v13, 0
	v_mov_b32_e32 v14, 0
	v_mov_b32_e32 v15, 0
	v_mov_b32_e32 v16, 0
	v_mov_b32_e32 v17, 0
	v_mov_b32_e32 v18, 0
	v_mov_b32_e32 v19, 0
	v_mov_b32_e32 v20, 0
	v_mov_b32_e32 v21, 0
	v_mov_b32_e32 v22, 0
	v_mov_b32_e32 v23, 0
	v_mov_b32_e32 v24, 0
	v_mov_b32_e32 v25, 0
	v_mov_b32_e32 v26, 0
	v_mov_b32_e32 v27, 0
	v_mov_b32_e32 v28, 0
	v_mov_b32_e32 v29, 0
	v_mov_b32_e32 v30, 0
	v_mov_b32_e32 v31, 0
	v_mov_b32_e32 v32, 0
	v_mov_b32_e32 v33, 0
	v_mov_b32_e32 v34, 0
	v_mov_b32_e32 v35, 0
	v_mov_b32_e32 v36, 0
	v_mov_b32_e32 v37, 0
	v_mov_b32_e32 v38, 0
	v_mov_b32_e32 v39, 0
	v_mov_b32_e32 v40, 0
	v_mov_b32_e32 v41, 0
	v_mov_b32_e32 v42, 0
	v_mov_b32_e32 v43, 0
	v_mov_b32_e32 v44, 0
	v_mov_b32_e32 v45, 0
	v_mov_b32_e32 v46, 0
	v_mov_b32_e32 v47, 0
	v_mov_b32_e32 v48, 0
	v_mov_b32_e32 v49, 0
	v_mov_b32_e32 v50, 0
	v_mov_b32_e32 v51, 0
	v_mov_b32_e32 v52, 0
	v_mov_b32_e32 v53, 0
	v_mov_b32_e32 v54, 0
	v_mov_b32_e32 v55, 0
	v_mov_b32_e32 v56, 0
	v_mov_b32_e32 v57, 0
	v_mov_b32_e32 v58, 0
	v_mov_b32_e32 v59, 0
	v_mov_b32_e32 v60, 0
	v_mov_b32_e32 v61, 0
	v_mov_b32_e32 v62, 0
	v_mov_b32_e32 v63, 0
	v_mov_b32_e32 v64, 0
	v_mov_b32_e32 v65, 0
	v_mov_b32_e32 v66, 0
	v_mov_b32_e32 v67, 0
	v_mov_b32_e32 v68, 0
	v_mov_b32_e32 v69, 0
	v_mov_b32_e32 v70, 0
	v_mov_b32_e32 v71, 0
	v_mov_b32_e32 v72, 0
	v_mov_b32_e32 v73, 0
	v_mov_b32_e32 v74, 0
	v_mov_b32_e32 v75, 0
	v_mov_b32_e32 v76, 0
	v_mov_b32_e32 v77, 0
	v_mov_b32_e32 v78, 0
	v_mov_b32_e32 v79, 0
	v_mov_b32_e32 v80, 0
	v_mov_b32_e32 v81, 0
	v_mov_b32_e32 v82, 0
	v_mov_b32_e32 v83, 0
	v_mov_b32_e32 v84, 0
	v_mov_b32_e32 v85, 0
	v_mov_b32_e32 v86, 0
	v_mov_b32_e32 v87, 0
	v_mov_b32_e32 v88, 0
	v_mov_b32_e32 v89, 0
	v_mov_b32_e32 v90, 0
	v_mov_b32_e32 v91, 0
	v_mov_b32_e32 v92, 0
	v_mov_b32_e32 v93, 0
	v_mov_b32_e32 v94, 0
	v_mov_b32_e32 v95, 0
	v_mov_b32_e32 v96, 0
	v_mov_b32_e32 v97, 0
	v_mov_b32_e32 v98, 0
	v_mov_b32_e32 v99, 0
	v_mov_b32_e32 v100, 0
	v_mov_b32_e32 v101, 0
	v_mov_b32_e32 v102, 0
	v_mov_b32_e32 v103, 0
	v_mov_b32_e32 v104, 0
	v_mov_b32_e32 v105, 0
	v_mov_b32_e32 v106, 0
	v_mov_b32_e32 v107, 0
	v_mov_b32_e32 v108, 0
	v_mov_b32_e32 v109, 0
	v_mov_b32_e32 v110, 0
	v_mov_b32_e32 v111, 0
	v_mov_b32_e32 v112, 0
	v_mov_b32_e32 v113, 0
	v_mov_b32_e32 v114, 0
	v_mov_b32_e32 v115, 0
	v_mov_b32_e32 v116, 0
	v_mov_b32_e32 v117, 0
	v_mov_b32_e32 v118, 0
	v_mov_b32_e32 v119, 0
	v_mov_b32_e32 v120, 0
	v_mov_b32_e32 v121, 0
	v_mov_b32_e32 v122, 0
	v_mov_b32_e32 v123, 0
	v_mov_b32_e32 v124, 0
	v_mov_b32_e32 v125, 0
	v_mov_b32_e32 v126, 0
	v_mov_b32_e32 v127, 0
; #define PG8_STAGE(bufoff, gbase, voff) do { _Pragma("unroll") for (int _i = 0; _i < 2; ++_i) \
;         __builtin_amdgcn_global_load_lds((const unsigned*)((const char*)(gbase) + (voff)[_i]), (PG8_LAS unsigned*)(lds + (bufoff) + ldsw + _i * 8192), 16, 0, 0); } while (0)
; #define PG8_LDA(dst, b, h) do { _Pragma("unroll") for (int m = 0; m < 4; ++m) _Pragma("unroll") for (int k = 0; k < 2; ++k) dst[m][k] = *(const PG8_LAS bf16x8*)(lds + PG8_SA(b, h) + aoff + m * 2048 + k * 1024); } while (0)
; #define PG8_MMA(ai, bj, At, Bt) do { __builtin_amdgcn_s_setprio(1); _Pragma("unroll") for (int m = 0; m < 4; ++m) _Pragma("unroll") for (int n = 0; n < 2; ++n) _Pragma("unroll") for (int k = 0; k < 2; ++k) \
;         acc[ai][bj][m][n] = __builtin_amdgcn_mfma_f32_16x16x32_bf16(Bt[n][k], At[m][k], acc[ai][bj][m][n], 0, 0, 0); __builtin_amdgcn_s_setprio(0); } while (0)
; #define PG8_WAIT_V(n) asm volatile("s_waitcnt vmcnt(" #n ")" ::: "memory")
; #define PG8_WAIT_L(n) asm volatile("s_waitcnt lgkmcnt(" #n ")" ::: "memory")
; #define PG8_BAR __builtin_amdgcn_s_barrier()
; #define PG8_SCHED __builtin_amdgcn_sched_barrier(0)
; template <class Epi, class Sched, bool ALIGN_EPI = false, bool SP2 = false>
; __device__ __forceinline__ void gemm_phase(PG8_LAS unsigned char* lds, const Gemm g, const Sched& S, const Epi& E) {
;     ...
;             PG8_WAIT_V(8); PG8_WAIT_L(0); PG8_BAR; PG8_MMA(0, 0, At, B0); PG8_MMA(0, 1, At, B1); PG8_BAR; PG8_SCHED;
;             PG8_LDA(At, 0, 1); PG8_STAGE(PG8_SB(0, 0), b2, voffB); PG8_STAGE(PG8_SB(0, 1), b2 + hstepB, voffB); PG8_STAGE(PG8_SA(0, 0), a2, voffA);
;             PG8_WAIT_V(8); PG8_WAIT_L(0); PG8_BAR; PG8_MMA(1, 0, At, B0); PG8_MMA(1, 1, At, B1); PG8_BAR; PG8_SCHED;
.Lzskip_5:
	s_waitcnt vmcnt(8)
	s_waitcnt lgkmcnt(0)
	s_barrier
	s_setprio 1
	s_waitcnt lgkmcnt(0)
	v_mfma_f32_16x16x32_bf16 v[124:127], v[128:131], v[160:163], v[124:127]
	v_mfma_f32_16x16x32_bf16 v[120:123], v[136:139], v[160:163], v[120:123]
	v_mfma_f32_16x16x32_bf16 v[108:111], v[128:131], v[168:171], v[108:111]
	v_mfma_f32_16x16x32_bf16 v[104:107], v[136:139], v[168:171], v[104:107]
	v_mfma_f32_16x16x32_bf16 v[92:95], v[128:131], v[176:179], v[92:95]
	v_mfma_f32_16x16x32_bf16 v[88:91], v[136:139], v[176:179], v[88:91]
	v_mfma_f32_16x16x32_bf16 v[76:79], v[128:131], v[220:223], v[76:79]
	v_mfma_f32_16x16x32_bf16 v[72:75], v[136:139], v[220:223], v[72:75]
	v_mfma_f32_16x16x32_bf16 v[124:127], v[132:135], v[164:167], v[124:127]
	v_mfma_f32_16x16x32_bf16 v[120:123], v[140:143], v[164:167], v[120:123]
	v_mfma_f32_16x16x32_bf16 v[108:111], v[132:135], v[172:175], v[108:111]
	v_mfma_f32_16x16x32_bf16 v[104:107], v[140:143], v[172:175], v[104:107]
	v_mfma_f32_16x16x32_bf16 v[92:95], v[132:135], v[180:183], v[92:95]
	v_mfma_f32_16x16x32_bf16 v[88:91], v[140:143], v[180:183], v[88:91]
	v_mfma_f32_16x16x32_bf16 v[76:79], v[132:135], v[224:227], v[76:79]
	v_mfma_f32_16x16x32_bf16 v[72:75], v[140:143], v[224:227], v[72:75]
	s_setprio 0
	s_setprio 1
	v_mfma_f32_16x16x32_bf16 v[116:119], v[144:147], v[160:163], v[116:119]
	v_mfma_f32_16x16x32_bf16 v[112:115], v[152:155], v[160:163], v[112:115]
	v_mfma_f32_16x16x32_bf16 v[100:103], v[144:147], v[168:171], v[100:103]
	v_mfma_f32_16x16x32_bf16 v[96:99], v[152:155], v[168:171], v[96:99]
	v_mfma_f32_16x16x32_bf16 v[84:87], v[144:147], v[176:179], v[84:87]
	v_mfma_f32_16x16x32_bf16 v[80:83], v[152:155], v[176:179], v[80:83]
	v_mfma_f32_16x16x32_bf16 v[68:71], v[144:147], v[220:223], v[68:71]
	v_mfma_f32_16x16x32_bf16 v[64:67], v[152:155], v[220:223], v[64:67]
	v_mfma_f32_16x16x32_bf16 v[116:119], v[148:151], v[164:167], v[116:119]
	v_mfma_f32_16x16x32_bf16 v[112:115], v[156:159], v[164:167], v[112:115]
	v_mfma_f32_16x16x32_bf16 v[100:103], v[148:151], v[172:175], v[100:103]
	v_mfma_f32_16x16x32_bf16 v[96:99], v[156:159], v[172:175], v[96:99]
	v_mfma_f32_16x16x32_bf16 v[84:87], v[148:151], v[180:183], v[84:87]
	v_mfma_f32_16x16x32_bf16 v[80:83], v[156:159], v[180:183], v[80:83]
	v_mfma_f32_16x16x32_bf16 v[68:71], v[148:151], v[224:227], v[68:71]
	v_mfma_f32_16x16x32_bf16 v[64:67], v[156:159], v[224:227], v[64:67]
	s_setprio 0
	s_barrier
	s_add_i32 s73, s85, s14
	v_lshl_add_u64 v[208:209], s[90:91], 0, v[190:191]
	s_mov_b32 m0, s73
	ds_read_b128 v[160:163], v213 offset:16384
	ds_read_b128 v[164:167], v213 offset:17408
	ds_read_b128 v[168:171], v213 offset:18432
	ds_read_b128 v[172:175], v213 offset:19456
	ds_read_b128 v[176:179], v213 offset:20480
	ds_read_b128 v[180:183], v213 offset:21504
	ds_read_b128 v[220:223], v213 offset:22528
	ds_read_b128 v[224:227], v213 offset:23552
	global_load_lds_dwordx4 v[208:209], off
	v_lshl_add_u64 v[228:229], v[208:209], 0, s[10:11]
	s_add_i32 m0, s73, 0x2000
	s_add_i32 s73, s86, s14
	global_load_lds_dwordx4 v[228:229], off
	v_lshl_add_u64 v[228:229], v[208:209], 0, s[34:35]
	s_mov_b32 m0, s73
	s_nop 0
	global_load_lds_dwordx4 v[228:229], off
	v_lshl_add_u64 v[228:229], v[208:209], 0, s[36:37]
	s_add_i32 m0, s73, 0x2000
	s_nop 0
	global_load_lds_dwordx4 v[228:229], off
	v_lshl_add_u64 v[228:229], s[78:79], 0, v[190:191]
	s_mov_b32 m0, s15
	v_lshl_add_u64 v[230:231], v[228:229], 0, s[10:11]
	global_load_lds_dwordx4 v[228:229], off
	s_mov_b32 m0, s17
	s_nop 0
	global_load_lds_dwordx4 v[230:231], off
	s_waitcnt vmcnt(8)
	s_waitcnt lgkmcnt(0)
	s_barrier
	s_setprio 1
	s_waitcnt lgkmcnt(0)
	v_mfma_f32_16x16x32_bf16 v[60:63], v[128:131], v[160:163], v[60:63]
	v_mfma_f32_16x16x32_bf16 v[56:59], v[136:139], v[160:163], v[56:59]
	v_mfma_f32_16x16x32_bf16 v[44:47], v[128:131], v[168:171], v[44:47]
	v_mfma_f32_16x16x32_bf16 v[40:43], v[136:139], v[168:171], v[40:43]
	v_mfma_f32_16x16x32_bf16 v[28:31], v[128:131], v[176:179], v[28:31]
	v_mfma_f32_16x16x32_bf16 v[24:27], v[136:139], v[176:179], v[24:27]
	v_mfma_f32_16x16x32_bf16 v[12:15], v[128:131], v[220:223], v[12:15]
	v_mfma_f32_16x16x32_bf16 v[8:11], v[136:139], v[220:223], v[8:11]
	v_mfma_f32_16x16x32_bf16 v[60:63], v[132:135], v[164:167], v[60:63]
	v_mfma_f32_16x16x32_bf16 v[56:59], v[140:143], v[164:167], v[56:59]
	v_mfma_f32_16x16x32_bf16 v[44:47], v[132:135], v[172:175], v[44:47]
	v_mfma_f32_16x16x32_bf16 v[40:43], v[140:143], v[172:175], v[40:43]
	v_mfma_f32_16x16x32_bf16 v[28:31], v[132:135], v[180:183], v[28:31]
	v_mfma_f32_16x16x32_bf16 v[24:27], v[140:143], v[180:183], v[24:27]
	v_mfma_f32_16x16x32_bf16 v[12:15], v[132:135], v[224:227], v[12:15]
	v_mfma_f32_16x16x32_bf16 v[8:11], v[140:143], v[224:227], v[8:11]
	s_setprio 0
	s_setprio 1
	v_mfma_f32_16x16x32_bf16 v[52:55], v[144:147], v[160:163], v[52:55]
	v_mfma_f32_16x16x32_bf16 v[48:51], v[152:155], v[160:163], v[48:51]
	v_mfma_f32_16x16x32_bf16 v[36:39], v[144:147], v[168:171], v[36:39]
	v_mfma_f32_16x16x32_bf16 v[32:35], v[152:155], v[168:171], v[32:35]
	v_mfma_f32_16x16x32_bf16 v[20:23], v[144:147], v[176:179], v[20:23]
	v_mfma_f32_16x16x32_bf16 v[16:19], v[152:155], v[176:179], v[16:19]
	v_mfma_f32_16x16x32_bf16 v[4:7], v[144:147], v[220:223], v[4:7]
	v_mfma_f32_16x16x32_bf16 v[0:3], v[152:155], v[220:223], v[0:3]
	v_mfma_f32_16x16x32_bf16 v[52:55], v[148:151], v[164:167], v[52:55]
	v_mfma_f32_16x16x32_bf16 v[48:51], v[156:159], v[164:167], v[48:51]
	v_mfma_f32_16x16x32_bf16 v[36:39], v[148:151], v[172:175], v[36:39]
	v_mfma_f32_16x16x32_bf16 v[32:35], v[156:159], v[172:175], v[32:35]
	v_mfma_f32_16x16x32_bf16 v[20:23], v[148:151], v[180:183], v[20:23]
	v_mfma_f32_16x16x32_bf16 v[16:19], v[156:159], v[180:183], v[16:19]
	v_mfma_f32_16x16x32_bf16 v[4:7], v[148:151], v[224:227], v[4:7]
	v_mfma_f32_16x16x32_bf16 v[0:3], v[156:159], v[224:227], v[0:3]
	s_setprio 0
	s_barrier
; #define PG8_STAGE(bufoff, gbase, voff) do { _Pragma("unroll") for (int _i = 0; _i < 2; ++_i) \
;         __builtin_amdgcn_global_load_lds((const unsigned*)((const char*)(gbase) + (voff)[_i]), (PG8_LAS unsigned*)(lds + (bufoff) + ldsw + _i * 8192), 16, 0, 0); } while (0)
; #define PG8_LDA(dst, b, h) do { _Pragma("unroll") for (int m = 0; m < 4; ++m) _Pragma("unroll") for (int k = 0; k < 2; ++k) dst[m][k] = *(const PG8_LAS bf16x8*)(lds + PG8_SA(b, h) + aoff + m * 2048 + k * 1024); } while (0)
; #define PG8_LDB(dst, b, h) do { _Pragma("unroll") for (int n = 0; n < 2; ++n) _Pragma("unroll") for (int k = 0; k < 2; ++k) dst[n][k] = *(const PG8_LAS bf16x8*)(lds + PG8_SB(b, h) + boff + n * 2048 + k * 1024); } while (0)
; #define PG8_MMA(ai, bj, At, Bt) do { __builtin_amdgcn_s_setprio(1); _Pragma("unroll") for (int m = 0; m < 4; ++m) _Pragma("unroll") for (int n = 0; n < 2; ++n) _Pragma("unroll") for (int k = 0; k < 2; ++k) \
;         acc[ai][bj][m][n] = __builtin_amdgcn_mfma_f32_16x16x32_bf16(Bt[n][k], At[m][k], acc[ai][bj][m][n], 0, 0, 0); __builtin_amdgcn_s_setprio(0); } while (0)
; #define PG8_WAIT_V(n) asm volatile("s_waitcnt vmcnt(" #n ")" ::: "memory")
; #define PG8_WAIT_L(n) asm volatile("s_waitcnt lgkmcnt(" #n ")" ::: "memory")
; #define PG8_BAR __builtin_amdgcn_s_barrier()
; #define PG8_SCHED __builtin_amdgcn_sched_barrier(0)
; template <class Epi, class Sched, bool ALIGN_EPI = false, bool SP2 = false>
; __device__ __forceinline__ void gemm_phase(PG8_LAS unsigned char* lds, const Gemm g, const Sched& S, const Epi& E) {
;     ...
;             PG8_LDB(B0, 1, 0); PG8_LDB(B1, 1, 1); PG8_SCHED; PG8_LDA(At, 1, 0); PG8_STAGE(PG8_SA(0, 1), a2 + hstepA, voffA);
;             PG8_WAIT_V(8); PG8_WAIT_L(0); PG8_BAR; PG8_MMA(0, 0, At, B0); PG8_MMA(0, 1, At, B1); PG8_BAR; PG8_SCHED;
;             PG8_LDA(At, 1, 1); PG8_STAGE(PG8_SB(1, 0), b3, voffB); PG8_STAGE(PG8_SB(1, 1), b3 + hstepB, voffB); PG8_STAGE(PG8_SA(1, 0), a3, voffA);
;             PG8_WAIT_V(8); PG8_WAIT_L(0); PG8_BAR; PG8_MMA(1, 0, At, B0); PG8_MMA(1, 1, At, B1); PG8_BAR; PG8_SCHED;
	ds_read_b128 v[128:131], v214
	ds_read_b128 v[132:135], v214 offset:1024
	ds_read_b128 v[136:139], v214 offset:2048
	ds_read_b128 v[140:143], v214 offset:3072
	ds_read_b128 v[144:147], v215
	ds_read_b128 v[148:151], v215 offset:1024
	ds_read_b128 v[152:155], v215 offset:2048
	ds_read_b128 v[156:159], v215 offset:3072
	s_mov_b32 m0, s18
	v_lshl_add_u64 v[230:231], v[228:229], 0, s[34:35]
	ds_read_b128 v[160:163], v213 offset:32768
	ds_read_b128 v[164:167], v213 offset:33792
	ds_read_b128 v[168:171], v213 offset:34816
	ds_read_b128 v[172:175], v213 offset:35840
	ds_read_b128 v[176:179], v213 offset:36864
	ds_read_b128 v[180:183], v213 offset:37888
	ds_read_b128 v[220:223], v213 offset:38912
	ds_read_b128 v[224:227], v213 offset:39936
	global_load_lds_dwordx4 v[230:231], off
	v_lshl_add_u64 v[230:231], v[228:229], 0, s[36:37]
	s_mov_b32 m0, s19
	s_nop 0
	global_load_lds_dwordx4 v[230:231], off
	s_waitcnt vmcnt(8)
	s_waitcnt lgkmcnt(0)
	s_barrier
	s_setprio 1
	s_waitcnt lgkmcnt(0)
	v_mfma_f32_16x16x32_bf16 v[124:127], v[128:131], v[160:163], v[124:127]
	v_mfma_f32_16x16x32_bf16 v[120:123], v[136:139], v[160:163], v[120:123]
	v_mfma_f32_16x16x32_bf16 v[108:111], v[128:131], v[168:171], v[108:111]
	v_mfma_f32_16x16x32_bf16 v[104:107], v[136:139], v[168:171], v[104:107]
	v_mfma_f32_16x16x32_bf16 v[92:95], v[128:131], v[176:179], v[92:95]
	v_mfma_f32_16x16x32_bf16 v[88:91], v[136:139], v[176:179], v[88:91]
	v_mfma_f32_16x16x32_bf16 v[76:79], v[128:131], v[220:223], v[76:79]
	v_mfma_f32_16x16x32_bf16 v[72:75], v[136:139], v[220:223], v[72:75]
	v_mfma_f32_16x16x32_bf16 v[124:127], v[132:135], v[164:167], v[124:127]
	v_mfma_f32_16x16x32_bf16 v[120:123], v[140:143], v[164:167], v[120:123]
	v_mfma_f32_16x16x32_bf16 v[108:111], v[132:135], v[172:175], v[108:111]
	v_mfma_f32_16x16x32_bf16 v[104:107], v[140:143], v[172:175], v[104:107]
	v_mfma_f32_16x16x32_bf16 v[92:95], v[132:135], v[180:183], v[92:95]
	v_mfma_f32_16x16x32_bf16 v[88:91], v[140:143], v[180:183], v[88:91]
	v_mfma_f32_16x16x32_bf16 v[76:79], v[132:135], v[224:227], v[76:79]
	v_mfma_f32_16x16x32_bf16 v[72:75], v[140:143], v[224:227], v[72:75]
	s_setprio 0
	s_setprio 1
	v_mfma_f32_16x16x32_bf16 v[116:119], v[144:147], v[160:163], v[116:119]
	v_mfma_f32_16x16x32_bf16 v[112:115], v[152:155], v[160:163], v[112:115]
	v_mfma_f32_16x16x32_bf16 v[100:103], v[144:147], v[168:171], v[100:103]
	v_mfma_f32_16x16x32_bf16 v[96:99], v[152:155], v[168:171], v[96:99]
	v_mfma_f32_16x16x32_bf16 v[84:87], v[144:147], v[176:179], v[84:87]
	v_mfma_f32_16x16x32_bf16 v[80:83], v[152:155], v[176:179], v[80:83]
	v_mfma_f32_16x16x32_bf16 v[68:71], v[144:147], v[220:223], v[68:71]
	v_mfma_f32_16x16x32_bf16 v[64:67], v[152:155], v[220:223], v[64:67]
	v_mfma_f32_16x16x32_bf16 v[116:119], v[148:151], v[164:167], v[116:119]
	v_mfma_f32_16x16x32_bf16 v[112:115], v[156:159], v[164:167], v[112:115]
	v_mfma_f32_16x16x32_bf16 v[100:103], v[148:151], v[172:175], v[100:103]
	v_mfma_f32_16x16x32_bf16 v[96:99], v[156:159], v[172:175], v[96:99]
	v_mfma_f32_16x16x32_bf16 v[84:87], v[148:151], v[180:183], v[84:87]
	v_mfma_f32_16x16x32_bf16 v[80:83], v[156:159], v[180:183], v[80:83]
	v_mfma_f32_16x16x32_bf16 v[68:71], v[148:151], v[224:227], v[68:71]
	v_mfma_f32_16x16x32_bf16 v[64:67], v[156:159], v[224:227], v[64:67]
	s_setprio 0
	s_barrier
	s_add_i32 s73, s87, s14
	v_lshl_add_u64 v[230:231], v[208:209], 0, s[38:39]
	s_mov_b32 m0, s73
	ds_read_b128 v[160:163], v213 offset:49152
	ds_read_b128 v[164:167], v213 offset:50176
	ds_read_b128 v[168:171], v213 offset:51200
	ds_read_b128 v[172:175], v213 offset:52224
	ds_read_b128 v[176:179], v213 offset:53248
	ds_read_b128 v[180:183], v213 offset:54272
	ds_read_b128 v[220:223], v213 offset:55296
	ds_read_b128 v[224:227], v213 offset:56320
	global_load_lds_dwordx4 v[230:231], off
	v_lshl_add_u64 v[230:231], v[208:209], 0, s[40:41]
	s_add_i32 m0, s73, 0x2000
	s_add_i32 s73, s88, s14
	global_load_lds_dwordx4 v[230:231], off
	v_lshl_add_u64 v[230:231], v[208:209], 0, s[42:43]
	s_mov_b32 m0, s73
	v_lshl_add_u64 v[208:209], v[208:209], 0, s[44:45]
	global_load_lds_dwordx4 v[230:231], off
	s_add_i32 m0, s73, 0x2000
	s_nop 0
	global_load_lds_dwordx4 v[208:209], off
	v_lshl_add_u64 v[208:209], v[228:229], 0, s[38:39]
	s_mov_b32 m0, s74
	s_nop 0
	global_load_lds_dwordx4 v[208:209], off
	v_lshl_add_u64 v[208:209], v[228:229], 0, s[40:41]
	s_mov_b32 m0, s75
	s_nop 0
	global_load_lds_dwordx4 v[208:209], off
	s_waitcnt vmcnt(8)
	s_waitcnt lgkmcnt(0)
	s_barrier
	s_setprio 1
	s_waitcnt lgkmcnt(0)
	v_mfma_f32_16x16x32_bf16 v[60:63], v[128:131], v[160:163], v[60:63]
	v_mfma_f32_16x16x32_bf16 v[56:59], v[136:139], v[160:163], v[56:59]
	v_mfma_f32_16x16x32_bf16 v[44:47], v[128:131], v[168:171], v[44:47]
	v_mfma_f32_16x16x32_bf16 v[40:43], v[136:139], v[168:171], v[40:43]
	v_mfma_f32_16x16x32_bf16 v[28:31], v[128:131], v[176:179], v[28:31]
	v_mfma_f32_16x16x32_bf16 v[24:27], v[136:139], v[176:179], v[24:27]
	v_mfma_f32_16x16x32_bf16 v[12:15], v[128:131], v[220:223], v[12:15]
	v_mfma_f32_16x16x32_bf16 v[8:11], v[136:139], v[220:223], v[8:11]
	v_mfma_f32_16x16x32_bf16 v[60:63], v[132:135], v[164:167], v[60:63]
	v_mfma_f32_16x16x32_bf16 v[56:59], v[140:143], v[164:167], v[56:59]
	v_mfma_f32_16x16x32_bf16 v[44:47], v[132:135], v[172:175], v[44:47]
	v_mfma_f32_16x16x32_bf16 v[40:43], v[140:143], v[172:175], v[40:43]
	v_mfma_f32_16x16x32_bf16 v[28:31], v[132:135], v[180:183], v[28:31]
	v_mfma_f32_16x16x32_bf16 v[24:27], v[140:143], v[180:183], v[24:27]
	v_mfma_f32_16x16x32_bf16 v[12:15], v[132:135], v[224:227], v[12:15]
	v_mfma_f32_16x16x32_bf16 v[8:11], v[140:143], v[224:227], v[8:11]
	s_setprio 0
	s_setprio 1
	v_mfma_f32_16x16x32_bf16 v[52:55], v[144:147], v[160:163], v[52:55]
	v_mfma_f32_16x16x32_bf16 v[48:51], v[152:155], v[160:163], v[48:51]
	v_mfma_f32_16x16x32_bf16 v[36:39], v[144:147], v[168:171], v[36:39]
	v_mfma_f32_16x16x32_bf16 v[32:35], v[152:155], v[168:171], v[32:35]
	v_mfma_f32_16x16x32_bf16 v[20:23], v[144:147], v[176:179], v[20:23]
	v_mfma_f32_16x16x32_bf16 v[16:19], v[152:155], v[176:179], v[16:19]
	v_mfma_f32_16x16x32_bf16 v[4:7], v[144:147], v[220:223], v[4:7]
	v_mfma_f32_16x16x32_bf16 v[0:3], v[152:155], v[220:223], v[0:3]
	v_mfma_f32_16x16x32_bf16 v[52:55], v[148:151], v[164:167], v[52:55]
	v_mfma_f32_16x16x32_bf16 v[48:51], v[156:159], v[164:167], v[48:51]
	v_mfma_f32_16x16x32_bf16 v[36:39], v[148:151], v[172:175], v[36:39]
	v_mfma_f32_16x16x32_bf16 v[32:35], v[156:159], v[172:175], v[32:35]
	v_mfma_f32_16x16x32_bf16 v[20:23], v[148:151], v[180:183], v[20:23]
	v_mfma_f32_16x16x32_bf16 v[16:19], v[156:159], v[180:183], v[16:19]
	v_mfma_f32_16x16x32_bf16 v[4:7], v[148:151], v[224:227], v[4:7]
	v_mfma_f32_16x16x32_bf16 v[0:3], v[156:159], v[224:227], v[0:3]
	s_setprio 0
	s_barrier
	s_add_i32 s72, s72, 2
	s_add_u32 s68, s68, 0x10000
	s_addc_u32 s69, s69, 0
	s_add_u32 s70, s70, 0x10000
	s_addc_u32 s71, s71, 0
	s_cmp_gt_u32 s72, 13
	s_cbranch_scc0 .LBB0_751
	s_and_b64 vcc, exec, s[48:49]
	s_cbranch_vccz .LBB0_754
	s_barrier

; #define PG8_STAGE(bufoff, gbase, voff) do { _Pragma("unroll") for (int _i = 0; _i < 2; ++_i) \
;         __builtin_amdgcn_global_load_lds((const unsigned*)((const char*)(gbase) + (voff)[_i]), (PG8_LAS unsigned*)(lds + (bufoff) + ldsw + _i * 8192), 16, 0, 0); } while (0)
; #define PG8_LDA(dst, b, h) do { _Pragma("unroll") for (int m = 0; m < 4; ++m) _Pragma("unroll") for (int k = 0; k < 2; ++k) dst[m][k] = *(const PG8_LAS bf16x8*)(lds + PG8_SA(b, h) + aoff + m * 2048 + k * 1024); } while (0)
; #define PG8_LDB(dst, b, h) do { _Pragma("unroll") for (int n = 0; n < 2; ++n) _Pragma("unroll") for (int k = 0; k < 2; ++k) dst[n][k] = *(const PG8_LAS bf16x8*)(lds + PG8_SB(b, h) + boff + n * 2048 + k * 1024); } while (0)
; #define PG8_SCHED __builtin_amdgcn_sched_barrier(0)
; template <class Epi, class Sched, bool ALIGN_EPI = false, bool SP2 = false>
; __device__ __forceinline__ void gemm_phase(PG8_LAS unsigned char* lds, const Gemm g, const Sched& S, const Epi& E) {
;     ...
;         const bool has_next = S.next(ui + 1, nxt);
;         const char* nA = has_next ? (const char*)g.A + (size_t)nxt.pm * tstepA : cA; const char* nB = has_next ? (const char*)g.Bt + (size_t)nxt.pn * tstepB : cB;
;         for (int t = 0; t < nt; t += 2) {
;             const bool last = (t == nt - 2);
;             const char* a1 = cA + (size_t)(t + 1) * kstepA;
;             const char* a2 = last ? nA : cA + (size_t)(t + 2) * kstepA; const char* b2 = last ? nB : cB + (size_t)(t + 2) * kstep;
;             const char* a3 = a2 + kstepA; const char* b3 = b2 + kstep;
;             if (last && has_next) S.a_ready(nxt);
;             if constexpr (SP2) {
;             PG8_LDB(B0, 0, 0); PG8_LDB(B1, 0, 1); PG8_SCHED; PG8_LDA(At, 0, 0); PG8_STAGE(PG8_SA(1, 1), a1 + hstepA, voffA);
;     ...
; #pragma unroll
;         for (int a = 0; a < 2; ++a)
; #pragma unroll
;             for (int b = 0; b < 2; ++b)
; #pragma unroll
;                 for (int m = 0; m < 4; ++m)
; #pragma unroll
;                     for (int n = 0; n < 2; ++n) acc[a][b][m][n] = (f32x4){0.f, 0.f, 0.f, 0.f};
.LBB0_837:
	s_ashr_i32 s55, s54, 31
	s_lshl_b64 s[56:57], s[54:55], 19
	s_add_u32 s56, s12, s56
	s_addc_u32 s57, s13, s57
	s_and_b64 s[58:59], s[2:3], exec
	s_cselect_b32 s55, s57, s63
	s_cselect_b32 s80, s56, s62
	s_ashr_i32 s53, s52, 31
	s_lshl_b64 s[58:59], s[52:53], 19
	s_add_u32 s58, s33, s58
	s_addc_u32 s59, s83, s59
	s_and_b64 s[78:79], s[2:3], exec
	s_cselect_b32 s53, s59, s65
	s_cselect_b32 s81, s58, s64
	s_add_u32 s62, s62, 0x10000
	s_addc_u32 s63, s63, 0
	s_add_u32 s64, s64, 0x10000
	s_addc_u32 s65, s65, 0
	s_mov_b32 s82, -2
.LBB0_838:
	ds_read_b128 v[148:151], v141
	ds_read_b128 v[152:155], v141 offset:1024
	ds_read_b128 v[156:159], v141 offset:2048
	ds_read_b128 v[160:163], v141 offset:3072
	ds_read_b128 v[164:167], v142
	ds_read_b128 v[168:171], v142 offset:1024
	ds_read_b128 v[172:175], v142 offset:2048
	ds_read_b128 v[176:179], v142 offset:3072
	s_cmp_eq_u32 s82, 12
	s_cselect_b32 s79, s55, s63
	s_cselect_b32 s78, s80, s62
	s_cselect_b32 s85, s53, s65
	s_cselect_b32 s84, s81, s64
	v_lshl_add_u64 v[216:217], s[62:63], 0, v[190:191]
	v_lshl_add_u64 v[220:221], v[216:217], 0, s[46:47]
	s_add_i32 m0, s18, 0xc000
	ds_read_b128 v[180:183], v143
	ds_read_b128 v[184:187], v143 offset:1024
	ds_read_b128 v[192:195], v143 offset:2048
	ds_read_b128 v[196:199], v143 offset:3072
	ds_read_b128 v[200:203], v143 offset:4096
	ds_read_b128 v[204:207], v143 offset:5120
	ds_read_b128 v[208:211], v143 offset:6144
	ds_read_b128 v[212:215], v143 offset:7168
	global_load_lds_dwordx4 v[220:221], off
	v_lshl_add_u64 v[216:217], v[216:217], 0, s[48:49]
	s_add_i32 m0, s18, 0xe000
	s_nop 0
	global_load_lds_dwordx4 v[216:217], off
	s_cmp_lg_u32 s82, -2
	s_cbranch_scc1 .Lzskip_6
	v_mov_b32_e32 v0, 0
	v_mov_b32_e32 v1, 0
	v_mov_b32_e32 v2, 0
	v_mov_b32_e32 v3, 0
	v_mov_b32_e32 v4, 0
	v_mov_b32_e32 v5, 0
	v_mov_b32_e32 v6, 0
	v_mov_b32_e32 v7, 0
	v_mov_b32_e32 v8, 0
	v_mov_b32_e32 v9, 0
	v_mov_b32_e32 v10, 0
	v_mov_b32_e32 v11, 0
	v_mov_b32_e32 v12, 0
	v_mov_b32_e32 v13, 0
	v_mov_b32_e32 v14, 0
	v_mov_b32_e32 v15, 0
	v_mov_b32_e32 v16, 0
	v_mov_b32_e32 v17, 0
	v_mov_b32_e32 v18, 0
	v_mov_b32_e32 v19, 0
	v_mov_b32_e32 v20, 0
	v_mov_b32_e32 v21, 0
	v_mov_b32_e32 v22, 0
	v_mov_b32_e32 v23, 0
	v_mov_b32_e32 v24, 0
	v_mov_b32_e32 v25, 0
	v_mov_b32_e32 v26, 0
	v_mov_b32_e32 v27, 0
	v_mov_b32_e32 v28, 0
	v_mov_b32_e32 v29, 0
	v_mov_b32_e32 v30, 0
	v_mov_b32_e32 v31, 0
	v_mov_b32_e32 v32, 0
	v_mov_b32_e32 v33, 0
	v_mov_b32_e32 v34, 0
	v_mov_b32_e32 v35, 0
	v_mov_b32_e32 v36, 0
	v_mov_b32_e32 v37, 0
	v_mov_b32_e32 v38, 0
	v_mov_b32_e32 v39, 0
	v_mov_b32_e32 v40, 0
	v_mov_b32_e32 v41, 0
	v_mov_b32_e32 v42, 0
	v_mov_b32_e32 v43, 0
	v_mov_b32_e32 v44, 0
	v_mov_b32_e32 v45, 0
	v_mov_b32_e32 v46, 0
	v_mov_b32_e32 v47, 0
	v_mov_b32_e32 v48, 0
	v_mov_b32_e32 v49, 0
	v_mov_b32_e32 v50, 0
	v_mov_b32_e32 v51, 0
	v_mov_b32_e32 v52, 0
	v_mov_b32_e32 v53, 0
	v_mov_b32_e32 v54, 0
	v_mov_b32_e32 v55, 0
	v_mov_b32_e32 v56, 0
	v_mov_b32_e32 v57, 0
	v_mov_b32_e32 v58, 0
	v_mov_b32_e32 v59, 0
	v_mov_b32_e32 v60, 0
	v_mov_b32_e32 v61, 0
	v_mov_b32_e32 v62, 0
	v_mov_b32_e32 v63, 0
	v_mov_b32_e32 v64, 0
	v_mov_b32_e32 v65, 0
	v_mov_b32_e32 v66, 0
	v_mov_b32_e32 v67, 0
	v_mov_b32_e32 v68, 0
	v_mov_b32_e32 v69, 0
	v_mov_b32_e32 v70, 0
	v_mov_b32_e32 v71, 0
	v_mov_b32_e32 v72, 0
	v_mov_b32_e32 v73, 0
	v_mov_b32_e32 v74, 0
	v_mov_b32_e32 v75, 0
	v_mov_b32_e32 v76, 0
	v_mov_b32_e32 v77, 0
	v_mov_b32_e32 v78, 0
	v_mov_b32_e32 v79, 0
	v_mov_b32_e32 v80, 0
	v_mov_b32_e32 v81, 0
	v_mov_b32_e32 v82, 0
	v_mov_b32_e32 v83, 0
	v_mov_b32_e32 v84, 0
	v_mov_b32_e32 v85, 0
	v_mov_b32_e32 v86, 0
	v_mov_b32_e32 v87, 0
	v_mov_b32_e32 v88, 0
	v_mov_b32_e32 v89, 0
	v_mov_b32_e32 v90, 0
	v_mov_b32_e32 v91, 0
	v_mov_b32_e32 v92, 0
	v_mov_b32_e32 v93, 0
	v_mov_b32_e32 v94, 0
	v_mov_b32_e32 v95, 0
	v_mov_b32_e32 v96, 0
	v_mov_b32_e32 v97, 0
	v_mov_b32_e32 v98, 0
	v_mov_b32_e32 v99, 0
	v_mov_b32_e32 v100, 0
	v_mov_b32_e32 v101, 0
	v_mov_b32_e32 v102, 0
	v_mov_b32_e32 v103, 0
	v_mov_b32_e32 v104, 0
	v_mov_b32_e32 v105, 0
	v_mov_b32_e32 v106, 0
	v_mov_b32_e32 v107, 0
	v_mov_b32_e32 v108, 0
	v_mov_b32_e32 v109, 0
	v_mov_b32_e32 v110, 0
	v_mov_b32_e32 v111, 0
	v_mov_b32_e32 v112, 0
	v_mov_b32_e32 v113, 0
	v_mov_b32_e32 v114, 0
	v_mov_b32_e32 v115, 0
	v_mov_b32_e32 v116, 0
	v_mov_b32_e32 v117, 0
	v_mov_b32_e32 v118, 0
	v_mov_b32_e32 v119, 0
	v_mov_b32_e32 v120, 0
	v_mov_b32_e32 v121, 0
	v_mov_b32_e32 v122, 0
	v_mov_b32_e32 v123, 0
	v_mov_b32_e32 v124, 0
	v_mov_b32_e32 v125, 0
	v_mov_b32_e32 v126, 0
	v_mov_b32_e32 v127, 0
; #define PG8_STAGE(bufoff, gbase, voff) do { _Pragma("unroll") for (int _i = 0; _i < 2; ++_i) \
;         __builtin_amdgcn_global_load_lds((const unsigned*)((const char*)(gbase) + (voff)[_i]), (PG8_LAS unsigned*)(lds + (bufoff) + ldsw + _i * 8192), 16, 0, 0); } while (0)
; #define PG8_LDA(dst, b, h) do { _Pragma("unroll") for (int m = 0; m < 4; ++m) _Pragma("unroll") for (int k = 0; k < 2; ++k) dst[m][k] = *(const PG8_LAS bf16x8*)(lds + PG8_SA(b, h) + aoff + m * 2048 + k * 1024); } while (0)
; #define PG8_MMA(ai, bj, At, Bt) do { __builtin_amdgcn_s_setprio(1); _Pragma("unroll") for (int m = 0; m < 4; ++m) _Pragma("unroll") for (int n = 0; n < 2; ++n) _Pragma("unroll") for (int k = 0; k < 2; ++k) \
;         acc[ai][bj][m][n] = __builtin_amdgcn_mfma_f32_16x16x32_bf16(Bt[n][k], At[m][k], acc[ai][bj][m][n], 0, 0, 0); __builtin_amdgcn_s_setprio(0); } while (0)
; #define PG8_WAIT_V(n) asm volatile("s_waitcnt vmcnt(" #n ")" ::: "memory")
; #define PG8_WAIT_L(n) asm volatile("s_waitcnt lgkmcnt(" #n ")" ::: "memory")
; #define PG8_BAR __builtin_amdgcn_s_barrier()
; #define PG8_SCHED __builtin_amdgcn_sched_barrier(0)
; template <class Epi, class Sched, bool ALIGN_EPI = false, bool SP2 = false>
; __device__ __forceinline__ void gemm_phase(PG8_LAS unsigned char* lds, const Gemm g, const Sched& S, const Epi& E) {
;     ...
;             PG8_WAIT_V(8); PG8_WAIT_L(0); PG8_BAR; PG8_MMA(0, 0, At, B0); PG8_MMA(0, 1, At, B1); PG8_BAR; PG8_SCHED;
;             PG8_LDA(At, 0, 1); PG8_STAGE(PG8_SB(0, 0), b2, voffB); PG8_STAGE(PG8_SB(0, 1), b2 + hstepB, voffB); PG8_STAGE(PG8_SA(0, 0), a2, voffA);
;             PG8_WAIT_V(8); PG8_WAIT_L(0); PG8_BAR; PG8_MMA(1, 0, At, B0); PG8_MMA(1, 1, At, B1); PG8_BAR; PG8_SCHED;
.Lzskip_6:
	s_waitcnt vmcnt(8)
	s_waitcnt lgkmcnt(0)
	s_barrier
	s_setprio 1
	s_waitcnt lgkmcnt(0)
	v_mfma_f32_16x16x32_bf16 v[116:119], v[148:151], v[180:183], v[116:119]
	v_mfma_f32_16x16x32_bf16 v[112:115], v[156:159], v[180:183], v[112:115]
	v_mfma_f32_16x16x32_bf16 v[108:111], v[148:151], v[192:195], v[108:111]
	v_mfma_f32_16x16x32_bf16 v[100:103], v[156:159], v[192:195], v[100:103]
	v_mfma_f32_16x16x32_bf16 v[92:95], v[148:151], v[200:203], v[92:95]
	v_mfma_f32_16x16x32_bf16 v[84:87], v[156:159], v[200:203], v[84:87]
	v_mfma_f32_16x16x32_bf16 v[76:79], v[148:151], v[208:211], v[76:79]
	v_mfma_f32_16x16x32_bf16 v[68:71], v[156:159], v[208:211], v[68:71]
	v_mfma_f32_16x16x32_bf16 v[116:119], v[152:155], v[184:187], v[116:119]
	v_mfma_f32_16x16x32_bf16 v[112:115], v[160:163], v[184:187], v[112:115]
	v_mfma_f32_16x16x32_bf16 v[108:111], v[152:155], v[196:199], v[108:111]
	v_mfma_f32_16x16x32_bf16 v[100:103], v[160:163], v[196:199], v[100:103]
	v_mfma_f32_16x16x32_bf16 v[92:95], v[152:155], v[204:207], v[92:95]
	v_mfma_f32_16x16x32_bf16 v[84:87], v[160:163], v[204:207], v[84:87]
	v_mfma_f32_16x16x32_bf16 v[76:79], v[152:155], v[212:215], v[76:79]
	v_mfma_f32_16x16x32_bf16 v[68:71], v[160:163], v[212:215], v[68:71]
	s_setprio 0
	s_setprio 1
	v_mfma_f32_16x16x32_bf16 v[124:127], v[164:167], v[180:183], v[124:127]
	v_mfma_f32_16x16x32_bf16 v[120:123], v[172:175], v[180:183], v[120:123]
	v_mfma_f32_16x16x32_bf16 v[104:107], v[164:167], v[192:195], v[104:107]
	v_mfma_f32_16x16x32_bf16 v[96:99], v[172:175], v[192:195], v[96:99]
	v_mfma_f32_16x16x32_bf16 v[88:91], v[164:167], v[200:203], v[88:91]
	v_mfma_f32_16x16x32_bf16 v[80:83], v[172:175], v[200:203], v[80:83]
	v_mfma_f32_16x16x32_bf16 v[72:75], v[164:167], v[208:211], v[72:75]
	v_mfma_f32_16x16x32_bf16 v[64:67], v[172:175], v[208:211], v[64:67]
	v_mfma_f32_16x16x32_bf16 v[124:127], v[168:171], v[184:187], v[124:127]
	v_mfma_f32_16x16x32_bf16 v[120:123], v[176:179], v[184:187], v[120:123]
	v_mfma_f32_16x16x32_bf16 v[104:107], v[168:171], v[196:199], v[104:107]
	v_mfma_f32_16x16x32_bf16 v[96:99], v[176:179], v[196:199], v[96:99]
	v_mfma_f32_16x16x32_bf16 v[88:91], v[168:171], v[204:207], v[88:91]
	v_mfma_f32_16x16x32_bf16 v[80:83], v[176:179], v[204:207], v[80:83]
	v_mfma_f32_16x16x32_bf16 v[72:75], v[168:171], v[212:215], v[72:75]
	v_mfma_f32_16x16x32_bf16 v[64:67], v[176:179], v[212:215], v[64:67]
	s_setprio 0
	s_barrier
	v_lshl_add_u64 v[216:217], s[84:85], 0, v[190:191]
	s_add_i32 s84, s74, s14
	s_mov_b32 m0, s84
	ds_read_b128 v[180:183], v143 offset:16384
	ds_read_b128 v[184:187], v143 offset:17408
	ds_read_b128 v[192:195], v143 offset:18432
	ds_read_b128 v[196:199], v143 offset:19456
	ds_read_b128 v[200:203], v143 offset:20480
	ds_read_b128 v[204:207], v143 offset:21504
	ds_read_b128 v[208:211], v143 offset:22528
	ds_read_b128 v[212:215], v143 offset:23552
	global_load_lds_dwordx4 v[216:217], off
	v_lshl_add_u64 v[220:221], v[216:217], 0, s[6:7]
	s_add_i32 m0, s84, 0x2000
	s_add_i32 s84, s75, s14
	global_load_lds_dwordx4 v[220:221], off
	v_lshl_add_u64 v[220:221], v[216:217], 0, s[8:9]
	s_mov_b32 m0, s84
	s_nop 0
	global_load_lds_dwordx4 v[220:221], off
	v_lshl_add_u64 v[220:221], v[216:217], 0, s[10:11]
	s_add_i32 m0, s84, 0x2000
	s_nop 0
	global_load_lds_dwordx4 v[220:221], off
	v_lshl_add_u64 v[220:221], s[78:79], 0, v[190:191]
	s_mov_b32 m0, s18
	v_lshl_add_u64 v[222:223], v[220:221], 0, s[6:7]
	global_load_lds_dwordx4 v[220:221], off
	s_mov_b32 m0, s19
	s_nop 0
	global_load_lds_dwordx4 v[222:223], off
	s_waitcnt vmcnt(8)
	s_waitcnt lgkmcnt(0)
	s_barrier
	s_setprio 1
	s_waitcnt lgkmcnt(0)
	v_mfma_f32_16x16x32_bf16 v[60:63], v[148:151], v[180:183], v[60:63]
	v_mfma_f32_16x16x32_bf16 v[52:55], v[156:159], v[180:183], v[52:55]
	v_mfma_f32_16x16x32_bf16 v[44:47], v[148:151], v[192:195], v[44:47]
	v_mfma_f32_16x16x32_bf16 v[36:39], v[156:159], v[192:195], v[36:39]
	v_mfma_f32_16x16x32_bf16 v[28:31], v[148:151], v[200:203], v[28:31]
	v_mfma_f32_16x16x32_bf16 v[20:23], v[156:159], v[200:203], v[20:23]
	v_mfma_f32_16x16x32_bf16 v[12:15], v[148:151], v[208:211], v[12:15]
	v_mfma_f32_16x16x32_bf16 v[4:7], v[156:159], v[208:211], v[4:7]
	v_mfma_f32_16x16x32_bf16 v[60:63], v[152:155], v[184:187], v[60:63]
	v_mfma_f32_16x16x32_bf16 v[52:55], v[160:163], v[184:187], v[52:55]
	v_mfma_f32_16x16x32_bf16 v[44:47], v[152:155], v[196:199], v[44:47]
	v_mfma_f32_16x16x32_bf16 v[36:39], v[160:163], v[196:199], v[36:39]
	v_mfma_f32_16x16x32_bf16 v[28:31], v[152:155], v[204:207], v[28:31]
	v_mfma_f32_16x16x32_bf16 v[20:23], v[160:163], v[204:207], v[20:23]
	v_mfma_f32_16x16x32_bf16 v[12:15], v[152:155], v[212:215], v[12:15]
	v_mfma_f32_16x16x32_bf16 v[4:7], v[160:163], v[212:215], v[4:7]
	s_setprio 0
	s_setprio 1
	v_mfma_f32_16x16x32_bf16 v[56:59], v[164:167], v[180:183], v[56:59]
	v_mfma_f32_16x16x32_bf16 v[48:51], v[172:175], v[180:183], v[48:51]
	v_mfma_f32_16x16x32_bf16 v[40:43], v[164:167], v[192:195], v[40:43]
	v_mfma_f32_16x16x32_bf16 v[32:35], v[172:175], v[192:195], v[32:35]
	v_mfma_f32_16x16x32_bf16 v[24:27], v[164:167], v[200:203], v[24:27]
	v_mfma_f32_16x16x32_bf16 v[16:19], v[172:175], v[200:203], v[16:19]
	v_mfma_f32_16x16x32_bf16 v[8:11], v[164:167], v[208:211], v[8:11]
	v_mfma_f32_16x16x32_bf16 v[0:3], v[172:175], v[208:211], v[0:3]
	v_mfma_f32_16x16x32_bf16 v[56:59], v[168:171], v[184:187], v[56:59]
	v_mfma_f32_16x16x32_bf16 v[48:51], v[176:179], v[184:187], v[48:51]
	v_mfma_f32_16x16x32_bf16 v[40:43], v[168:171], v[196:199], v[40:43]
	v_mfma_f32_16x16x32_bf16 v[32:35], v[176:179], v[196:199], v[32:35]
	v_mfma_f32_16x16x32_bf16 v[24:27], v[168:171], v[204:207], v[24:27]
	v_mfma_f32_16x16x32_bf16 v[16:19], v[176:179], v[204:207], v[16:19]
	v_mfma_f32_16x16x32_bf16 v[8:11], v[168:171], v[212:215], v[8:11]
	v_mfma_f32_16x16x32_bf16 v[0:3], v[176:179], v[212:215], v[0:3]
	s_setprio 0
	s_barrier
; #define PG8_STAGE(bufoff, gbase, voff) do { _Pragma("unroll") for (int _i = 0; _i < 2; ++_i) \
;         __builtin_amdgcn_global_load_lds((const unsigned*)((const char*)(gbase) + (voff)[_i]), (PG8_LAS unsigned*)(lds + (bufoff) + ldsw + _i * 8192), 16, 0, 0); } while (0)
; #define PG8_LDA(dst, b, h) do { _Pragma("unroll") for (int m = 0; m < 4; ++m) _Pragma("unroll") for (int k = 0; k < 2; ++k) dst[m][k] = *(const PG8_LAS bf16x8*)(lds + PG8_SA(b, h) + aoff + m * 2048 + k * 1024); } while (0)
; #define PG8_LDB(dst, b, h) do { _Pragma("unroll") for (int n = 0; n < 2; ++n) _Pragma("unroll") for (int k = 0; k < 2; ++k) dst[n][k] = *(const PG8_LAS bf16x8*)(lds + PG8_SB(b, h) + boff + n * 2048 + k * 1024); } while (0)
; #define PG8_MMA(ai, bj, At, Bt) do { __builtin_amdgcn_s_setprio(1); _Pragma("unroll") for (int m = 0; m < 4; ++m) _Pragma("unroll") for (int n = 0; n < 2; ++n) _Pragma("unroll") for (int k = 0; k < 2; ++k) \
;         acc[ai][bj][m][n] = __builtin_amdgcn_mfma_f32_16x16x32_bf16(Bt[n][k], At[m][k], acc[ai][bj][m][n], 0, 0, 0); __builtin_amdgcn_s_setprio(0); } while (0)
; #define PG8_WAIT_V(n) asm volatile("s_waitcnt vmcnt(" #n ")" ::: "memory")
; #define PG8_WAIT_L(n) asm volatile("s_waitcnt lgkmcnt(" #n ")" ::: "memory")
; #define PG8_BAR __builtin_amdgcn_s_barrier()
; #define PG8_SCHED __builtin_amdgcn_sched_barrier(0)
; template <class Epi, class Sched, bool ALIGN_EPI = false, bool SP2 = false>
; __device__ __forceinline__ void gemm_phase(PG8_LAS unsigned char* lds, const Gemm g, const Sched& S, const Epi& E) {
;     ...
;             PG8_LDB(B0, 1, 0); PG8_LDB(B1, 1, 1); PG8_SCHED; PG8_LDA(At, 1, 0); PG8_STAGE(PG8_SA(0, 1), a2 + hstepA, voffA);
;             PG8_WAIT_V(8); PG8_WAIT_L(0); PG8_BAR; PG8_MMA(0, 0, At, B0); PG8_MMA(0, 1, At, B1); PG8_BAR; PG8_SCHED;
;             PG8_LDA(At, 1, 1); PG8_STAGE(PG8_SB(1, 0), b3, voffB); PG8_STAGE(PG8_SB(1, 1), b3 + hstepB, voffB); PG8_STAGE(PG8_SA(1, 0), a3, voffA);
;             PG8_WAIT_V(8); PG8_WAIT_L(0); PG8_BAR; PG8_MMA(1, 0, At, B0); PG8_MMA(1, 1, At, B1); PG8_BAR; PG8_SCHED;
	ds_read_b128 v[148:151], v144
	ds_read_b128 v[152:155], v144 offset:1024
	ds_read_b128 v[156:159], v144 offset:2048
	ds_read_b128 v[160:163], v144 offset:3072
	ds_read_b128 v[164:167], v145
	ds_read_b128 v[168:171], v145 offset:1024
	ds_read_b128 v[172:175], v145 offset:2048
	ds_read_b128 v[176:179], v145 offset:3072
	s_mov_b32 m0, s66
	v_lshl_add_u64 v[222:223], v[220:221], 0, s[8:9]
	ds_read_b128 v[180:183], v143 offset:32768
	ds_read_b128 v[184:187], v143 offset:33792
	ds_read_b128 v[192:195], v143 offset:34816
	ds_read_b128 v[196:199], v143 offset:35840
	ds_read_b128 v[200:203], v143 offset:36864
	ds_read_b128 v[204:207], v143 offset:37888
	ds_read_b128 v[208:211], v143 offset:38912
	ds_read_b128 v[212:215], v143 offset:39936
	global_load_lds_dwordx4 v[222:223], off
	v_lshl_add_u64 v[222:223], v[220:221], 0, s[10:11]
	s_mov_b32 m0, s67
	s_nop 0
	global_load_lds_dwordx4 v[222:223], off
	s_waitcnt vmcnt(8)
	s_waitcnt lgkmcnt(0)
	s_barrier
	s_setprio 1
	s_waitcnt lgkmcnt(0)
	v_mfma_f32_16x16x32_bf16 v[116:119], v[148:151], v[180:183], v[116:119]
	v_mfma_f32_16x16x32_bf16 v[112:115], v[156:159], v[180:183], v[112:115]
	v_mfma_f32_16x16x32_bf16 v[108:111], v[148:151], v[192:195], v[108:111]
	v_mfma_f32_16x16x32_bf16 v[100:103], v[156:159], v[192:195], v[100:103]
	v_mfma_f32_16x16x32_bf16 v[92:95], v[148:151], v[200:203], v[92:95]
	v_mfma_f32_16x16x32_bf16 v[84:87], v[156:159], v[200:203], v[84:87]
	v_mfma_f32_16x16x32_bf16 v[76:79], v[148:151], v[208:211], v[76:79]
	v_mfma_f32_16x16x32_bf16 v[68:71], v[156:159], v[208:211], v[68:71]
	v_mfma_f32_16x16x32_bf16 v[116:119], v[152:155], v[184:187], v[116:119]
	v_mfma_f32_16x16x32_bf16 v[112:115], v[160:163], v[184:187], v[112:115]
	v_mfma_f32_16x16x32_bf16 v[108:111], v[152:155], v[196:199], v[108:111]
	v_mfma_f32_16x16x32_bf16 v[100:103], v[160:163], v[196:199], v[100:103]
	v_mfma_f32_16x16x32_bf16 v[92:95], v[152:155], v[204:207], v[92:95]
	v_mfma_f32_16x16x32_bf16 v[84:87], v[160:163], v[204:207], v[84:87]
	v_mfma_f32_16x16x32_bf16 v[76:79], v[152:155], v[212:215], v[76:79]
	v_mfma_f32_16x16x32_bf16 v[68:71], v[160:163], v[212:215], v[68:71]
	s_setprio 0
	s_setprio 1
	v_mfma_f32_16x16x32_bf16 v[124:127], v[164:167], v[180:183], v[124:127]
	v_mfma_f32_16x16x32_bf16 v[120:123], v[172:175], v[180:183], v[120:123]
	v_mfma_f32_16x16x32_bf16 v[104:107], v[164:167], v[192:195], v[104:107]
	v_mfma_f32_16x16x32_bf16 v[96:99], v[172:175], v[192:195], v[96:99]
	v_mfma_f32_16x16x32_bf16 v[88:91], v[164:167], v[200:203], v[88:91]
	v_mfma_f32_16x16x32_bf16 v[80:83], v[172:175], v[200:203], v[80:83]
	v_mfma_f32_16x16x32_bf16 v[72:75], v[164:167], v[208:211], v[72:75]
	v_mfma_f32_16x16x32_bf16 v[64:67], v[172:175], v[208:211], v[64:67]
	v_mfma_f32_16x16x32_bf16 v[124:127], v[168:171], v[184:187], v[124:127]
	v_mfma_f32_16x16x32_bf16 v[120:123], v[176:179], v[184:187], v[120:123]
	v_mfma_f32_16x16x32_bf16 v[104:107], v[168:171], v[196:199], v[104:107]
	v_mfma_f32_16x16x32_bf16 v[96:99], v[176:179], v[196:199], v[96:99]
	v_mfma_f32_16x16x32_bf16 v[88:91], v[168:171], v[204:207], v[88:91]
	v_mfma_f32_16x16x32_bf16 v[80:83], v[176:179], v[204:207], v[80:83]
	v_mfma_f32_16x16x32_bf16 v[72:75], v[168:171], v[212:215], v[72:75]
	v_mfma_f32_16x16x32_bf16 v[64:67], v[176:179], v[212:215], v[64:67]
	s_setprio 0
	s_barrier
	s_add_i32 s78, s76, s14
	v_lshl_add_u64 v[222:223], v[216:217], 0, s[34:35]
	s_mov_b32 m0, s78
	ds_read_b128 v[180:183], v143 offset:49152
	ds_read_b128 v[184:187], v143 offset:50176
	ds_read_b128 v[192:195], v143 offset:51200
	ds_read_b128 v[196:199], v143 offset:52224
	ds_read_b128 v[200:203], v143 offset:53248
	ds_read_b128 v[204:207], v143 offset:54272
	ds_read_b128 v[208:211], v143 offset:55296
	ds_read_b128 v[212:215], v143 offset:56320
	global_load_lds_dwordx4 v[222:223], off
	v_lshl_add_u64 v[222:223], v[216:217], 0, s[36:37]
	s_add_i32 m0, s78, 0x2000
	s_add_i32 s78, s77, s14
	global_load_lds_dwordx4 v[222:223], off
	v_lshl_add_u64 v[222:223], v[216:217], 0, s[38:39]
	s_mov_b32 m0, s78
	v_lshl_add_u64 v[216:217], v[216:217], 0, s[40:41]
	global_load_lds_dwordx4 v[222:223], off
	s_add_i32 m0, s78, 0x2000
	s_nop 0
	global_load_lds_dwordx4 v[216:217], off
	v_lshl_add_u64 v[216:217], v[220:221], 0, s[34:35]
	s_mov_b32 m0, s68
	s_nop 0
	global_load_lds_dwordx4 v[216:217], off
	v_lshl_add_u64 v[216:217], v[220:221], 0, s[36:37]
	s_mov_b32 m0, s69
	s_nop 0
	global_load_lds_dwordx4 v[216:217], off
	s_waitcnt vmcnt(8)
	s_waitcnt lgkmcnt(0)
	s_barrier
	s_setprio 1
	s_waitcnt lgkmcnt(0)
	v_mfma_f32_16x16x32_bf16 v[60:63], v[148:151], v[180:183], v[60:63]
	v_mfma_f32_16x16x32_bf16 v[52:55], v[156:159], v[180:183], v[52:55]
	v_mfma_f32_16x16x32_bf16 v[44:47], v[148:151], v[192:195], v[44:47]
	v_mfma_f32_16x16x32_bf16 v[36:39], v[156:159], v[192:195], v[36:39]
	v_mfma_f32_16x16x32_bf16 v[28:31], v[148:151], v[200:203], v[28:31]
	v_mfma_f32_16x16x32_bf16 v[20:23], v[156:159], v[200:203], v[20:23]
	v_mfma_f32_16x16x32_bf16 v[12:15], v[148:151], v[208:211], v[12:15]
	v_mfma_f32_16x16x32_bf16 v[4:7], v[156:159], v[208:211], v[4:7]
	v_mfma_f32_16x16x32_bf16 v[60:63], v[152:155], v[184:187], v[60:63]
	v_mfma_f32_16x16x32_bf16 v[52:55], v[160:163], v[184:187], v[52:55]
	v_mfma_f32_16x16x32_bf16 v[44:47], v[152:155], v[196:199], v[44:47]
	v_mfma_f32_16x16x32_bf16 v[36:39], v[160:163], v[196:199], v[36:39]
	v_mfma_f32_16x16x32_bf16 v[28:31], v[152:155], v[204:207], v[28:31]
	v_mfma_f32_16x16x32_bf16 v[20:23], v[160:163], v[204:207], v[20:23]
	v_mfma_f32_16x16x32_bf16 v[12:15], v[152:155], v[212:215], v[12:15]
	v_mfma_f32_16x16x32_bf16 v[4:7], v[160:163], v[212:215], v[4:7]
	s_setprio 0
	s_setprio 1
	v_mfma_f32_16x16x32_bf16 v[56:59], v[164:167], v[180:183], v[56:59]
	v_mfma_f32_16x16x32_bf16 v[48:51], v[172:175], v[180:183], v[48:51]
	v_mfma_f32_16x16x32_bf16 v[40:43], v[164:167], v[192:195], v[40:43]
	v_mfma_f32_16x16x32_bf16 v[32:35], v[172:175], v[192:195], v[32:35]
	v_mfma_f32_16x16x32_bf16 v[24:27], v[164:167], v[200:203], v[24:27]
	v_mfma_f32_16x16x32_bf16 v[16:19], v[172:175], v[200:203], v[16:19]
	v_mfma_f32_16x16x32_bf16 v[8:11], v[164:167], v[208:211], v[8:11]
	v_mfma_f32_16x16x32_bf16 v[0:3], v[172:175], v[208:211], v[0:3]
	v_mfma_f32_16x16x32_bf16 v[56:59], v[168:171], v[184:187], v[56:59]
	v_mfma_f32_16x16x32_bf16 v[48:51], v[176:179], v[184:187], v[48:51]
	v_mfma_f32_16x16x32_bf16 v[40:43], v[168:171], v[196:199], v[40:43]
	v_mfma_f32_16x16x32_bf16 v[32:35], v[176:179], v[196:199], v[32:35]
	v_mfma_f32_16x16x32_bf16 v[24:27], v[168:171], v[204:207], v[24:27]
	v_mfma_f32_16x16x32_bf16 v[16:19], v[176:179], v[204:207], v[16:19]
	v_mfma_f32_16x16x32_bf16 v[8:11], v[168:171], v[212:215], v[8:11]
	v_mfma_f32_16x16x32_bf16 v[0:3], v[176:179], v[212:215], v[0:3]
	s_setprio 0
	s_barrier
	s_add_i32 s82, s82, 2
	s_add_u32 s62, s62, 0x10000
	s_addc_u32 s63, s63, 0
	s_add_u32 s64, s64, 0x10000
	s_addc_u32 s65, s65, 0
	s_cmp_gt_u32 s82, 13
	s_cbranch_scc0 .LBB0_838
	s_and_b64 vcc, exec, s[44:45]
	s_cbranch_vccz .LBB0_841
	s_barrier

; #define PG8_STAGE(bufoff, gbase, voff) do { _Pragma("unroll") for (int _i = 0; _i < 2; ++_i) \
;         __builtin_amdgcn_global_load_lds((const unsigned*)((const char*)(gbase) + (voff)[_i]), (PG8_LAS unsigned*)(lds + (bufoff) + ldsw + _i * 8192), 16, 0, 0); } while (0)
; #define PG8_LDA(dst, b, h) do { _Pragma("unroll") for (int m = 0; m < 4; ++m) _Pragma("unroll") for (int k = 0; k < 2; ++k) dst[m][k] = *(const PG8_LAS bf16x8*)(lds + PG8_SA(b, h) + aoff + m * 2048 + k * 1024); } while (0)
; #define PG8_LDB(dst, b, h) do { _Pragma("unroll") for (int n = 0; n < 2; ++n) _Pragma("unroll") for (int k = 0; k < 2; ++k) dst[n][k] = *(const PG8_LAS bf16x8*)(lds + PG8_SB(b, h) + boff + n * 2048 + k * 1024); } while (0)
; #define PG8_MMA(ai, bj, At, Bt) do { __builtin_amdgcn_s_setprio(1); _Pragma("unroll") for (int m = 0; m < 4; ++m) _Pragma("unroll") for (int n = 0; n < 2; ++n) _Pragma("unroll") for (int k = 0; k < 2; ++k) \
;         acc[ai][bj][m][n] = __builtin_amdgcn_mfma_f32_16x16x32_bf16(Bt[n][k], At[m][k], acc[ai][bj][m][n], 0, 0, 0); __builtin_amdgcn_s_setprio(0); } while (0)
; #define PG8_WAIT_V(n) asm volatile("s_waitcnt vmcnt(" #n ")" ::: "memory")
; template <class Epi, class Sched, bool ALIGN_EPI = false, bool SP2 = false>
; __device__ __forceinline__ void gemm_phase(PG8_LAS unsigned char* lds, const Gemm g, const Sched& S, const Epi& E) {
;     ...
;         for (int t = 0; t < nt; t += 2) {
;             const bool last = (t == nt - 2);
;             const char* a1 = cA + (size_t)(t + 1) * kstepA;
;             const char* a2 = last ? nA : cA + (size_t)(t + 2) * kstepA; const char* b2 = last ? nB : cB + (size_t)(t + 2) * kstep;
;             const char* a3 = a2 + kstepA; const char* b3 = b2 + kstep;
;             if (last && has_next) S.a_ready(nxt);
;             if constexpr (SP2) {
;             PG8_LDB(B0, 0, 0); PG8_LDB(B1, 0, 1); PG8_SCHED; PG8_LDA(At, 0, 0); PG8_STAGE(PG8_SA(1, 1), a1 + hstepA, voffA);
;             PG8_WAIT_V(8); PG8_WAIT_L(0); PG8_BAR; PG8_MMA(0, 0, At, B0); PG8_MMA(0, 1, At, B1); PG8_BAR; PG8_SCHED;
;     ...
; #pragma unroll
;         for (int a = 0; a < 2; ++a)
; #pragma unroll
;             for (int b = 0; b < 2; ++b)
; #pragma unroll
;                 for (int m = 0; m < 4; ++m)
; #pragma unroll
;                     for (int n = 0; n < 2; ++n) acc[a][b][m][n] = (f32x4){0.f, 0.f, 0.f, 0.f};
;         cur = nxt; cA = nA; cB = nB; ++ui;
.LBB0_923:
	s_add_u32 s6, s6, 0x10000
	s_addc_u32 s7, s7, 0
	s_add_u32 s64, s64, 0x10000
	s_addc_u32 s65, s65, 0
	s_mov_b32 s66, -2
	s_waitcnt lgkmcnt(0)
.LBB0_924:
	ds_read_b128 v[84:87], v221
	ds_read_b128 v[92:95], v221 offset:1024
	ds_read_b128 v[104:107], v221 offset:2048
	ds_read_b128 v[116:119], v221 offset:3072
	ds_read_b128 v[128:131], v222
	ds_read_b128 v[140:143], v222 offset:1024
	ds_read_b128 v[152:155], v222 offset:2048
	ds_read_b128 v[156:159], v222 offset:3072
	s_cmp_eq_u32 s66, 40
	s_cselect_b32 s69, s1, s7
	s_cselect_b32 s68, s0, s6
	s_cselect_b32 s71, s63, s65
	s_cselect_b32 s70, s62, s64
	v_lshl_add_u64 v[216:217], s[6:7], 0, v[190:191]
	v_lshl_add_u64 v[228:229], v[216:217], 0, s[58:59]
	s_add_i32 m0, s15, 0xc000
	ds_read_b128 v[160:163], v223
	ds_read_b128 v[164:167], v223 offset:1024
	ds_read_b128 v[168:171], v223 offset:2048
	ds_read_b128 v[172:175], v223 offset:3072
	ds_read_b128 v[176:179], v223 offset:4096
	ds_read_b128 v[180:183], v223 offset:5120
	ds_read_b128 v[184:187], v223 offset:6144
	ds_read_b128 v[212:215], v223 offset:7168
	global_load_lds_dwordx4 v[228:229], off
	v_lshl_add_u64 v[216:217], v[216:217], 0, s[60:61]
	s_add_i32 m0, s15, 0xe000
	s_nop 0
	global_load_lds_dwordx4 v[216:217], off
	s_cmp_lg_u32 s66, -2
	s_cbranch_scc1 .Lzskip_7
	v_mov_b32_e32 v0, 0
	v_mov_b32_e32 v1, 0
	v_mov_b32_e32 v2, 0
	v_mov_b32_e32 v3, 0
	v_mov_b32_e32 v4, 0
	v_mov_b32_e32 v5, 0
	v_mov_b32_e32 v6, 0
	v_mov_b32_e32 v7, 0
	v_mov_b32_e32 v8, 0
	v_mov_b32_e32 v9, 0
	v_mov_b32_e32 v10, 0
	v_mov_b32_e32 v11, 0
	v_mov_b32_e32 v12, 0
	v_mov_b32_e32 v13, 0
	v_mov_b32_e32 v14, 0
	v_mov_b32_e32 v15, 0
	v_mov_b32_e32 v16, 0
	v_mov_b32_e32 v17, 0
	v_mov_b32_e32 v18, 0
	v_mov_b32_e32 v19, 0
	v_mov_b32_e32 v20, 0
	v_mov_b32_e32 v21, 0
	v_mov_b32_e32 v22, 0
	v_mov_b32_e32 v23, 0
	v_mov_b32_e32 v24, 0
	v_mov_b32_e32 v25, 0
	v_mov_b32_e32 v26, 0
	v_mov_b32_e32 v27, 0
	v_mov_b32_e32 v28, 0
	v_mov_b32_e32 v29, 0
	v_mov_b32_e32 v30, 0
	v_mov_b32_e32 v31, 0
	v_mov_b32_e32 v32, 0
	v_mov_b32_e32 v33, 0
	v_mov_b32_e32 v34, 0
	v_mov_b32_e32 v35, 0
	v_mov_b32_e32 v36, 0
	v_mov_b32_e32 v37, 0
	v_mov_b32_e32 v38, 0
	v_mov_b32_e32 v39, 0
	v_mov_b32_e32 v40, 0
	v_mov_b32_e32 v41, 0
	v_mov_b32_e32 v42, 0
	v_mov_b32_e32 v43, 0
	v_mov_b32_e32 v44, 0
	v_mov_b32_e32 v45, 0
	v_mov_b32_e32 v46, 0
	v_mov_b32_e32 v47, 0
	v_mov_b32_e32 v48, 0
	v_mov_b32_e32 v49, 0
	v_mov_b32_e32 v50, 0
	v_mov_b32_e32 v51, 0
	v_mov_b32_e32 v52, 0
	v_mov_b32_e32 v53, 0
	v_mov_b32_e32 v54, 0
	v_mov_b32_e32 v55, 0
	v_mov_b32_e32 v56, 0
	v_mov_b32_e32 v57, 0
	v_mov_b32_e32 v58, 0
	v_mov_b32_e32 v59, 0
	v_mov_b32_e32 v60, 0
	v_mov_b32_e32 v61, 0
	v_mov_b32_e32 v62, 0
	v_mov_b32_e32 v63, 0
	v_mov_b32_e32 v64, 0
	v_mov_b32_e32 v65, 0
	v_mov_b32_e32 v66, 0
	v_mov_b32_e32 v67, 0
	v_mov_b32_e32 v68, 0
	v_mov_b32_e32 v69, 0
	v_mov_b32_e32 v70, 0
	v_mov_b32_e32 v71, 0
	v_mov_b32_e32 v72, 0
	v_mov_b32_e32 v73, 0
	v_mov_b32_e32 v74, 0
	v_mov_b32_e32 v75, 0
	v_mov_b32_e32 v76, 0
	v_mov_b32_e32 v77, 0
	v_mov_b32_e32 v78, 0
	v_mov_b32_e32 v79, 0
	v_mov_b32_e32 v80, 0
	v_mov_b32_e32 v81, 0
	v_mov_b32_e32 v82, 0
	v_mov_b32_e32 v83, 0
	v_mov_b32_e32 v88, 0
	v_mov_b32_e32 v89, 0
	v_mov_b32_e32 v90, 0
	v_mov_b32_e32 v91, 0
	v_mov_b32_e32 v96, 0
	v_mov_b32_e32 v97, 0
	v_mov_b32_e32 v98, 0
	v_mov_b32_e32 v99, 0
	v_mov_b32_e32 v100, 0
	v_mov_b32_e32 v101, 0
	v_mov_b32_e32 v102, 0
	v_mov_b32_e32 v103, 0
	v_mov_b32_e32 v108, 0
	v_mov_b32_e32 v109, 0
	v_mov_b32_e32 v110, 0
	v_mov_b32_e32 v111, 0
	v_mov_b32_e32 v112, 0
	v_mov_b32_e32 v113, 0
	v_mov_b32_e32 v114, 0
	v_mov_b32_e32 v115, 0
	v_mov_b32_e32 v120, 0
	v_mov_b32_e32 v121, 0
	v_mov_b32_e32 v122, 0
	v_mov_b32_e32 v123, 0
	v_mov_b32_e32 v124, 0
	v_mov_b32_e32 v125, 0
	v_mov_b32_e32 v126, 0
	v_mov_b32_e32 v127, 0
	v_mov_b32_e32 v132, 0
	v_mov_b32_e32 v133, 0
	v_mov_b32_e32 v134, 0
	v_mov_b32_e32 v135, 0
	v_mov_b32_e32 v136, 0
	v_mov_b32_e32 v137, 0
	v_mov_b32_e32 v138, 0
	v_mov_b32_e32 v139, 0
	v_mov_b32_e32 v144, 0
	v_mov_b32_e32 v145, 0
	v_mov_b32_e32 v146, 0
	v_mov_b32_e32 v147, 0
	v_mov_b32_e32 v148, 0
	v_mov_b32_e32 v149, 0
	v_mov_b32_e32 v150, 0
	v_mov_b32_e32 v151, 0
.Lzskip_7:
	s_waitcnt vmcnt(8)
	s_waitcnt lgkmcnt(0)
	s_barrier
	s_setprio 1
	s_waitcnt lgkmcnt(0)
	v_mfma_f32_16x16x32_bf16 v[148:151], v[84:87], v[160:163], v[148:151]
	v_mfma_f32_16x16x32_bf16 v[144:147], v[104:107], v[160:163], v[144:147]
	v_mfma_f32_16x16x32_bf16 v[124:127], v[84:87], v[168:171], v[124:127]
	v_mfma_f32_16x16x32_bf16 v[120:123], v[104:107], v[168:171], v[120:123]
	v_mfma_f32_16x16x32_bf16 v[100:103], v[84:87], v[176:179], v[100:103]
	v_mfma_f32_16x16x32_bf16 v[96:99], v[104:107], v[176:179], v[96:99]
	v_mfma_f32_16x16x32_bf16 v[76:79], v[84:87], v[184:187], v[76:79]
	v_mfma_f32_16x16x32_bf16 v[72:75], v[104:107], v[184:187], v[72:75]
	v_mfma_f32_16x16x32_bf16 v[148:151], v[92:95], v[164:167], v[148:151]
	v_mfma_f32_16x16x32_bf16 v[144:147], v[116:119], v[164:167], v[144:147]
	v_mfma_f32_16x16x32_bf16 v[124:127], v[92:95], v[172:175], v[124:127]
	v_mfma_f32_16x16x32_bf16 v[120:123], v[116:119], v[172:175], v[120:123]
	v_mfma_f32_16x16x32_bf16 v[100:103], v[92:95], v[180:183], v[100:103]
	v_mfma_f32_16x16x32_bf16 v[96:99], v[116:119], v[180:183], v[96:99]
	v_mfma_f32_16x16x32_bf16 v[76:79], v[92:95], v[212:215], v[76:79]
	v_mfma_f32_16x16x32_bf16 v[72:75], v[116:119], v[212:215], v[72:75]
	s_setprio 0
	s_setprio 1
	v_mfma_f32_16x16x32_bf16 v[136:139], v[128:131], v[160:163], v[136:139]
	v_mfma_f32_16x16x32_bf16 v[132:135], v[152:155], v[160:163], v[132:135]
	v_mfma_f32_16x16x32_bf16 v[112:115], v[128:131], v[168:171], v[112:115]
	v_mfma_f32_16x16x32_bf16 v[108:111], v[152:155], v[168:171], v[108:111]
	v_mfma_f32_16x16x32_bf16 v[88:91], v[128:131], v[176:179], v[88:91]
	v_mfma_f32_16x16x32_bf16 v[80:83], v[152:155], v[176:179], v[80:83]
	v_mfma_f32_16x16x32_bf16 v[68:71], v[128:131], v[184:187], v[68:71]
	v_mfma_f32_16x16x32_bf16 v[64:67], v[152:155], v[184:187], v[64:67]
	v_mfma_f32_16x16x32_bf16 v[136:139], v[140:143], v[164:167], v[136:139]
	v_mfma_f32_16x16x32_bf16 v[132:135], v[156:159], v[164:167], v[132:135]
	v_mfma_f32_16x16x32_bf16 v[112:115], v[140:143], v[172:175], v[112:115]
	v_mfma_f32_16x16x32_bf16 v[108:111], v[156:159], v[172:175], v[108:111]
	v_mfma_f32_16x16x32_bf16 v[88:91], v[140:143], v[180:183], v[88:91]
	v_mfma_f32_16x16x32_bf16 v[80:83], v[156:159], v[180:183], v[80:83]
	v_mfma_f32_16x16x32_bf16 v[68:71], v[140:143], v[212:215], v[68:71]
	v_mfma_f32_16x16x32_bf16 v[64:67], v[156:159], v[212:215], v[64:67]
	s_setprio 0
	s_barrier
; #define PG8_STAGE(bufoff, gbase, voff) do { _Pragma("unroll") for (int _i = 0; _i < 2; ++_i) \
;         __builtin_amdgcn_global_load_lds((const unsigned*)((const char*)(gbase) + (voff)[_i]), (PG8_LAS unsigned*)(lds + (bufoff) + ldsw + _i * 8192), 16, 0, 0); } while (0)
; #define PG8_LDA(dst, b, h) do { _Pragma("unroll") for (int m = 0; m < 4; ++m) _Pragma("unroll") for (int k = 0; k < 2; ++k) dst[m][k] = *(const PG8_LAS bf16x8*)(lds + PG8_SA(b, h) + aoff + m * 2048 + k * 1024); } while (0)
; #define PG8_LDB(dst, b, h) do { _Pragma("unroll") for (int n = 0; n < 2; ++n) _Pragma("unroll") for (int k = 0; k < 2; ++k) dst[n][k] = *(const PG8_LAS bf16x8*)(lds + PG8_SB(b, h) + boff + n * 2048 + k * 1024); } while (0)
; #define PG8_MMA(ai, bj, At, Bt) do { __builtin_amdgcn_s_setprio(1); _Pragma("unroll") for (int m = 0; m < 4; ++m) _Pragma("unroll") for (int n = 0; n < 2; ++n) _Pragma("unroll") for (int k = 0; k < 2; ++k) \
;         acc[ai][bj][m][n] = __builtin_amdgcn_mfma_f32_16x16x32_bf16(Bt[n][k], At[m][k], acc[ai][bj][m][n], 0, 0, 0); __builtin_amdgcn_s_setprio(0); } while (0)
; #define PG8_WAIT_V(n) asm volatile("s_waitcnt vmcnt(" #n ")" ::: "memory")
; #define PG8_WAIT_L(n) asm volatile("s_waitcnt lgkmcnt(" #n ")" ::: "memory")
; #define PG8_BAR __builtin_amdgcn_s_barrier()
; #define PG8_SCHED __builtin_amdgcn_sched_barrier(0)
; template <class Epi, class Sched, bool ALIGN_EPI = false, bool SP2 = false>
; __device__ __forceinline__ void gemm_phase(PG8_LAS unsigned char* lds, const Gemm g, const Sched& S, const Epi& E) {
;     ...
;             PG8_LDA(At, 0, 1); PG8_STAGE(PG8_SB(0, 0), b2, voffB); PG8_STAGE(PG8_SB(0, 1), b2 + hstepB, voffB); PG8_STAGE(PG8_SA(0, 0), a2, voffA);
;             PG8_WAIT_V(8); PG8_WAIT_L(0); PG8_BAR; PG8_MMA(1, 0, At, B0); PG8_MMA(1, 1, At, B1); PG8_BAR; PG8_SCHED;
;             PG8_LDB(B0, 1, 0); PG8_LDB(B1, 1, 1); PG8_SCHED; PG8_LDA(At, 1, 0); PG8_STAGE(PG8_SA(0, 1), a2 + hstepA, voffA);
;             PG8_WAIT_V(8); PG8_WAIT_L(0); PG8_BAR; PG8_MMA(0, 0, At, B0); PG8_MMA(0, 1, At, B1); PG8_BAR; PG8_SCHED;
	s_add_i32 s33, s81, s14
	v_lshl_add_u64 v[216:217], s[70:71], 0, v[190:191]
	s_mov_b32 m0, s33
	ds_read_b128 v[160:163], v223 offset:16384
	ds_read_b128 v[164:167], v223 offset:17408
	ds_read_b128 v[168:171], v223 offset:18432
	ds_read_b128 v[172:175], v223 offset:19456
	ds_read_b128 v[176:179], v223 offset:20480
	ds_read_b128 v[180:183], v223 offset:21504
	ds_read_b128 v[184:187], v223 offset:22528
	ds_read_b128 v[212:215], v223 offset:23552
	global_load_lds_dwordx4 v[216:217], off
	v_lshl_add_u64 v[228:229], v[216:217], 0, s[8:9]
	s_add_i32 m0, s33, 0x2000
	s_add_i32 s33, s82, s14
	global_load_lds_dwordx4 v[228:229], off
	v_lshl_add_u64 v[228:229], v[216:217], 0, s[10:11]
	s_mov_b32 m0, s33
	s_nop 0
	global_load_lds_dwordx4 v[228:229], off
	v_lshl_add_u64 v[228:229], v[216:217], 0, s[40:41]
	s_add_i32 m0, s33, 0x2000
	s_nop 0
	global_load_lds_dwordx4 v[228:229], off
	v_lshl_add_u64 v[228:229], s[68:69], 0, v[190:191]
	s_mov_b32 m0, s15
	v_lshl_add_u64 v[230:231], v[228:229], 0, s[8:9]
	global_load_lds_dwordx4 v[228:229], off
	s_mov_b32 m0, s17
	s_nop 0
	global_load_lds_dwordx4 v[230:231], off
	s_waitcnt vmcnt(8)
	s_waitcnt lgkmcnt(0)
	s_barrier
	s_setprio 1
	s_waitcnt lgkmcnt(0)
	v_mfma_f32_16x16x32_bf16 v[60:63], v[84:87], v[160:163], v[60:63]
	v_mfma_f32_16x16x32_bf16 v[56:59], v[104:107], v[160:163], v[56:59]
	v_mfma_f32_16x16x32_bf16 v[44:47], v[84:87], v[168:171], v[44:47]
	v_mfma_f32_16x16x32_bf16 v[40:43], v[104:107], v[168:171], v[40:43]
	v_mfma_f32_16x16x32_bf16 v[28:31], v[84:87], v[176:179], v[28:31]
	v_mfma_f32_16x16x32_bf16 v[24:27], v[104:107], v[176:179], v[24:27]
	v_mfma_f32_16x16x32_bf16 v[12:15], v[84:87], v[184:187], v[12:15]
	v_mfma_f32_16x16x32_bf16 v[8:11], v[104:107], v[184:187], v[8:11]
	v_mfma_f32_16x16x32_bf16 v[60:63], v[92:95], v[164:167], v[60:63]
	v_mfma_f32_16x16x32_bf16 v[56:59], v[116:119], v[164:167], v[56:59]
	v_mfma_f32_16x16x32_bf16 v[44:47], v[92:95], v[172:175], v[44:47]
	v_mfma_f32_16x16x32_bf16 v[40:43], v[116:119], v[172:175], v[40:43]
	v_mfma_f32_16x16x32_bf16 v[28:31], v[92:95], v[180:183], v[28:31]
	v_mfma_f32_16x16x32_bf16 v[24:27], v[116:119], v[180:183], v[24:27]
	v_mfma_f32_16x16x32_bf16 v[12:15], v[92:95], v[212:215], v[12:15]
	v_mfma_f32_16x16x32_bf16 v[8:11], v[116:119], v[212:215], v[8:11]
	s_setprio 0
	s_setprio 1
	v_mfma_f32_16x16x32_bf16 v[52:55], v[128:131], v[160:163], v[52:55]
	v_mfma_f32_16x16x32_bf16 v[48:51], v[152:155], v[160:163], v[48:51]
	v_mfma_f32_16x16x32_bf16 v[36:39], v[128:131], v[168:171], v[36:39]
	v_mfma_f32_16x16x32_bf16 v[32:35], v[152:155], v[168:171], v[32:35]
	v_mfma_f32_16x16x32_bf16 v[20:23], v[128:131], v[176:179], v[20:23]
	v_mfma_f32_16x16x32_bf16 v[16:19], v[152:155], v[176:179], v[16:19]
	v_mfma_f32_16x16x32_bf16 v[4:7], v[128:131], v[184:187], v[4:7]
	v_mfma_f32_16x16x32_bf16 v[0:3], v[152:155], v[184:187], v[0:3]
	v_mfma_f32_16x16x32_bf16 v[52:55], v[140:143], v[164:167], v[52:55]
	v_mfma_f32_16x16x32_bf16 v[48:51], v[156:159], v[164:167], v[48:51]
	v_mfma_f32_16x16x32_bf16 v[36:39], v[140:143], v[172:175], v[36:39]
	v_mfma_f32_16x16x32_bf16 v[32:35], v[156:159], v[172:175], v[32:35]
	v_mfma_f32_16x16x32_bf16 v[20:23], v[140:143], v[180:183], v[20:23]
	v_mfma_f32_16x16x32_bf16 v[16:19], v[156:159], v[180:183], v[16:19]
	v_mfma_f32_16x16x32_bf16 v[4:7], v[140:143], v[212:215], v[4:7]
	v_mfma_f32_16x16x32_bf16 v[0:3], v[156:159], v[212:215], v[0:3]
	s_setprio 0
	s_barrier
	ds_read_b128 v[84:87], v224
	ds_read_b128 v[92:95], v224 offset:1024
	ds_read_b128 v[104:107], v224 offset:2048
	ds_read_b128 v[116:119], v224 offset:3072
	ds_read_b128 v[128:131], v225
	ds_read_b128 v[140:143], v225 offset:1024
	ds_read_b128 v[152:155], v225 offset:2048
	ds_read_b128 v[156:159], v225 offset:3072
	s_mov_b32 m0, s18
	v_lshl_add_u64 v[230:231], v[228:229], 0, s[10:11]
	ds_read_b128 v[160:163], v223 offset:32768
	ds_read_b128 v[164:167], v223 offset:33792
	ds_read_b128 v[168:171], v223 offset:34816
	ds_read_b128 v[172:175], v223 offset:35840
	ds_read_b128 v[176:179], v223 offset:36864
	ds_read_b128 v[180:183], v223 offset:37888
	ds_read_b128 v[184:187], v223 offset:38912
	ds_read_b128 v[212:215], v223 offset:39936
	global_load_lds_dwordx4 v[230:231], off
	v_lshl_add_u64 v[230:231], v[228:229], 0, s[40:41]
	s_mov_b32 m0, s19
	s_nop 0
	global_load_lds_dwordx4 v[230:231], off
	s_waitcnt vmcnt(8)
	s_waitcnt lgkmcnt(0)
	s_barrier
; #define PG8_STAGE(bufoff, gbase, voff) do { _Pragma("unroll") for (int _i = 0; _i < 2; ++_i) \
;         __builtin_amdgcn_global_load_lds((const unsigned*)((const char*)(gbase) + (voff)[_i]), (PG8_LAS unsigned*)(lds + (bufoff) + ldsw + _i * 8192), 16, 0, 0); } while (0)
; #define PG8_LDA(dst, b, h) do { _Pragma("unroll") for (int m = 0; m < 4; ++m) _Pragma("unroll") for (int k = 0; k < 2; ++k) dst[m][k] = *(const PG8_LAS bf16x8*)(lds + PG8_SA(b, h) + aoff + m * 2048 + k * 1024); } while (0)
; #define PG8_LDB(dst, b, h) do { _Pragma("unroll") for (int n = 0; n < 2; ++n) _Pragma("unroll") for (int k = 0; k < 2; ++k) dst[n][k] = *(const PG8_LAS bf16x8*)(lds + PG8_SB(b, h) + boff + n * 2048 + k * 1024); } while (0)
; #define PG8_MMA(ai, bj, At, Bt) do { __builtin_amdgcn_s_setprio(1); _Pragma("unroll") for (int m = 0; m < 4; ++m) _Pragma("unroll") for (int n = 0; n < 2; ++n) _Pragma("unroll") for (int k = 0; k < 2; ++k) \
;         acc[ai][bj][m][n] = __builtin_amdgcn_mfma_f32_16x16x32_bf16(Bt[n][k], At[m][k], acc[ai][bj][m][n], 0, 0, 0); __builtin_amdgcn_s_setprio(0); } while (0)
; #define PG8_WAIT_V(n) asm volatile("s_waitcnt vmcnt(" #n ")" ::: "memory")
; #define PG8_WAIT_L(n) asm volatile("s_waitcnt lgkmcnt(" #n ")" ::: "memory")
; #define PG8_BAR __builtin_amdgcn_s_barrier()
; #define PG8_SCHED __builtin_amdgcn_sched_barrier(0)
; template <class Epi, class Sched, bool ALIGN_EPI = false, bool SP2 = false>
; __device__ __forceinline__ void gemm_phase(PG8_LAS unsigned char* lds, const Gemm g, const Sched& S, const Epi& E) {
;     ...
;             PG8_LDB(B0, 1, 0); PG8_LDB(B1, 1, 1); PG8_SCHED; PG8_LDA(At, 1, 0); PG8_STAGE(PG8_SA(0, 1), a2 + hstepA, voffA);
;             PG8_WAIT_V(8); PG8_WAIT_L(0); PG8_BAR; PG8_MMA(0, 0, At, B0); PG8_MMA(0, 1, At, B1); PG8_BAR; PG8_SCHED;
;             PG8_LDA(At, 1, 1); PG8_STAGE(PG8_SB(1, 0), b3, voffB); PG8_STAGE(PG8_SB(1, 1), b3 + hstepB, voffB); PG8_STAGE(PG8_SA(1, 0), a3, voffA);
;             PG8_WAIT_V(8); PG8_WAIT_L(0); PG8_BAR; PG8_MMA(1, 0, At, B0); PG8_MMA(1, 1, At, B1); PG8_BAR; PG8_SCHED;
;     ...
;         if constexpr (ALIGN_EPI) { if (wr == 0) PG8_BAR; }
	s_setprio 1
	s_waitcnt lgkmcnt(0)
	v_mfma_f32_16x16x32_bf16 v[148:151], v[84:87], v[160:163], v[148:151]
	v_mfma_f32_16x16x32_bf16 v[144:147], v[104:107], v[160:163], v[144:147]
	v_mfma_f32_16x16x32_bf16 v[124:127], v[84:87], v[168:171], v[124:127]
	v_mfma_f32_16x16x32_bf16 v[120:123], v[104:107], v[168:171], v[120:123]
	v_mfma_f32_16x16x32_bf16 v[100:103], v[84:87], v[176:179], v[100:103]
	v_mfma_f32_16x16x32_bf16 v[96:99], v[104:107], v[176:179], v[96:99]
	v_mfma_f32_16x16x32_bf16 v[76:79], v[84:87], v[184:187], v[76:79]
	v_mfma_f32_16x16x32_bf16 v[72:75], v[104:107], v[184:187], v[72:75]
	v_mfma_f32_16x16x32_bf16 v[148:151], v[92:95], v[164:167], v[148:151]
	v_mfma_f32_16x16x32_bf16 v[144:147], v[116:119], v[164:167], v[144:147]
	v_mfma_f32_16x16x32_bf16 v[124:127], v[92:95], v[172:175], v[124:127]
	v_mfma_f32_16x16x32_bf16 v[120:123], v[116:119], v[172:175], v[120:123]
	v_mfma_f32_16x16x32_bf16 v[100:103], v[92:95], v[180:183], v[100:103]
	v_mfma_f32_16x16x32_bf16 v[96:99], v[116:119], v[180:183], v[96:99]
	v_mfma_f32_16x16x32_bf16 v[76:79], v[92:95], v[212:215], v[76:79]
	v_mfma_f32_16x16x32_bf16 v[72:75], v[116:119], v[212:215], v[72:75]
	s_setprio 0
	s_setprio 1
	v_mfma_f32_16x16x32_bf16 v[136:139], v[128:131], v[160:163], v[136:139]
	v_mfma_f32_16x16x32_bf16 v[132:135], v[152:155], v[160:163], v[132:135]
	v_mfma_f32_16x16x32_bf16 v[112:115], v[128:131], v[168:171], v[112:115]
	v_mfma_f32_16x16x32_bf16 v[108:111], v[152:155], v[168:171], v[108:111]
	v_mfma_f32_16x16x32_bf16 v[88:91], v[128:131], v[176:179], v[88:91]
	v_mfma_f32_16x16x32_bf16 v[80:83], v[152:155], v[176:179], v[80:83]
	v_mfma_f32_16x16x32_bf16 v[68:71], v[128:131], v[184:187], v[68:71]
	v_mfma_f32_16x16x32_bf16 v[64:67], v[152:155], v[184:187], v[64:67]
	v_mfma_f32_16x16x32_bf16 v[136:139], v[140:143], v[164:167], v[136:139]
	v_mfma_f32_16x16x32_bf16 v[132:135], v[156:159], v[164:167], v[132:135]
	v_mfma_f32_16x16x32_bf16 v[112:115], v[140:143], v[172:175], v[112:115]
	v_mfma_f32_16x16x32_bf16 v[108:111], v[156:159], v[172:175], v[108:111]
	v_mfma_f32_16x16x32_bf16 v[88:91], v[140:143], v[180:183], v[88:91]
	v_mfma_f32_16x16x32_bf16 v[80:83], v[156:159], v[180:183], v[80:83]
	v_mfma_f32_16x16x32_bf16 v[68:71], v[140:143], v[212:215], v[68:71]
	v_mfma_f32_16x16x32_bf16 v[64:67], v[156:159], v[212:215], v[64:67]
	s_setprio 0
	s_barrier
	s_add_i32 s33, s83, s14
	v_lshl_add_u64 v[230:231], v[216:217], 0, s[42:43]
	s_mov_b32 m0, s33
	ds_read_b128 v[160:163], v223 offset:49152
	ds_read_b128 v[164:167], v223 offset:50176
	ds_read_b128 v[168:171], v223 offset:51200
	ds_read_b128 v[172:175], v223 offset:52224
	ds_read_b128 v[176:179], v223 offset:53248
	ds_read_b128 v[180:183], v223 offset:54272
	ds_read_b128 v[184:187], v223 offset:55296
	ds_read_b128 v[212:215], v223 offset:56320
	global_load_lds_dwordx4 v[230:231], off
	v_lshl_add_u64 v[230:231], v[216:217], 0, s[44:45]
	s_add_i32 m0, s33, 0x2000
	s_add_i32 s33, s84, s14
	global_load_lds_dwordx4 v[230:231], off
	v_lshl_add_u64 v[230:231], v[216:217], 0, s[46:47]
	s_mov_b32 m0, s33
	v_lshl_add_u64 v[216:217], v[216:217], 0, s[48:49]
	global_load_lds_dwordx4 v[230:231], off
	s_add_i32 m0, s33, 0x2000
	s_nop 0
	global_load_lds_dwordx4 v[216:217], off
	v_lshl_add_u64 v[216:217], v[228:229], 0, s[42:43]
	s_mov_b32 m0, s74
	s_nop 0
	global_load_lds_dwordx4 v[216:217], off
	v_lshl_add_u64 v[216:217], v[228:229], 0, s[44:45]
	s_mov_b32 m0, s75
	s_nop 0
	global_load_lds_dwordx4 v[216:217], off
	s_waitcnt vmcnt(8)
	s_waitcnt lgkmcnt(0)
	s_barrier
	s_setprio 1
	s_waitcnt lgkmcnt(0)
	v_mfma_f32_16x16x32_bf16 v[60:63], v[84:87], v[160:163], v[60:63]
	v_mfma_f32_16x16x32_bf16 v[56:59], v[104:107], v[160:163], v[56:59]
	v_mfma_f32_16x16x32_bf16 v[44:47], v[84:87], v[168:171], v[44:47]
	v_mfma_f32_16x16x32_bf16 v[40:43], v[104:107], v[168:171], v[40:43]
	v_mfma_f32_16x16x32_bf16 v[28:31], v[84:87], v[176:179], v[28:31]
	v_mfma_f32_16x16x32_bf16 v[24:27], v[104:107], v[176:179], v[24:27]
	v_mfma_f32_16x16x32_bf16 v[12:15], v[84:87], v[184:187], v[12:15]
	v_mfma_f32_16x16x32_bf16 v[8:11], v[104:107], v[184:187], v[8:11]
	v_mfma_f32_16x16x32_bf16 v[60:63], v[92:95], v[164:167], v[60:63]
	v_mfma_f32_16x16x32_bf16 v[56:59], v[116:119], v[164:167], v[56:59]
	v_mfma_f32_16x16x32_bf16 v[44:47], v[92:95], v[172:175], v[44:47]
	v_mfma_f32_16x16x32_bf16 v[40:43], v[116:119], v[172:175], v[40:43]
	v_mfma_f32_16x16x32_bf16 v[28:31], v[92:95], v[180:183], v[28:31]
	v_mfma_f32_16x16x32_bf16 v[24:27], v[116:119], v[180:183], v[24:27]
	v_mfma_f32_16x16x32_bf16 v[12:15], v[92:95], v[212:215], v[12:15]
	v_mfma_f32_16x16x32_bf16 v[8:11], v[116:119], v[212:215], v[8:11]
	s_setprio 0
	s_setprio 1
	v_mfma_f32_16x16x32_bf16 v[52:55], v[128:131], v[160:163], v[52:55]
	v_mfma_f32_16x16x32_bf16 v[48:51], v[152:155], v[160:163], v[48:51]
	v_mfma_f32_16x16x32_bf16 v[36:39], v[128:131], v[168:171], v[36:39]
	v_mfma_f32_16x16x32_bf16 v[32:35], v[152:155], v[168:171], v[32:35]
	v_mfma_f32_16x16x32_bf16 v[20:23], v[128:131], v[176:179], v[20:23]
	v_mfma_f32_16x16x32_bf16 v[16:19], v[152:155], v[176:179], v[16:19]
	v_mfma_f32_16x16x32_bf16 v[4:7], v[128:131], v[184:187], v[4:7]
	v_mfma_f32_16x16x32_bf16 v[0:3], v[152:155], v[184:187], v[0:3]
	v_mfma_f32_16x16x32_bf16 v[52:55], v[140:143], v[164:167], v[52:55]
	v_mfma_f32_16x16x32_bf16 v[48:51], v[156:159], v[164:167], v[48:51]
	v_mfma_f32_16x16x32_bf16 v[36:39], v[140:143], v[172:175], v[36:39]
	v_mfma_f32_16x16x32_bf16 v[32:35], v[156:159], v[172:175], v[32:35]
	v_mfma_f32_16x16x32_bf16 v[20:23], v[140:143], v[180:183], v[20:23]
	v_mfma_f32_16x16x32_bf16 v[16:19], v[156:159], v[180:183], v[16:19]
	v_mfma_f32_16x16x32_bf16 v[4:7], v[140:143], v[212:215], v[4:7]
	v_mfma_f32_16x16x32_bf16 v[0:3], v[156:159], v[212:215], v[0:3]
	s_setprio 0
	s_barrier
	s_add_i32 s66, s66, 2
	s_add_u32 s6, s6, 0x10000
	s_addc_u32 s7, s7, 0
	s_add_u32 s64, s64, 0x10000
	s_addc_u32 s65, s65, 0
	s_cmp_gt_u32 s66, 41
	s_cbranch_scc0 .LBB0_924
	s_and_b64 vcc, exec, s[54:55]
	s_cbranch_vccz .LBB0_927
	s_barrier

; #define PG8_STAGE(bufoff, gbase, voff) do { _Pragma("unroll") for (int _i = 0; _i < 2; ++_i) \
;         __builtin_amdgcn_global_load_lds((const unsigned*)((const char*)(gbase) + (voff)[_i]), (PG8_LAS unsigned*)(lds + (bufoff) + ldsw + _i * 8192), 16, 0, 0); } while (0)
; #define PG8_LDA(dst, b, h) do { _Pragma("unroll") for (int m = 0; m < 4; ++m) _Pragma("unroll") for (int k = 0; k < 2; ++k) dst[m][k] = *(const PG8_LAS bf16x8*)(lds + PG8_SA(b, h) + aoff + m * 2048 + k * 1024); } while (0)
; #define PG8_LDB(dst, b, h) do { _Pragma("unroll") for (int n = 0; n < 2; ++n) _Pragma("unroll") for (int k = 0; k < 2; ++k) dst[n][k] = *(const PG8_LAS bf16x8*)(lds + PG8_SB(b, h) + boff + n * 2048 + k * 1024); } while (0)
; #define PG8_MMA(ai, bj, At, Bt) do { __builtin_amdgcn_s_setprio(1); _Pragma("unroll") for (int m = 0; m < 4; ++m) _Pragma("unroll") for (int n = 0; n < 2; ++n) _Pragma("unroll") for (int k = 0; k < 2; ++k) \
;         acc[ai][bj][m][n] = __builtin_amdgcn_mfma_f32_16x16x32_bf16(Bt[n][k], At[m][k], acc[ai][bj][m][n], 0, 0, 0); __builtin_amdgcn_s_setprio(0); } while (0)
; #define PG8_WAIT_V(n) asm volatile("s_waitcnt vmcnt(" #n ")" ::: "memory")
; #define PG8_WAIT_L(n) asm volatile("s_waitcnt lgkmcnt(" #n ")" ::: "memory")
; #define PG8_BAR __builtin_amdgcn_s_barrier()
; #define PG8_SCHED __builtin_amdgcn_sched_barrier(0)
; template <class Epi, class Sched, bool ALIGN_EPI = false, bool SP2 = false>
; __device__ __forceinline__ void gemm_phase(PG8_LAS unsigned char* lds, const Gemm g, const Sched& S, const Epi& E) {
;     ...
;             PG8_LDB(B0, 0, 0); PG8_LDB(B1, 0, 1); PG8_SCHED; PG8_LDA(At, 0, 0); PG8_STAGE(PG8_SA(1, 1), a1 + hstepA, voffA);
;             PG8_WAIT_V(8); PG8_WAIT_L(0); PG8_BAR; PG8_MMA(0, 0, At, B0); PG8_MMA(0, 1, At, B1); PG8_BAR; PG8_SCHED;
;     ...
; #pragma unroll
;         for (int a = 0; a < 2; ++a)
; #pragma unroll
;             for (int b = 0; b < 2; ++b)
; #pragma unroll
;                 for (int m = 0; m < 4; ++m)
; #pragma unroll
;                     for (int n = 0; n < 2; ++n) acc[a][b][m][n] = (f32x4){0.f, 0.f, 0.f, 0.f};
.LBB0_1003:
	s_add_u32 s70, s70, 0x10000
	s_addc_u32 s71, s71, 0
	s_add_u32 s69, s72, 0x10000
	s_addc_u32 s72, s73, 0
	s_mov_b32 s73, -2
.LBB0_1004:
	ds_read_b128 v[128:131], v220
	ds_read_b128 v[132:135], v220 offset:1024
	ds_read_b128 v[136:139], v220 offset:2048
	ds_read_b128 v[140:143], v220 offset:3072
	ds_read_b128 v[144:147], v221
	ds_read_b128 v[148:151], v221 offset:1024
	ds_read_b128 v[152:155], v221 offset:2048
	ds_read_b128 v[156:159], v221 offset:3072
	s_cmp_eq_u32 s73, 40
	s_cselect_b32 s75, s1, s71
	s_cselect_b32 s74, s0, s70
	s_cselect_b32 s77, s67, s72
	s_cselect_b32 s76, s66, s69
	v_lshl_add_u64 v[238:239], s[70:71], 0, v[190:191]
	v_lshl_add_u64 v[240:241], v[238:239], 0, s[62:63]
	s_add_i32 m0, s15, 0xc000
	ds_read_b128 v[160:163], v222
	ds_read_b128 v[164:167], v222 offset:1024
	ds_read_b128 v[168:171], v222 offset:2048
	ds_read_b128 v[172:175], v222 offset:3072
	ds_read_b128 v[176:179], v222 offset:4096
	ds_read_b128 v[180:183], v222 offset:5120
	ds_read_b128 v[230:233], v222 offset:6144
	ds_read_b128 v[234:237], v222 offset:7168
	global_load_lds_dwordx4 v[240:241], off
	v_lshl_add_u64 v[238:239], v[238:239], 0, s[64:65]
	s_add_i32 m0, s15, 0xe000
	s_nop 0
	global_load_lds_dwordx4 v[238:239], off
	s_cmp_lg_u32 s73, -2
	s_cbranch_scc1 .Lzskip_8
	v_mov_b32_e32 v0, 0
	v_mov_b32_e32 v1, 0
	v_mov_b32_e32 v2, 0
	v_mov_b32_e32 v3, 0
	v_mov_b32_e32 v4, 0
	v_mov_b32_e32 v5, 0
	v_mov_b32_e32 v6, 0
	v_mov_b32_e32 v7, 0
	v_mov_b32_e32 v8, 0
	v_mov_b32_e32 v9, 0
	v_mov_b32_e32 v10, 0
	v_mov_b32_e32 v11, 0
	v_mov_b32_e32 v12, 0
	v_mov_b32_e32 v13, 0
	v_mov_b32_e32 v14, 0
	v_mov_b32_e32 v15, 0
	v_mov_b32_e32 v16, 0
	v_mov_b32_e32 v17, 0
	v_mov_b32_e32 v18, 0
	v_mov_b32_e32 v19, 0
	v_mov_b32_e32 v20, 0
	v_mov_b32_e32 v21, 0
	v_mov_b32_e32 v22, 0
	v_mov_b32_e32 v23, 0
	v_mov_b32_e32 v24, 0
	v_mov_b32_e32 v25, 0
	v_mov_b32_e32 v26, 0
	v_mov_b32_e32 v27, 0
	v_mov_b32_e32 v28, 0
	v_mov_b32_e32 v29, 0
	v_mov_b32_e32 v30, 0
	v_mov_b32_e32 v31, 0
	v_mov_b32_e32 v32, 0
	v_mov_b32_e32 v33, 0
	v_mov_b32_e32 v34, 0
	v_mov_b32_e32 v35, 0
	v_mov_b32_e32 v36, 0
	v_mov_b32_e32 v37, 0
	v_mov_b32_e32 v38, 0
	v_mov_b32_e32 v39, 0
	v_mov_b32_e32 v40, 0
	v_mov_b32_e32 v41, 0
	v_mov_b32_e32 v42, 0
	v_mov_b32_e32 v43, 0
	v_mov_b32_e32 v44, 0
	v_mov_b32_e32 v45, 0
	v_mov_b32_e32 v46, 0
	v_mov_b32_e32 v47, 0
	v_mov_b32_e32 v48, 0
	v_mov_b32_e32 v49, 0
	v_mov_b32_e32 v50, 0
	v_mov_b32_e32 v51, 0
	v_mov_b32_e32 v52, 0
	v_mov_b32_e32 v53, 0
	v_mov_b32_e32 v54, 0
	v_mov_b32_e32 v55, 0
	v_mov_b32_e32 v56, 0
	v_mov_b32_e32 v57, 0
	v_mov_b32_e32 v58, 0
	v_mov_b32_e32 v59, 0
	v_mov_b32_e32 v60, 0
	v_mov_b32_e32 v61, 0
	v_mov_b32_e32 v62, 0
	v_mov_b32_e32 v63, 0
	v_mov_b32_e32 v64, 0
	v_mov_b32_e32 v65, 0
	v_mov_b32_e32 v66, 0
	v_mov_b32_e32 v67, 0
	v_mov_b32_e32 v68, 0
	v_mov_b32_e32 v69, 0
	v_mov_b32_e32 v70, 0
	v_mov_b32_e32 v71, 0
	v_mov_b32_e32 v72, 0
	v_mov_b32_e32 v73, 0
	v_mov_b32_e32 v74, 0
	v_mov_b32_e32 v75, 0
	v_mov_b32_e32 v76, 0
	v_mov_b32_e32 v77, 0
	v_mov_b32_e32 v78, 0
	v_mov_b32_e32 v79, 0
	v_mov_b32_e32 v80, 0
	v_mov_b32_e32 v81, 0
	v_mov_b32_e32 v82, 0
	v_mov_b32_e32 v83, 0
	v_mov_b32_e32 v84, 0
	v_mov_b32_e32 v85, 0
	v_mov_b32_e32 v86, 0
	v_mov_b32_e32 v87, 0
	v_mov_b32_e32 v88, 0
	v_mov_b32_e32 v89, 0
	v_mov_b32_e32 v90, 0
	v_mov_b32_e32 v91, 0
	v_mov_b32_e32 v92, 0
	v_mov_b32_e32 v93, 0
	v_mov_b32_e32 v94, 0
	v_mov_b32_e32 v95, 0
	v_mov_b32_e32 v96, 0
	v_mov_b32_e32 v97, 0
	v_mov_b32_e32 v98, 0
	v_mov_b32_e32 v99, 0
	v_mov_b32_e32 v100, 0
	v_mov_b32_e32 v101, 0
	v_mov_b32_e32 v102, 0
	v_mov_b32_e32 v103, 0
	v_mov_b32_e32 v104, 0
	v_mov_b32_e32 v105, 0
	v_mov_b32_e32 v106, 0
	v_mov_b32_e32 v107, 0
	v_mov_b32_e32 v108, 0
	v_mov_b32_e32 v109, 0
	v_mov_b32_e32 v110, 0
	v_mov_b32_e32 v111, 0
	v_mov_b32_e32 v112, 0
	v_mov_b32_e32 v113, 0
	v_mov_b32_e32 v114, 0
	v_mov_b32_e32 v115, 0
	v_mov_b32_e32 v116, 0
	v_mov_b32_e32 v117, 0
	v_mov_b32_e32 v118, 0
	v_mov_b32_e32 v119, 0
	v_mov_b32_e32 v120, 0
	v_mov_b32_e32 v121, 0
	v_mov_b32_e32 v122, 0
	v_mov_b32_e32 v123, 0
	v_mov_b32_e32 v124, 0
	v_mov_b32_e32 v125, 0
	v_mov_b32_e32 v126, 0
	v_mov_b32_e32 v127, 0
.Lzskip_8:
	s_waitcnt vmcnt(8)
	s_waitcnt lgkmcnt(0)
	s_barrier
	s_setprio 1
	s_waitcnt lgkmcnt(0)
	v_mfma_f32_16x16x32_bf16 v[124:127], v[128:131], v[160:163], v[124:127]
	v_mfma_f32_16x16x32_bf16 v[120:123], v[136:139], v[160:163], v[120:123]
	v_mfma_f32_16x16x32_bf16 v[108:111], v[128:131], v[168:171], v[108:111]
	v_mfma_f32_16x16x32_bf16 v[104:107], v[136:139], v[168:171], v[104:107]
	v_mfma_f32_16x16x32_bf16 v[92:95], v[128:131], v[176:179], v[92:95]
	v_mfma_f32_16x16x32_bf16 v[88:91], v[136:139], v[176:179], v[88:91]
	v_mfma_f32_16x16x32_bf16 v[76:79], v[128:131], v[230:233], v[76:79]
	v_mfma_f32_16x16x32_bf16 v[72:75], v[136:139], v[230:233], v[72:75]
	v_mfma_f32_16x16x32_bf16 v[124:127], v[132:135], v[164:167], v[124:127]
	v_mfma_f32_16x16x32_bf16 v[120:123], v[140:143], v[164:167], v[120:123]
	v_mfma_f32_16x16x32_bf16 v[108:111], v[132:135], v[172:175], v[108:111]
	v_mfma_f32_16x16x32_bf16 v[104:107], v[140:143], v[172:175], v[104:107]
	v_mfma_f32_16x16x32_bf16 v[92:95], v[132:135], v[180:183], v[92:95]
	v_mfma_f32_16x16x32_bf16 v[88:91], v[140:143], v[180:183], v[88:91]
	v_mfma_f32_16x16x32_bf16 v[76:79], v[132:135], v[234:237], v[76:79]
	v_mfma_f32_16x16x32_bf16 v[72:75], v[140:143], v[234:237], v[72:75]
	s_setprio 0
	s_setprio 1
	v_mfma_f32_16x16x32_bf16 v[116:119], v[144:147], v[160:163], v[116:119]
	v_mfma_f32_16x16x32_bf16 v[112:115], v[152:155], v[160:163], v[112:115]
	v_mfma_f32_16x16x32_bf16 v[100:103], v[144:147], v[168:171], v[100:103]
	v_mfma_f32_16x16x32_bf16 v[96:99], v[152:155], v[168:171], v[96:99]
	v_mfma_f32_16x16x32_bf16 v[84:87], v[144:147], v[176:179], v[84:87]
	v_mfma_f32_16x16x32_bf16 v[80:83], v[152:155], v[176:179], v[80:83]
	v_mfma_f32_16x16x32_bf16 v[68:71], v[144:147], v[230:233], v[68:71]
	v_mfma_f32_16x16x32_bf16 v[64:67], v[152:155], v[230:233], v[64:67]
	v_mfma_f32_16x16x32_bf16 v[116:119], v[148:151], v[164:167], v[116:119]
	v_mfma_f32_16x16x32_bf16 v[112:115], v[156:159], v[164:167], v[112:115]
	v_mfma_f32_16x16x32_bf16 v[100:103], v[148:151], v[172:175], v[100:103]
	v_mfma_f32_16x16x32_bf16 v[96:99], v[156:159], v[172:175], v[96:99]
	v_mfma_f32_16x16x32_bf16 v[84:87], v[148:151], v[180:183], v[84:87]
	v_mfma_f32_16x16x32_bf16 v[80:83], v[156:159], v[180:183], v[80:83]
	v_mfma_f32_16x16x32_bf16 v[68:71], v[148:151], v[234:237], v[68:71]
	v_mfma_f32_16x16x32_bf16 v[64:67], v[156:159], v[234:237], v[64:67]
	s_setprio 0
	s_barrier
; #define PG8_STAGE(bufoff, gbase, voff) do { _Pragma("unroll") for (int _i = 0; _i < 2; ++_i) \
;         __builtin_amdgcn_global_load_lds((const unsigned*)((const char*)(gbase) + (voff)[_i]), (PG8_LAS unsigned*)(lds + (bufoff) + ldsw + _i * 8192), 16, 0, 0); } while (0)
; #define PG8_LDA(dst, b, h) do { _Pragma("unroll") for (int m = 0; m < 4; ++m) _Pragma("unroll") for (int k = 0; k < 2; ++k) dst[m][k] = *(const PG8_LAS bf16x8*)(lds + PG8_SA(b, h) + aoff + m * 2048 + k * 1024); } while (0)
; #define PG8_LDB(dst, b, h) do { _Pragma("unroll") for (int n = 0; n < 2; ++n) _Pragma("unroll") for (int k = 0; k < 2; ++k) dst[n][k] = *(const PG8_LAS bf16x8*)(lds + PG8_SB(b, h) + boff + n * 2048 + k * 1024); } while (0)
; #define PG8_MMA(ai, bj, At, Bt) do { __builtin_amdgcn_s_setprio(1); _Pragma("unroll") for (int m = 0; m < 4; ++m) _Pragma("unroll") for (int n = 0; n < 2; ++n) _Pragma("unroll") for (int k = 0; k < 2; ++k) \
;         acc[ai][bj][m][n] = __builtin_amdgcn_mfma_f32_16x16x32_bf16(Bt[n][k], At[m][k], acc[ai][bj][m][n], 0, 0, 0); __builtin_amdgcn_s_setprio(0); } while (0)
; #define PG8_WAIT_V(n) asm volatile("s_waitcnt vmcnt(" #n ")" ::: "memory")
; #define PG8_WAIT_L(n) asm volatile("s_waitcnt lgkmcnt(" #n ")" ::: "memory")
; #define PG8_BAR __builtin_amdgcn_s_barrier()
; #define PG8_SCHED __builtin_amdgcn_sched_barrier(0)
; template <class Epi, class Sched, bool ALIGN_EPI = false, bool SP2 = false>
; __device__ __forceinline__ void gemm_phase(PG8_LAS unsigned char* lds, const Gemm g, const Sched& S, const Epi& E) {
;     ...
;             PG8_LDA(At, 0, 1); PG8_STAGE(PG8_SB(0, 0), b2, voffB); PG8_STAGE(PG8_SB(0, 1), b2 + hstepB, voffB); PG8_STAGE(PG8_SA(0, 0), a2, voffA);
;             PG8_WAIT_V(8); PG8_WAIT_L(0); PG8_BAR; PG8_MMA(1, 0, At, B0); PG8_MMA(1, 1, At, B1); PG8_BAR; PG8_SCHED;
;             PG8_LDB(B0, 1, 0); PG8_LDB(B1, 1, 1); PG8_SCHED; PG8_LDA(At, 1, 0); PG8_STAGE(PG8_SA(0, 1), a2 + hstepA, voffA);
	s_add_i32 s33, s86, s14
	v_lshl_add_u64 v[238:239], s[76:77], 0, v[190:191]
	s_mov_b32 m0, s33
	ds_read_b128 v[160:163], v222 offset:16384
	ds_read_b128 v[164:167], v222 offset:17408
	ds_read_b128 v[168:171], v222 offset:18432
	ds_read_b128 v[172:175], v222 offset:19456
	ds_read_b128 v[176:179], v222 offset:20480
	ds_read_b128 v[180:183], v222 offset:21504
	ds_read_b128 v[230:233], v222 offset:22528
	ds_read_b128 v[234:237], v222 offset:23552
	global_load_lds_dwordx4 v[238:239], off
	v_lshl_add_u64 v[240:241], v[238:239], 0, s[40:41]
	s_add_i32 m0, s33, 0x2000
	s_add_i32 s33, s87, s14
	global_load_lds_dwordx4 v[240:241], off
	v_lshl_add_u64 v[240:241], v[238:239], 0, s[42:43]
	s_mov_b32 m0, s33
	s_nop 0
	global_load_lds_dwordx4 v[240:241], off
	v_lshl_add_u64 v[240:241], v[238:239], 0, s[44:45]
	s_add_i32 m0, s33, 0x2000
	s_nop 0
	global_load_lds_dwordx4 v[240:241], off
	v_lshl_add_u64 v[240:241], s[74:75], 0, v[190:191]
	s_mov_b32 m0, s15
	v_lshl_add_u64 v[242:243], v[240:241], 0, s[40:41]
	global_load_lds_dwordx4 v[240:241], off
	s_mov_b32 m0, s17
	s_nop 0
	global_load_lds_dwordx4 v[242:243], off
	s_waitcnt vmcnt(8)
	s_waitcnt lgkmcnt(0)
	s_barrier
	s_setprio 1
	s_waitcnt lgkmcnt(0)
	v_mfma_f32_16x16x32_bf16 v[60:63], v[128:131], v[160:163], v[60:63]
	v_mfma_f32_16x16x32_bf16 v[56:59], v[136:139], v[160:163], v[56:59]
	v_mfma_f32_16x16x32_bf16 v[44:47], v[128:131], v[168:171], v[44:47]
	v_mfma_f32_16x16x32_bf16 v[40:43], v[136:139], v[168:171], v[40:43]
	v_mfma_f32_16x16x32_bf16 v[28:31], v[128:131], v[176:179], v[28:31]
	v_mfma_f32_16x16x32_bf16 v[24:27], v[136:139], v[176:179], v[24:27]
	v_mfma_f32_16x16x32_bf16 v[12:15], v[128:131], v[230:233], v[12:15]
	v_mfma_f32_16x16x32_bf16 v[8:11], v[136:139], v[230:233], v[8:11]
	v_mfma_f32_16x16x32_bf16 v[60:63], v[132:135], v[164:167], v[60:63]
	v_mfma_f32_16x16x32_bf16 v[56:59], v[140:143], v[164:167], v[56:59]
	v_mfma_f32_16x16x32_bf16 v[44:47], v[132:135], v[172:175], v[44:47]
	v_mfma_f32_16x16x32_bf16 v[40:43], v[140:143], v[172:175], v[40:43]
	v_mfma_f32_16x16x32_bf16 v[28:31], v[132:135], v[180:183], v[28:31]
	v_mfma_f32_16x16x32_bf16 v[24:27], v[140:143], v[180:183], v[24:27]
	v_mfma_f32_16x16x32_bf16 v[12:15], v[132:135], v[234:237], v[12:15]
	v_mfma_f32_16x16x32_bf16 v[8:11], v[140:143], v[234:237], v[8:11]
	s_setprio 0
	s_setprio 1
	v_mfma_f32_16x16x32_bf16 v[52:55], v[144:147], v[160:163], v[52:55]
	v_mfma_f32_16x16x32_bf16 v[48:51], v[152:155], v[160:163], v[48:51]
	v_mfma_f32_16x16x32_bf16 v[36:39], v[144:147], v[168:171], v[36:39]
	v_mfma_f32_16x16x32_bf16 v[32:35], v[152:155], v[168:171], v[32:35]
	v_mfma_f32_16x16x32_bf16 v[20:23], v[144:147], v[176:179], v[20:23]
	v_mfma_f32_16x16x32_bf16 v[16:19], v[152:155], v[176:179], v[16:19]
	v_mfma_f32_16x16x32_bf16 v[4:7], v[144:147], v[230:233], v[4:7]
	v_mfma_f32_16x16x32_bf16 v[0:3], v[152:155], v[230:233], v[0:3]
	v_mfma_f32_16x16x32_bf16 v[52:55], v[148:151], v[164:167], v[52:55]
	v_mfma_f32_16x16x32_bf16 v[48:51], v[156:159], v[164:167], v[48:51]
	v_mfma_f32_16x16x32_bf16 v[36:39], v[148:151], v[172:175], v[36:39]
	v_mfma_f32_16x16x32_bf16 v[32:35], v[156:159], v[172:175], v[32:35]
	v_mfma_f32_16x16x32_bf16 v[20:23], v[148:151], v[180:183], v[20:23]
	v_mfma_f32_16x16x32_bf16 v[16:19], v[156:159], v[180:183], v[16:19]
	v_mfma_f32_16x16x32_bf16 v[4:7], v[148:151], v[234:237], v[4:7]
	v_mfma_f32_16x16x32_bf16 v[0:3], v[156:159], v[234:237], v[0:3]
	s_setprio 0
	s_barrier
	ds_read_b128 v[128:131], v223
	ds_read_b128 v[132:135], v223 offset:1024
	ds_read_b128 v[136:139], v223 offset:2048
	ds_read_b128 v[140:143], v223 offset:3072
	ds_read_b128 v[144:147], v224
	ds_read_b128 v[148:151], v224 offset:1024
	ds_read_b128 v[152:155], v224 offset:2048
	ds_read_b128 v[156:159], v224 offset:3072
	s_mov_b32 m0, s18
	v_lshl_add_u64 v[242:243], v[240:241], 0, s[42:43]
	ds_read_b128 v[160:163], v222 offset:32768
	ds_read_b128 v[164:167], v222 offset:33792
	ds_read_b128 v[168:171], v222 offset:34816
	ds_read_b128 v[172:175], v222 offset:35840
	ds_read_b128 v[176:179], v222 offset:36864
	ds_read_b128 v[180:183], v222 offset:37888
	ds_read_b128 v[230:233], v222 offset:38912
	ds_read_b128 v[234:237], v222 offset:39936
	global_load_lds_dwordx4 v[242:243], off
	v_lshl_add_u64 v[242:243], v[240:241], 0, s[44:45]
	s_mov_b32 m0, s19
	s_nop 0
	global_load_lds_dwordx4 v[242:243], off
	s_waitcnt vmcnt(8)
	s_waitcnt lgkmcnt(0)
	s_barrier
; #define PG8_STAGE(bufoff, gbase, voff) do { _Pragma("unroll") for (int _i = 0; _i < 2; ++_i) \
;         __builtin_amdgcn_global_load_lds((const unsigned*)((const char*)(gbase) + (voff)[_i]), (PG8_LAS unsigned*)(lds + (bufoff) + ldsw + _i * 8192), 16, 0, 0); } while (0)
; #define PG8_LDA(dst, b, h) do { _Pragma("unroll") for (int m = 0; m < 4; ++m) _Pragma("unroll") for (int k = 0; k < 2; ++k) dst[m][k] = *(const PG8_LAS bf16x8*)(lds + PG8_SA(b, h) + aoff + m * 2048 + k * 1024); } while (0)
; #define PG8_MMA(ai, bj, At, Bt) do { __builtin_amdgcn_s_setprio(1); _Pragma("unroll") for (int m = 0; m < 4; ++m) _Pragma("unroll") for (int n = 0; n < 2; ++n) _Pragma("unroll") for (int k = 0; k < 2; ++k) \
;         acc[ai][bj][m][n] = __builtin_amdgcn_mfma_f32_16x16x32_bf16(Bt[n][k], At[m][k], acc[ai][bj][m][n], 0, 0, 0); __builtin_amdgcn_s_setprio(0); } while (0)
; #define PG8_WAIT_V(n) asm volatile("s_waitcnt vmcnt(" #n ")" ::: "memory")
; #define PG8_WAIT_L(n) asm volatile("s_waitcnt lgkmcnt(" #n ")" ::: "memory")
; #define PG8_BAR __builtin_amdgcn_s_barrier()
; #define PG8_SCHED __builtin_amdgcn_sched_barrier(0)
; template <class Epi, class Sched, bool ALIGN_EPI = false, bool SP2 = false>
; __device__ __forceinline__ void gemm_phase(PG8_LAS unsigned char* lds, const Gemm g, const Sched& S, const Epi& E) {
;     ...
;             PG8_WAIT_V(8); PG8_WAIT_L(0); PG8_BAR; PG8_MMA(0, 0, At, B0); PG8_MMA(0, 1, At, B1); PG8_BAR; PG8_SCHED;
;             PG8_LDA(At, 1, 1); PG8_STAGE(PG8_SB(1, 0), b3, voffB); PG8_STAGE(PG8_SB(1, 1), b3 + hstepB, voffB); PG8_STAGE(PG8_SA(1, 0), a3, voffA);
;             PG8_WAIT_V(8); PG8_WAIT_L(0); PG8_BAR; PG8_MMA(1, 0, At, B0); PG8_MMA(1, 1, At, B1); PG8_BAR; PG8_SCHED;
;     ...
;         if constexpr (ALIGN_EPI) { if (wr == 0) PG8_BAR; }
	s_setprio 1
	s_waitcnt lgkmcnt(0)
	v_mfma_f32_16x16x32_bf16 v[124:127], v[128:131], v[160:163], v[124:127]
	v_mfma_f32_16x16x32_bf16 v[120:123], v[136:139], v[160:163], v[120:123]
	v_mfma_f32_16x16x32_bf16 v[108:111], v[128:131], v[168:171], v[108:111]
	v_mfma_f32_16x16x32_bf16 v[104:107], v[136:139], v[168:171], v[104:107]
	v_mfma_f32_16x16x32_bf16 v[92:95], v[128:131], v[176:179], v[92:95]
	v_mfma_f32_16x16x32_bf16 v[88:91], v[136:139], v[176:179], v[88:91]
	v_mfma_f32_16x16x32_bf16 v[76:79], v[128:131], v[230:233], v[76:79]
	v_mfma_f32_16x16x32_bf16 v[72:75], v[136:139], v[230:233], v[72:75]
	v_mfma_f32_16x16x32_bf16 v[124:127], v[132:135], v[164:167], v[124:127]
	v_mfma_f32_16x16x32_bf16 v[120:123], v[140:143], v[164:167], v[120:123]
	v_mfma_f32_16x16x32_bf16 v[108:111], v[132:135], v[172:175], v[108:111]
	v_mfma_f32_16x16x32_bf16 v[104:107], v[140:143], v[172:175], v[104:107]
	v_mfma_f32_16x16x32_bf16 v[92:95], v[132:135], v[180:183], v[92:95]
	v_mfma_f32_16x16x32_bf16 v[88:91], v[140:143], v[180:183], v[88:91]
	v_mfma_f32_16x16x32_bf16 v[76:79], v[132:135], v[234:237], v[76:79]
	v_mfma_f32_16x16x32_bf16 v[72:75], v[140:143], v[234:237], v[72:75]
	s_setprio 0
	s_setprio 1
	v_mfma_f32_16x16x32_bf16 v[116:119], v[144:147], v[160:163], v[116:119]
	v_mfma_f32_16x16x32_bf16 v[112:115], v[152:155], v[160:163], v[112:115]
	v_mfma_f32_16x16x32_bf16 v[100:103], v[144:147], v[168:171], v[100:103]
	v_mfma_f32_16x16x32_bf16 v[96:99], v[152:155], v[168:171], v[96:99]
	v_mfma_f32_16x16x32_bf16 v[84:87], v[144:147], v[176:179], v[84:87]
	v_mfma_f32_16x16x32_bf16 v[80:83], v[152:155], v[176:179], v[80:83]
	v_mfma_f32_16x16x32_bf16 v[68:71], v[144:147], v[230:233], v[68:71]
	v_mfma_f32_16x16x32_bf16 v[64:67], v[152:155], v[230:233], v[64:67]
	v_mfma_f32_16x16x32_bf16 v[116:119], v[148:151], v[164:167], v[116:119]
	v_mfma_f32_16x16x32_bf16 v[112:115], v[156:159], v[164:167], v[112:115]
	v_mfma_f32_16x16x32_bf16 v[100:103], v[148:151], v[172:175], v[100:103]
	v_mfma_f32_16x16x32_bf16 v[96:99], v[156:159], v[172:175], v[96:99]
	v_mfma_f32_16x16x32_bf16 v[84:87], v[148:151], v[180:183], v[84:87]
	v_mfma_f32_16x16x32_bf16 v[80:83], v[156:159], v[180:183], v[80:83]
	v_mfma_f32_16x16x32_bf16 v[68:71], v[148:151], v[234:237], v[68:71]
	v_mfma_f32_16x16x32_bf16 v[64:67], v[156:159], v[234:237], v[64:67]
	s_setprio 0
	s_barrier
	s_add_i32 s33, s88, s14
	v_lshl_add_u64 v[242:243], v[238:239], 0, s[46:47]
	s_mov_b32 m0, s33
	ds_read_b128 v[160:163], v222 offset:49152
	ds_read_b128 v[164:167], v222 offset:50176
	ds_read_b128 v[168:171], v222 offset:51200
	ds_read_b128 v[172:175], v222 offset:52224
	ds_read_b128 v[176:179], v222 offset:53248
	ds_read_b128 v[180:183], v222 offset:54272
	ds_read_b128 v[230:233], v222 offset:55296
	ds_read_b128 v[234:237], v222 offset:56320
	global_load_lds_dwordx4 v[242:243], off
	v_lshl_add_u64 v[242:243], v[238:239], 0, s[48:49]
	s_add_i32 m0, s33, 0x2000
	s_add_i32 s33, s89, s14
	global_load_lds_dwordx4 v[242:243], off
	v_lshl_add_u64 v[242:243], v[238:239], 0, s[52:53]
	s_mov_b32 m0, s33
	v_lshl_add_u64 v[238:239], v[238:239], 0, s[54:55]
	global_load_lds_dwordx4 v[242:243], off
	s_add_i32 m0, s33, 0x2000
	s_nop 0
	global_load_lds_dwordx4 v[238:239], off
	v_lshl_add_u64 v[238:239], v[240:241], 0, s[46:47]
	s_mov_b32 m0, s80
	s_nop 0
	global_load_lds_dwordx4 v[238:239], off
	v_lshl_add_u64 v[238:239], v[240:241], 0, s[48:49]
	s_mov_b32 m0, s81
	s_nop 0
	global_load_lds_dwordx4 v[238:239], off
	s_waitcnt vmcnt(8)
	s_waitcnt lgkmcnt(0)
	s_barrier
	s_setprio 1
	s_waitcnt lgkmcnt(0)
	v_mfma_f32_16x16x32_bf16 v[60:63], v[128:131], v[160:163], v[60:63]
	v_mfma_f32_16x16x32_bf16 v[56:59], v[136:139], v[160:163], v[56:59]
	v_mfma_f32_16x16x32_bf16 v[44:47], v[128:131], v[168:171], v[44:47]
	v_mfma_f32_16x16x32_bf16 v[40:43], v[136:139], v[168:171], v[40:43]
	v_mfma_f32_16x16x32_bf16 v[28:31], v[128:131], v[176:179], v[28:31]
	v_mfma_f32_16x16x32_bf16 v[24:27], v[136:139], v[176:179], v[24:27]
	v_mfma_f32_16x16x32_bf16 v[12:15], v[128:131], v[230:233], v[12:15]
	v_mfma_f32_16x16x32_bf16 v[8:11], v[136:139], v[230:233], v[8:11]
	v_mfma_f32_16x16x32_bf16 v[60:63], v[132:135], v[164:167], v[60:63]
	v_mfma_f32_16x16x32_bf16 v[56:59], v[140:143], v[164:167], v[56:59]
	v_mfma_f32_16x16x32_bf16 v[44:47], v[132:135], v[172:175], v[44:47]
	v_mfma_f32_16x16x32_bf16 v[40:43], v[140:143], v[172:175], v[40:43]
	v_mfma_f32_16x16x32_bf16 v[28:31], v[132:135], v[180:183], v[28:31]
	v_mfma_f32_16x16x32_bf16 v[24:27], v[140:143], v[180:183], v[24:27]
	v_mfma_f32_16x16x32_bf16 v[12:15], v[132:135], v[234:237], v[12:15]
	v_mfma_f32_16x16x32_bf16 v[8:11], v[140:143], v[234:237], v[8:11]
	s_setprio 0
	s_setprio 1
	v_mfma_f32_16x16x32_bf16 v[52:55], v[144:147], v[160:163], v[52:55]
	v_mfma_f32_16x16x32_bf16 v[48:51], v[152:155], v[160:163], v[48:51]
	v_mfma_f32_16x16x32_bf16 v[36:39], v[144:147], v[168:171], v[36:39]
	v_mfma_f32_16x16x32_bf16 v[32:35], v[152:155], v[168:171], v[32:35]
	v_mfma_f32_16x16x32_bf16 v[20:23], v[144:147], v[176:179], v[20:23]
	v_mfma_f32_16x16x32_bf16 v[16:19], v[152:155], v[176:179], v[16:19]
	v_mfma_f32_16x16x32_bf16 v[4:7], v[144:147], v[230:233], v[4:7]
	v_mfma_f32_16x16x32_bf16 v[0:3], v[152:155], v[230:233], v[0:3]
	v_mfma_f32_16x16x32_bf16 v[52:55], v[148:151], v[164:167], v[52:55]
	v_mfma_f32_16x16x32_bf16 v[48:51], v[156:159], v[164:167], v[48:51]
	v_mfma_f32_16x16x32_bf16 v[36:39], v[148:151], v[172:175], v[36:39]
	v_mfma_f32_16x16x32_bf16 v[32:35], v[156:159], v[172:175], v[32:35]
	v_mfma_f32_16x16x32_bf16 v[20:23], v[148:151], v[180:183], v[20:23]
	v_mfma_f32_16x16x32_bf16 v[16:19], v[156:159], v[180:183], v[16:19]
	v_mfma_f32_16x16x32_bf16 v[4:7], v[148:151], v[234:237], v[4:7]
	v_mfma_f32_16x16x32_bf16 v[0:3], v[156:159], v[234:237], v[0:3]
	s_setprio 0
	s_barrier
	s_add_i32 s73, s73, 2
	s_add_u32 s70, s70, 0x10000
	s_addc_u32 s71, s71, 0
	s_add_u32 s69, s69, 0x10000
	s_addc_u32 s72, s72, 0
	s_cmp_gt_u32 s73, 41
	s_cbranch_scc0 .LBB0_1004
	s_and_b64 vcc, exec, s[60:61]
	s_cbranch_vccz .LBB0_1007
	s_barrier
